# saddr-form K-loop DMA loads, fuller version: all redundant 64-bit address adds removed in every GEMM K-loop (10-16 per loop body), loop heads 64-byte aligned
# speedup vs baseline: 1.0011x; 1.0011x over previous
.LBB0_197:
	ds_read_b128 v[34:37], v184
	ds_read_b128 v[38:41], v184 offset:1024
	ds_read_b128 v[42:45], v184 offset:2048
	ds_read_b128 v[46:49], v184 offset:3072
	ds_read_b128 v[166:169], v185
	ds_read_b128 v[170:173], v185 offset:1024
	ds_read_b128 v[190:193], v185 offset:2048
	ds_read_b128 v[194:197], v185 offset:3072
	s_add_u32 s13, s8, 0xfffc0080
	s_addc_u32 s24, s9, -1
	s_cmp_eq_u32 s12, 12
	s_cselect_b32 s87, s15, s24
	s_cselect_b32 s86, s23, s13
	s_cselect_b32 s85, s77, vcc_hi
	s_cselect_b32 s84, s79, vcc_lo
	s_nop 0
	s_add_i32 m0, s90, 0xc000
	ds_read_b128 v[198:201], v186
	ds_read_b128 v[202:205], v186 offset:1024
	ds_read_b128 v[206:209], v186 offset:2048
	ds_read_b128 v[210:213], v186 offset:3072
	ds_read_b128 v[214:217], v186 offset:4096
	ds_read_b128 v[218:221], v186 offset:5120
	ds_read_b128 v[222:225], v186 offset:6144
	ds_read_b128 v[226:229], v186 offset:7168
	global_load_lds_dwordx4 v158, s[8:9]
	s_nop 0
	s_add_i32 m0, s90, 0xe000
	s_nop 0
	global_load_lds_dwordx4 v160, s[8:9]
	s_waitcnt vmcnt(8)
	s_waitcnt lgkmcnt(0)
	s_barrier
	s_setprio 1
	s_waitcnt lgkmcnt(0)
	v_mfma_f32_16x16x32_bf16 v[142:145], v[34:37], v[198:201], v[142:145]
	v_mfma_f32_16x16x32_bf16 v[138:141], v[42:45], v[198:201], v[138:141]
	v_mfma_f32_16x16x32_bf16 v[126:129], v[34:37], v[206:209], v[126:129]
	v_mfma_f32_16x16x32_bf16 v[122:125], v[42:45], v[206:209], v[122:125]
	v_mfma_f32_16x16x32_bf16 v[110:113], v[34:37], v[214:217], v[110:113]
	v_mfma_f32_16x16x32_bf16 v[106:109], v[42:45], v[214:217], v[106:109]
	v_mfma_f32_16x16x32_bf16 v[94:97], v[34:37], v[222:225], v[94:97]
	v_mfma_f32_16x16x32_bf16 v[90:93], v[42:45], v[222:225], v[90:93]
	v_mfma_f32_16x16x32_bf16 v[142:145], v[38:41], v[202:205], v[142:145]
	v_mfma_f32_16x16x32_bf16 v[138:141], v[46:49], v[202:205], v[138:141]
	v_mfma_f32_16x16x32_bf16 v[126:129], v[38:41], v[210:213], v[126:129]
	v_mfma_f32_16x16x32_bf16 v[122:125], v[46:49], v[210:213], v[122:125]
	v_mfma_f32_16x16x32_bf16 v[110:113], v[38:41], v[218:221], v[110:113]
	v_mfma_f32_16x16x32_bf16 v[106:109], v[46:49], v[218:221], v[106:109]
	v_mfma_f32_16x16x32_bf16 v[94:97], v[38:41], v[226:229], v[94:97]
	v_mfma_f32_16x16x32_bf16 v[90:93], v[46:49], v[226:229], v[90:93]
	s_setprio 0
	s_setprio 1
	v_mfma_f32_16x16x32_bf16 v[134:137], v[166:169], v[198:201], v[134:137]
	v_mfma_f32_16x16x32_bf16 v[130:133], v[190:193], v[198:201], v[130:133]
	v_mfma_f32_16x16x32_bf16 v[118:121], v[166:169], v[206:209], v[118:121]
	v_mfma_f32_16x16x32_bf16 v[114:117], v[190:193], v[206:209], v[114:117]
	v_mfma_f32_16x16x32_bf16 v[102:105], v[166:169], v[214:217], v[102:105]
	v_mfma_f32_16x16x32_bf16 v[98:101], v[190:193], v[214:217], v[98:101]
	v_mfma_f32_16x16x32_bf16 v[86:89], v[166:169], v[222:225], v[86:89]
	v_mfma_f32_16x16x32_bf16 v[82:85], v[190:193], v[222:225], v[82:85]
	v_mfma_f32_16x16x32_bf16 v[134:137], v[170:173], v[202:205], v[134:137]
	v_mfma_f32_16x16x32_bf16 v[130:133], v[194:197], v[202:205], v[130:133]
	v_mfma_f32_16x16x32_bf16 v[118:121], v[170:173], v[210:213], v[118:121]
	v_mfma_f32_16x16x32_bf16 v[114:117], v[194:197], v[210:213], v[114:117]
	v_mfma_f32_16x16x32_bf16 v[102:105], v[170:173], v[218:221], v[102:105]
	v_mfma_f32_16x16x32_bf16 v[98:101], v[194:197], v[218:221], v[98:101]
	v_mfma_f32_16x16x32_bf16 v[86:89], v[170:173], v[226:229], v[86:89]
	v_mfma_f32_16x16x32_bf16 v[82:85], v[194:197], v[226:229], v[82:85]
	s_setprio 0
	s_barrier
	s_add_i32 s13, s62, s89
	s_nop 0
	s_mov_b32 m0, s13
	ds_read_b128 v[198:201], v186 offset:16384
	ds_read_b128 v[202:205], v186 offset:17408
	ds_read_b128 v[206:209], v186 offset:18432
	ds_read_b128 v[210:213], v186 offset:19456
	ds_read_b128 v[214:217], v186 offset:20480
	ds_read_b128 v[218:221], v186 offset:21504
	ds_read_b128 v[222:225], v186 offset:22528
	ds_read_b128 v[226:229], v186 offset:23552
	global_load_lds_dwordx4 v150, s[84:85]
	s_add_i32 m0, s13, 0x2000
	s_add_u32 s24, s84, 0x40000
	s_nop 0
	s_addc_u32 s25, s85, 0
	s_add_i32 s13, s63, s89
	global_load_lds_dwordx4 v154, s[84:85]
	s_nop 0
	s_mov_b32 m0, s13
	s_nop 0
	global_load_lds_dwordx4 v150, s[24:25]
	s_nop 0
	s_add_i32 m0, s13, 0x2000
	s_nop 0
	global_load_lds_dwordx4 v154, s[24:25]
	s_nop 0
	s_mov_b32 m0, s90
	s_nop 0
	global_load_lds_dwordx4 v148, s[86:87]
	s_mov_b32 m0, s91
	s_nop 0
	global_load_lds_dwordx4 v152, s[86:87]
	s_waitcnt vmcnt(8)
	s_waitcnt lgkmcnt(0)
	s_barrier
	s_setprio 1
	s_waitcnt lgkmcnt(0)
	v_mfma_f32_16x16x32_bf16 v[78:81], v[34:37], v[198:201], v[78:81]
	v_mfma_f32_16x16x32_bf16 v[74:77], v[42:45], v[198:201], v[74:77]
	v_mfma_f32_16x16x32_bf16 v[62:65], v[34:37], v[206:209], v[62:65]
	v_mfma_f32_16x16x32_bf16 v[58:61], v[42:45], v[206:209], v[58:61]
	v_mfma_f32_16x16x32_bf16 v[30:33], v[34:37], v[214:217], v[30:33]
	v_mfma_f32_16x16x32_bf16 v[26:29], v[42:45], v[214:217], v[26:29]
	v_mfma_f32_16x16x32_bf16 v[14:17], v[34:37], v[222:225], v[14:17]
	v_mfma_f32_16x16x32_bf16 v[10:13], v[42:45], v[222:225], v[10:13]
	v_mfma_f32_16x16x32_bf16 v[78:81], v[38:41], v[202:205], v[78:81]
	v_mfma_f32_16x16x32_bf16 v[74:77], v[46:49], v[202:205], v[74:77]
	v_mfma_f32_16x16x32_bf16 v[62:65], v[38:41], v[210:213], v[62:65]
	v_mfma_f32_16x16x32_bf16 v[58:61], v[46:49], v[210:213], v[58:61]
	v_mfma_f32_16x16x32_bf16 v[30:33], v[38:41], v[218:221], v[30:33]
	v_mfma_f32_16x16x32_bf16 v[26:29], v[46:49], v[218:221], v[26:29]
	v_mfma_f32_16x16x32_bf16 v[14:17], v[38:41], v[226:229], v[14:17]
	v_mfma_f32_16x16x32_bf16 v[10:13], v[46:49], v[226:229], v[10:13]
	s_setprio 0
	s_setprio 1
	v_mfma_f32_16x16x32_bf16 v[22:25], v[166:169], v[214:217], v[22:25]
	v_mfma_f32_16x16x32_bf16 v[18:21], v[190:193], v[214:217], v[18:21]
	v_mfma_f32_16x16x32_bf16 v[6:9], v[166:169], v[222:225], v[6:9]
	v_mfma_f32_16x16x32_bf16 v[2:5], v[190:193], v[222:225], v[2:5]
	v_mfma_f32_16x16x32_bf16 v[34:37], v[166:169], v[198:201], v[70:73]
	v_mfma_f32_16x16x32_bf16 v[38:41], v[190:193], v[198:201], v[66:69]
	v_mfma_f32_16x16x32_bf16 v[42:45], v[166:169], v[206:209], v[54:57]
	v_mfma_f32_16x16x32_bf16 v[46:49], v[190:193], v[206:209], v[50:53]
	v_mfma_f32_16x16x32_bf16 v[22:25], v[170:173], v[218:221], v[22:25]
	v_mfma_f32_16x16x32_bf16 v[18:21], v[194:197], v[218:221], v[18:21]
	v_mfma_f32_16x16x32_bf16 v[6:9], v[170:173], v[226:229], v[6:9]
	v_mfma_f32_16x16x32_bf16 v[2:5], v[194:197], v[226:229], v[2:5]
	v_mfma_f32_16x16x32_bf16 v[34:37], v[170:173], v[202:205], v[34:37]
	v_mfma_f32_16x16x32_bf16 v[38:41], v[194:197], v[202:205], v[38:41]
	v_mfma_f32_16x16x32_bf16 v[42:45], v[170:173], v[210:213], v[42:45]
	v_mfma_f32_16x16x32_bf16 v[46:49], v[194:197], v[210:213], v[46:49]
	s_setprio 0
	s_barrier
	s_add_i32 s13, 0, 0x18000
	s_add_i32 s3, 0, 0x1c000
	v_add_u32_e32 v70, s13, v175
	v_add_u32_e32 v194, s3, v175
	ds_read_b128 v[50:53], v70
	ds_read_b128 v[54:57], v70 offset:1024
	ds_read_b128 v[66:69], v70 offset:2048
	ds_read_b128 v[70:73], v70 offset:3072
	ds_read_b128 v[166:169], v194
	ds_read_b128 v[170:173], v194 offset:1024
	ds_read_b128 v[190:193], v194 offset:2048
	ds_read_b128 v[194:197], v194 offset:3072
	s_add_u32 s24, s86, 0x40000
	s_addc_u32 s25, s87, 0
	s_mov_b32 m0, s92
	s_nop 0
	ds_read_b128 v[198:201], v186 offset:32768
	ds_read_b128 v[202:205], v186 offset:33792
	ds_read_b128 v[206:209], v186 offset:34816
	ds_read_b128 v[210:213], v186 offset:35840
	ds_read_b128 v[214:217], v186 offset:36864
	ds_read_b128 v[218:221], v186 offset:37888
	ds_read_b128 v[222:225], v186 offset:38912
	ds_read_b128 v[226:229], v186 offset:39936
	global_load_lds_dwordx4 v148, s[24:25]
	s_nop 0
	s_mov_b32 m0, s93
	s_nop 0
	global_load_lds_dwordx4 v152, s[24:25]
	s_waitcnt vmcnt(8)
	s_waitcnt lgkmcnt(0)
	s_barrier
	s_setprio 1
	s_waitcnt lgkmcnt(0)
	v_mfma_f32_16x16x32_bf16 v[142:145], v[50:53], v[198:201], v[142:145]
	v_mfma_f32_16x16x32_bf16 v[138:141], v[66:69], v[198:201], v[138:141]
	v_mfma_f32_16x16x32_bf16 v[126:129], v[50:53], v[206:209], v[126:129]
	v_mfma_f32_16x16x32_bf16 v[122:125], v[66:69], v[206:209], v[122:125]
	v_mfma_f32_16x16x32_bf16 v[110:113], v[50:53], v[214:217], v[110:113]
	v_mfma_f32_16x16x32_bf16 v[106:109], v[66:69], v[214:217], v[106:109]
	v_mfma_f32_16x16x32_bf16 v[94:97], v[50:53], v[222:225], v[94:97]
	v_mfma_f32_16x16x32_bf16 v[90:93], v[66:69], v[222:225], v[90:93]
	v_mfma_f32_16x16x32_bf16 v[142:145], v[54:57], v[202:205], v[142:145]
	v_mfma_f32_16x16x32_bf16 v[138:141], v[70:73], v[202:205], v[138:141]
	v_mfma_f32_16x16x32_bf16 v[126:129], v[54:57], v[210:213], v[126:129]
	v_mfma_f32_16x16x32_bf16 v[122:125], v[70:73], v[210:213], v[122:125]
	v_mfma_f32_16x16x32_bf16 v[110:113], v[54:57], v[218:221], v[110:113]
	v_mfma_f32_16x16x32_bf16 v[106:109], v[70:73], v[218:221], v[106:109]
	v_mfma_f32_16x16x32_bf16 v[94:97], v[54:57], v[226:229], v[94:97]
	v_mfma_f32_16x16x32_bf16 v[90:93], v[70:73], v[226:229], v[90:93]
	s_setprio 0
	s_setprio 1
	v_mfma_f32_16x16x32_bf16 v[134:137], v[166:169], v[198:201], v[134:137]
	v_mfma_f32_16x16x32_bf16 v[130:133], v[190:193], v[198:201], v[130:133]
	v_mfma_f32_16x16x32_bf16 v[118:121], v[166:169], v[206:209], v[118:121]
	v_mfma_f32_16x16x32_bf16 v[114:117], v[190:193], v[206:209], v[114:117]
	v_mfma_f32_16x16x32_bf16 v[102:105], v[166:169], v[214:217], v[102:105]
	v_mfma_f32_16x16x32_bf16 v[98:101], v[190:193], v[214:217], v[98:101]
	v_mfma_f32_16x16x32_bf16 v[86:89], v[166:169], v[222:225], v[86:89]
	v_mfma_f32_16x16x32_bf16 v[82:85], v[190:193], v[222:225], v[82:85]
	v_mfma_f32_16x16x32_bf16 v[134:137], v[170:173], v[202:205], v[134:137]
	v_mfma_f32_16x16x32_bf16 v[130:133], v[194:197], v[202:205], v[130:133]
	v_mfma_f32_16x16x32_bf16 v[118:121], v[170:173], v[210:213], v[118:121]
	v_mfma_f32_16x16x32_bf16 v[114:117], v[194:197], v[210:213], v[114:117]
	v_mfma_f32_16x16x32_bf16 v[102:105], v[170:173], v[218:221], v[102:105]
	v_mfma_f32_16x16x32_bf16 v[98:101], v[194:197], v[218:221], v[98:101]
	v_mfma_f32_16x16x32_bf16 v[86:89], v[170:173], v[226:229], v[86:89]
	v_mfma_f32_16x16x32_bf16 v[82:85], v[194:197], v[226:229], v[82:85]
	s_setprio 0
	s_barrier
	s_add_i32 s13, s13, s89
	s_nop 0
	s_mov_b32 m0, s13
	ds_read_b128 v[198:201], v186 offset:49152
	ds_read_b128 v[202:205], v186 offset:50176
	ds_read_b128 v[206:209], v186 offset:51200
	ds_read_b128 v[210:213], v186 offset:52224
	ds_read_b128 v[214:217], v186 offset:53248
	ds_read_b128 v[218:221], v186 offset:54272
	ds_read_b128 v[222:225], v186 offset:55296
	ds_read_b128 v[226:229], v186 offset:56320
	global_load_lds_dwordx4 v251, s[84:85]
	s_add_i32 m0, s13, 0x2000
	s_add_u32 s24, s84, 0x40080
	s_nop 0
	s_addc_u32 s25, s85, 0
	s_add_i32 s3, s3, s89
	global_load_lds_dwordx4 v252, s[84:85]
	s_nop 0
	s_mov_b32 m0, s3
	s_nop 0
	global_load_lds_dwordx4 v150, s[24:25]
	s_nop 0
	s_add_i32 m0, s3, 0x2000
	s_nop 0
	global_load_lds_dwordx4 v154, s[24:25]
	s_nop 0
	s_mov_b32 m0, s97
	s_nop 0
	global_load_lds_dwordx4 v253, s[86:87]
	s_nop 0
	s_mov_b32 m0, s4
	s_nop 0
	global_load_lds_dwordx4 v254, s[86:87]
	s_waitcnt vmcnt(8)
	s_waitcnt lgkmcnt(0)
	s_barrier
	s_setprio 1
	s_waitcnt lgkmcnt(0)
	v_mfma_f32_16x16x32_bf16 v[78:81], v[50:53], v[198:201], v[78:81]
	v_mfma_f32_16x16x32_bf16 v[74:77], v[66:69], v[198:201], v[74:77]
	v_mfma_f32_16x16x32_bf16 v[62:65], v[50:53], v[206:209], v[62:65]
	v_mfma_f32_16x16x32_bf16 v[58:61], v[66:69], v[206:209], v[58:61]
	v_mfma_f32_16x16x32_bf16 v[30:33], v[50:53], v[214:217], v[30:33]
	v_mfma_f32_16x16x32_bf16 v[26:29], v[66:69], v[214:217], v[26:29]
	v_mfma_f32_16x16x32_bf16 v[14:17], v[50:53], v[222:225], v[14:17]
	v_mfma_f32_16x16x32_bf16 v[10:13], v[66:69], v[222:225], v[10:13]
	v_mfma_f32_16x16x32_bf16 v[78:81], v[54:57], v[202:205], v[78:81]
	v_mfma_f32_16x16x32_bf16 v[74:77], v[70:73], v[202:205], v[74:77]
	v_mfma_f32_16x16x32_bf16 v[62:65], v[54:57], v[210:213], v[62:65]
	v_mfma_f32_16x16x32_bf16 v[58:61], v[70:73], v[210:213], v[58:61]
	v_mfma_f32_16x16x32_bf16 v[30:33], v[54:57], v[218:221], v[30:33]
	v_mfma_f32_16x16x32_bf16 v[26:29], v[70:73], v[218:221], v[26:29]
	v_mfma_f32_16x16x32_bf16 v[14:17], v[54:57], v[226:229], v[14:17]
	v_mfma_f32_16x16x32_bf16 v[10:13], v[70:73], v[226:229], v[10:13]
	s_setprio 0
	s_setprio 1
	v_mfma_f32_16x16x32_bf16 v[34:37], v[166:169], v[198:201], v[34:37]
	v_mfma_f32_16x16x32_bf16 v[70:73], v[170:173], v[202:205], v[34:37]
	v_mfma_f32_16x16x32_bf16 v[34:37], v[190:193], v[198:201], v[38:41]
	v_mfma_f32_16x16x32_bf16 v[66:69], v[194:197], v[202:205], v[34:37]
	v_mfma_f32_16x16x32_bf16 v[34:37], v[166:169], v[206:209], v[42:45]
	v_mfma_f32_16x16x32_bf16 v[54:57], v[170:173], v[210:213], v[34:37]
	v_mfma_f32_16x16x32_bf16 v[34:37], v[190:193], v[206:209], v[46:49]
	v_mfma_f32_16x16x32_bf16 v[22:25], v[166:169], v[214:217], v[22:25]
	v_mfma_f32_16x16x32_bf16 v[18:21], v[190:193], v[214:217], v[18:21]
	v_mfma_f32_16x16x32_bf16 v[6:9], v[166:169], v[222:225], v[6:9]
	v_mfma_f32_16x16x32_bf16 v[2:5], v[190:193], v[222:225], v[2:5]
	v_mfma_f32_16x16x32_bf16 v[50:53], v[194:197], v[210:213], v[34:37]
	v_mfma_f32_16x16x32_bf16 v[22:25], v[170:173], v[218:221], v[22:25]
	v_mfma_f32_16x16x32_bf16 v[18:21], v[194:197], v[218:221], v[18:21]
	v_mfma_f32_16x16x32_bf16 v[6:9], v[170:173], v[226:229], v[6:9]
	v_mfma_f32_16x16x32_bf16 v[2:5], v[194:197], v[226:229], v[2:5]
	s_setprio 0
	s_barrier
	s_add_i32 s12, s12, 2
	s_add_u32 s8, s8, 0x100
	s_addc_u32 s9, s9, 0
	s_add_u32 vcc_lo, vcc_lo, 0x100
	s_addc_u32 vcc_hi, vcc_hi, 0
	s_cmp_gt_u32 s12, 13
	s_cbranch_scc0 .LBB0_197
	s_and_b64 vcc, exec, s[74:75]
	s_cbranch_vccz .LBB0_200
	s_barrier

.LBB0_633:
	ds_read_b128 v[152:155], v148
	ds_read_b128 v[156:159], v148 offset:1024
	ds_read_b128 v[160:163], v148 offset:2048
	ds_read_b128 v[164:167], v148 offset:3072
	ds_read_b128 v[168:171], v149
	ds_read_b128 v[172:175], v149 offset:1024
	ds_read_b128 v[176:179], v149 offset:2048
	ds_read_b128 v[180:183], v149 offset:3072
	s_add_i32 s13, s12, 2
	s_add_u32 s3, s88, 0xfffc0080
	s_addc_u32 s24, s89, -1
	s_cmp_eq_u32 s81, s12
	s_cselect_b32 s93, s7, s24
	s_cselect_b32 s92, s6, s3
	s_cselect_b32 s91, s85, vcc_lo
	s_cselect_b32 s90, s84, s83
	s_nop 0
	s_add_i32 m0, s22, 0xc000
	ds_read_b128 v[184:187], v150
	ds_read_b128 v[188:191], v150 offset:1024
	ds_read_b128 v[192:195], v150 offset:2048
	ds_read_b128 v[196:199], v150 offset:3072
	ds_read_b128 v[200:203], v150 offset:4096
	ds_read_b128 v[204:207], v150 offset:5120
	ds_read_b128 v[208:211], v150 offset:6144
	ds_read_b128 v[212:215], v150 offset:7168
	global_load_lds_dwordx4 v140, s[88:89]
	s_nop 0
	s_add_i32 m0, s22, 0xe000
	s_nop 0
	global_load_lds_dwordx4 v142, s[88:89]
	s_waitcnt vmcnt(8)
	s_waitcnt lgkmcnt(0)
	s_barrier
	s_setprio 1
	s_waitcnt lgkmcnt(0)
	v_mfma_f32_16x16x32_bf16 v[126:129], v[152:155], v[184:187], v[126:129]
	v_mfma_f32_16x16x32_bf16 v[122:125], v[160:163], v[184:187], v[122:125]
	v_mfma_f32_16x16x32_bf16 v[118:121], v[152:155], v[192:195], v[118:121]
	v_mfma_f32_16x16x32_bf16 v[114:117], v[160:163], v[192:195], v[114:117]
	v_mfma_f32_16x16x32_bf16 v[106:109], v[152:155], v[200:203], v[106:109]
	v_mfma_f32_16x16x32_bf16 v[98:101], v[160:163], v[200:203], v[98:101]
	v_mfma_f32_16x16x32_bf16 v[90:93], v[152:155], v[208:211], v[90:93]
	v_mfma_f32_16x16x32_bf16 v[82:85], v[160:163], v[208:211], v[82:85]
	v_mfma_f32_16x16x32_bf16 v[126:129], v[156:159], v[188:191], v[126:129]
	v_mfma_f32_16x16x32_bf16 v[122:125], v[164:167], v[188:191], v[122:125]
	v_mfma_f32_16x16x32_bf16 v[118:121], v[156:159], v[196:199], v[118:121]
	v_mfma_f32_16x16x32_bf16 v[114:117], v[164:167], v[196:199], v[114:117]
	v_mfma_f32_16x16x32_bf16 v[106:109], v[156:159], v[204:207], v[106:109]
	v_mfma_f32_16x16x32_bf16 v[98:101], v[164:167], v[204:207], v[98:101]
	v_mfma_f32_16x16x32_bf16 v[90:93], v[156:159], v[212:215], v[90:93]
	v_mfma_f32_16x16x32_bf16 v[82:85], v[164:167], v[212:215], v[82:85]
	s_setprio 0
	s_setprio 1
	v_mfma_f32_16x16x32_bf16 v[110:113], v[168:171], v[184:187], v[110:113]
	v_mfma_f32_16x16x32_bf16 v[102:105], v[176:179], v[184:187], v[102:105]
	v_mfma_f32_16x16x32_bf16 v[94:97], v[168:171], v[192:195], v[94:97]
	v_mfma_f32_16x16x32_bf16 v[86:89], v[176:179], v[192:195], v[86:89]
	v_mfma_f32_16x16x32_bf16 v[78:81], v[168:171], v[200:203], v[78:81]
	v_mfma_f32_16x16x32_bf16 v[74:77], v[176:179], v[200:203], v[74:77]
	v_mfma_f32_16x16x32_bf16 v[70:73], v[168:171], v[208:211], v[70:73]
	v_mfma_f32_16x16x32_bf16 v[66:69], v[176:179], v[208:211], v[66:69]
	v_mfma_f32_16x16x32_bf16 v[110:113], v[172:175], v[188:191], v[110:113]
	v_mfma_f32_16x16x32_bf16 v[102:105], v[180:183], v[188:191], v[102:105]
	v_mfma_f32_16x16x32_bf16 v[94:97], v[172:175], v[196:199], v[94:97]
	v_mfma_f32_16x16x32_bf16 v[86:89], v[180:183], v[196:199], v[86:89]
	v_mfma_f32_16x16x32_bf16 v[78:81], v[172:175], v[204:207], v[78:81]
	v_mfma_f32_16x16x32_bf16 v[74:77], v[180:183], v[204:207], v[74:77]
	v_mfma_f32_16x16x32_bf16 v[70:73], v[172:175], v[212:215], v[70:73]
	v_mfma_f32_16x16x32_bf16 v[66:69], v[180:183], v[212:215], v[66:69]
	s_setprio 0
	s_barrier
	s_add_i32 s3, s60, s4
	s_nop 0
	s_mov_b32 m0, s3
	ds_read_b128 v[184:187], v150 offset:16384
	ds_read_b128 v[188:191], v150 offset:17408
	ds_read_b128 v[192:195], v150 offset:18432
	ds_read_b128 v[196:199], v150 offset:19456
	ds_read_b128 v[200:203], v150 offset:20480
	ds_read_b128 v[204:207], v150 offset:21504
	ds_read_b128 v[208:211], v150 offset:22528
	ds_read_b128 v[212:215], v150 offset:23552
	global_load_lds_dwordx4 v134, s[90:91]
	s_add_i32 m0, s3, 0x2000
	s_add_u32 s24, s90, 0x40000
	s_nop 0
	s_addc_u32 s25, s91, 0
	s_add_i32 s3, s61, s4
	global_load_lds_dwordx4 v130, s[90:91]
	s_nop 0
	s_mov_b32 m0, s3
	s_nop 0
	global_load_lds_dwordx4 v134, s[24:25]
	s_nop 0
	s_add_i32 m0, s3, 0x2000
	s_nop 0
	global_load_lds_dwordx4 v130, s[24:25]
	s_nop 0
	s_mov_b32 m0, s22
	s_nop 0
	global_load_lds_dwordx4 v136, s[92:93]
	s_mov_b32 m0, s23
	s_nop 0
	global_load_lds_dwordx4 v132, s[92:93]
	s_waitcnt vmcnt(8)
	s_waitcnt lgkmcnt(0)
	s_barrier
	s_setprio 1
	s_waitcnt lgkmcnt(0)
	v_mfma_f32_16x16x32_bf16 v[62:65], v[152:155], v[184:187], v[62:65]
	v_mfma_f32_16x16x32_bf16 v[58:61], v[160:163], v[184:187], v[58:61]
	v_mfma_f32_16x16x32_bf16 v[54:57], v[152:155], v[192:195], v[54:57]
	v_mfma_f32_16x16x32_bf16 v[50:53], v[160:163], v[192:195], v[50:53]
	v_mfma_f32_16x16x32_bf16 v[42:45], v[152:155], v[200:203], v[42:45]
	v_mfma_f32_16x16x32_bf16 v[34:37], v[160:163], v[200:203], v[34:37]
	v_mfma_f32_16x16x32_bf16 v[26:29], v[152:155], v[208:211], v[26:29]
	v_mfma_f32_16x16x32_bf16 v[18:21], v[160:163], v[208:211], v[18:21]
	v_mfma_f32_16x16x32_bf16 v[62:65], v[156:159], v[188:191], v[62:65]
	v_mfma_f32_16x16x32_bf16 v[58:61], v[164:167], v[188:191], v[58:61]
	v_mfma_f32_16x16x32_bf16 v[54:57], v[156:159], v[196:199], v[54:57]
	v_mfma_f32_16x16x32_bf16 v[50:53], v[164:167], v[196:199], v[50:53]
	v_mfma_f32_16x16x32_bf16 v[42:45], v[156:159], v[204:207], v[42:45]
	v_mfma_f32_16x16x32_bf16 v[34:37], v[164:167], v[204:207], v[34:37]
	v_mfma_f32_16x16x32_bf16 v[26:29], v[156:159], v[212:215], v[26:29]
	v_mfma_f32_16x16x32_bf16 v[18:21], v[164:167], v[212:215], v[18:21]
	s_setprio 0
	s_setprio 1
	v_mfma_f32_16x16x32_bf16 v[46:49], v[168:171], v[184:187], v[46:49]
	v_mfma_f32_16x16x32_bf16 v[38:41], v[176:179], v[184:187], v[38:41]
	v_mfma_f32_16x16x32_bf16 v[30:33], v[168:171], v[192:195], v[30:33]
	v_mfma_f32_16x16x32_bf16 v[22:25], v[176:179], v[192:195], v[22:25]
	v_mfma_f32_16x16x32_bf16 v[14:17], v[168:171], v[200:203], v[14:17]
	v_mfma_f32_16x16x32_bf16 v[10:13], v[176:179], v[200:203], v[10:13]
	v_mfma_f32_16x16x32_bf16 v[6:9], v[168:171], v[208:211], v[6:9]
	v_mfma_f32_16x16x32_bf16 v[2:5], v[176:179], v[208:211], v[2:5]
	v_mfma_f32_16x16x32_bf16 v[46:49], v[172:175], v[188:191], v[46:49]
	v_mfma_f32_16x16x32_bf16 v[38:41], v[180:183], v[188:191], v[38:41]
	v_mfma_f32_16x16x32_bf16 v[30:33], v[172:175], v[196:199], v[30:33]
	v_mfma_f32_16x16x32_bf16 v[22:25], v[180:183], v[196:199], v[22:25]
	v_mfma_f32_16x16x32_bf16 v[14:17], v[172:175], v[204:207], v[14:17]
	v_mfma_f32_16x16x32_bf16 v[10:13], v[180:183], v[204:207], v[10:13]
	v_mfma_f32_16x16x32_bf16 v[6:9], v[172:175], v[212:215], v[6:9]
	v_mfma_f32_16x16x32_bf16 v[2:5], v[180:183], v[212:215], v[2:5]
	s_setprio 0
	s_barrier
	s_add_i32 s3, 0, 0x18000
	v_add_u32_e32 v151, s3, v1
	s_add_i32 s12, 0, 0x1c000
	ds_read_b128 v[152:155], v151
	ds_read_b128 v[156:159], v151 offset:1024
	ds_read_b128 v[160:163], v151 offset:2048
	ds_read_b128 v[164:167], v151 offset:3072
	v_add_u32_e32 v151, s12, v1
	ds_read_b128 v[168:171], v151
	ds_read_b128 v[172:175], v151 offset:1024
	ds_read_b128 v[176:179], v151 offset:2048
	ds_read_b128 v[180:183], v151 offset:3072
	s_add_u32 s24, s92, 0x40000
	s_addc_u32 s25, s93, 0
	s_mov_b32 m0, s33
	s_nop 0
	ds_read_b128 v[184:187], v150 offset:32768
	ds_read_b128 v[188:191], v150 offset:33792
	ds_read_b128 v[192:195], v150 offset:34816
	ds_read_b128 v[196:199], v150 offset:35840
	ds_read_b128 v[200:203], v150 offset:36864
	ds_read_b128 v[204:207], v150 offset:37888
	ds_read_b128 v[208:211], v150 offset:38912
	ds_read_b128 v[212:215], v150 offset:39936
	global_load_lds_dwordx4 v136, s[24:25]
	s_nop 0
	s_mov_b32 m0, s44
	s_nop 0
	global_load_lds_dwordx4 v132, s[24:25]
	s_waitcnt vmcnt(8)
	s_waitcnt lgkmcnt(0)
	s_barrier
	s_setprio 1
	s_waitcnt lgkmcnt(0)
	v_mfma_f32_16x16x32_bf16 v[126:129], v[152:155], v[184:187], v[126:129]
	v_mfma_f32_16x16x32_bf16 v[122:125], v[160:163], v[184:187], v[122:125]
	v_mfma_f32_16x16x32_bf16 v[118:121], v[152:155], v[192:195], v[118:121]
	v_mfma_f32_16x16x32_bf16 v[114:117], v[160:163], v[192:195], v[114:117]
	v_mfma_f32_16x16x32_bf16 v[106:109], v[152:155], v[200:203], v[106:109]
	v_mfma_f32_16x16x32_bf16 v[98:101], v[160:163], v[200:203], v[98:101]
	v_mfma_f32_16x16x32_bf16 v[90:93], v[152:155], v[208:211], v[90:93]
	v_mfma_f32_16x16x32_bf16 v[82:85], v[160:163], v[208:211], v[82:85]
	v_mfma_f32_16x16x32_bf16 v[126:129], v[156:159], v[188:191], v[126:129]
	v_mfma_f32_16x16x32_bf16 v[122:125], v[164:167], v[188:191], v[122:125]
	v_mfma_f32_16x16x32_bf16 v[118:121], v[156:159], v[196:199], v[118:121]
	v_mfma_f32_16x16x32_bf16 v[114:117], v[164:167], v[196:199], v[114:117]
	v_mfma_f32_16x16x32_bf16 v[106:109], v[156:159], v[204:207], v[106:109]
	v_mfma_f32_16x16x32_bf16 v[98:101], v[164:167], v[204:207], v[98:101]
	v_mfma_f32_16x16x32_bf16 v[90:93], v[156:159], v[212:215], v[90:93]
	v_mfma_f32_16x16x32_bf16 v[82:85], v[164:167], v[212:215], v[82:85]
	s_setprio 0
	s_setprio 1
	v_mfma_f32_16x16x32_bf16 v[110:113], v[168:171], v[184:187], v[110:113]
	v_mfma_f32_16x16x32_bf16 v[102:105], v[176:179], v[184:187], v[102:105]
	v_mfma_f32_16x16x32_bf16 v[94:97], v[168:171], v[192:195], v[94:97]
	v_mfma_f32_16x16x32_bf16 v[86:89], v[176:179], v[192:195], v[86:89]
	v_mfma_f32_16x16x32_bf16 v[78:81], v[168:171], v[200:203], v[78:81]
	v_mfma_f32_16x16x32_bf16 v[74:77], v[176:179], v[200:203], v[74:77]
	v_mfma_f32_16x16x32_bf16 v[70:73], v[168:171], v[208:211], v[70:73]
	v_mfma_f32_16x16x32_bf16 v[66:69], v[176:179], v[208:211], v[66:69]
	v_mfma_f32_16x16x32_bf16 v[110:113], v[172:175], v[188:191], v[110:113]
	v_mfma_f32_16x16x32_bf16 v[102:105], v[180:183], v[188:191], v[102:105]
	v_mfma_f32_16x16x32_bf16 v[94:97], v[172:175], v[196:199], v[94:97]
	v_mfma_f32_16x16x32_bf16 v[86:89], v[180:183], v[196:199], v[86:89]
	v_mfma_f32_16x16x32_bf16 v[78:81], v[172:175], v[204:207], v[78:81]
	v_mfma_f32_16x16x32_bf16 v[74:77], v[180:183], v[204:207], v[74:77]
	v_mfma_f32_16x16x32_bf16 v[70:73], v[172:175], v[212:215], v[70:73]
	v_mfma_f32_16x16x32_bf16 v[66:69], v[180:183], v[212:215], v[66:69]
	s_setprio 0
	s_barrier
	s_add_i32 s3, s3, s4
	s_nop 0
	s_mov_b32 m0, s3
	ds_read_b128 v[184:187], v150 offset:49152
	ds_read_b128 v[188:191], v150 offset:50176
	ds_read_b128 v[192:195], v150 offset:51200
	ds_read_b128 v[196:199], v150 offset:52224
	ds_read_b128 v[200:203], v150 offset:53248
	ds_read_b128 v[204:207], v150 offset:54272
	ds_read_b128 v[208:211], v150 offset:55296
	ds_read_b128 v[212:215], v150 offset:56320
	global_load_lds_dwordx4 v251, s[90:91]
	s_add_i32 m0, s3, 0x2000
	s_add_u32 s24, s90, 0x40080
	s_nop 0
	s_addc_u32 s25, s91, 0
	s_add_i32 s3, s12, s4
	global_load_lds_dwordx4 v252, s[90:91]
	s_nop 0
	s_mov_b32 m0, s3
	s_nop 0
	global_load_lds_dwordx4 v134, s[24:25]
	s_nop 0
	s_add_i32 m0, s3, 0x2000
	s_nop 0
	global_load_lds_dwordx4 v130, s[24:25]
	s_nop 0
	s_mov_b32 m0, s48
	s_nop 0
	global_load_lds_dwordx4 v253, s[92:93]
	s_nop 0
	s_mov_b32 m0, s49
	s_nop 0
	global_load_lds_dwordx4 v254, s[92:93]
	s_waitcnt vmcnt(8)
	s_waitcnt lgkmcnt(0)
	s_barrier
	s_setprio 1
	s_waitcnt lgkmcnt(0)
	v_mfma_f32_16x16x32_bf16 v[62:65], v[152:155], v[184:187], v[62:65]
	v_mfma_f32_16x16x32_bf16 v[58:61], v[160:163], v[184:187], v[58:61]
	v_mfma_f32_16x16x32_bf16 v[54:57], v[152:155], v[192:195], v[54:57]
	v_mfma_f32_16x16x32_bf16 v[50:53], v[160:163], v[192:195], v[50:53]
	v_mfma_f32_16x16x32_bf16 v[42:45], v[152:155], v[200:203], v[42:45]
	v_mfma_f32_16x16x32_bf16 v[34:37], v[160:163], v[200:203], v[34:37]
	v_mfma_f32_16x16x32_bf16 v[26:29], v[152:155], v[208:211], v[26:29]
	v_mfma_f32_16x16x32_bf16 v[18:21], v[160:163], v[208:211], v[18:21]
	v_mfma_f32_16x16x32_bf16 v[62:65], v[156:159], v[188:191], v[62:65]
	v_mfma_f32_16x16x32_bf16 v[58:61], v[164:167], v[188:191], v[58:61]
	v_mfma_f32_16x16x32_bf16 v[54:57], v[156:159], v[196:199], v[54:57]
	v_mfma_f32_16x16x32_bf16 v[50:53], v[164:167], v[196:199], v[50:53]
	v_mfma_f32_16x16x32_bf16 v[42:45], v[156:159], v[204:207], v[42:45]
	v_mfma_f32_16x16x32_bf16 v[34:37], v[164:167], v[204:207], v[34:37]
	v_mfma_f32_16x16x32_bf16 v[26:29], v[156:159], v[212:215], v[26:29]
	v_mfma_f32_16x16x32_bf16 v[18:21], v[164:167], v[212:215], v[18:21]
	s_setprio 0
	s_setprio 1
	v_mfma_f32_16x16x32_bf16 v[46:49], v[168:171], v[184:187], v[46:49]
	v_mfma_f32_16x16x32_bf16 v[38:41], v[176:179], v[184:187], v[38:41]
	v_mfma_f32_16x16x32_bf16 v[30:33], v[168:171], v[192:195], v[30:33]
	v_mfma_f32_16x16x32_bf16 v[22:25], v[176:179], v[192:195], v[22:25]
	v_mfma_f32_16x16x32_bf16 v[14:17], v[168:171], v[200:203], v[14:17]
	v_mfma_f32_16x16x32_bf16 v[10:13], v[176:179], v[200:203], v[10:13]
	v_mfma_f32_16x16x32_bf16 v[6:9], v[168:171], v[208:211], v[6:9]
	v_mfma_f32_16x16x32_bf16 v[2:5], v[176:179], v[208:211], v[2:5]
	v_mfma_f32_16x16x32_bf16 v[46:49], v[172:175], v[188:191], v[46:49]
	v_mfma_f32_16x16x32_bf16 v[38:41], v[180:183], v[188:191], v[38:41]
	v_mfma_f32_16x16x32_bf16 v[30:33], v[172:175], v[196:199], v[30:33]
	v_mfma_f32_16x16x32_bf16 v[22:25], v[180:183], v[196:199], v[22:25]
	v_mfma_f32_16x16x32_bf16 v[14:17], v[172:175], v[204:207], v[14:17]
	v_mfma_f32_16x16x32_bf16 v[10:13], v[180:183], v[204:207], v[10:13]
	v_mfma_f32_16x16x32_bf16 v[6:9], v[172:175], v[212:215], v[6:9]
	v_mfma_f32_16x16x32_bf16 v[2:5], v[180:183], v[212:215], v[2:5]
	s_setprio 0
	s_barrier
	s_add_u32 s88, s88, 0x100
	s_addc_u32 s89, s89, 0
	s_add_u32 s83, s83, 0x100
	s_addc_u32 vcc_lo, vcc_lo, 0
	s_cmp_ge_i32 s13, s87
	s_mov_b32 s12, s13
	s_cbranch_scc0 .LBB0_633
	s_and_b64 vcc, exec, s[76:77]
	s_cbranch_vccz .LBB0_636
	s_barrier

.LBB0_663:
	ds_read_b128 v[98:101], v222
	ds_read_b128 v[102:105], v222 offset:1024
	ds_read_b128 v[154:157], v222 offset:2048
	ds_read_b128 v[158:161], v222 offset:3072
	ds_read_b128 v[162:165], v223
	ds_read_b128 v[166:169], v223 offset:1024
	ds_read_b128 v[170:173], v223 offset:2048
	ds_read_b128 v[174:177], v223 offset:3072
	s_add_u32 s3, s82, 0xfffc0080
	s_addc_u32 s13, s83, -1
	s_cmp_eq_u32 s12, 12
	s_cselect_b32 s87, s37, s13
	s_cselect_b32 s86, s49, s3
	s_cselect_b32 s85, s71, vcc_lo
	s_cselect_b32 s84, s73, s79
	s_nop 0
	s_add_i32 m0, s22, 0xc000
	ds_read_b128 v[178:181], v224
	ds_read_b128 v[182:185], v224 offset:1024
	ds_read_b128 v[186:189], v224 offset:2048
	ds_read_b128 v[190:193], v224 offset:3072
	ds_read_b128 v[194:197], v224 offset:4096
	ds_read_b128 v[198:201], v224 offset:5120
	ds_read_b128 v[202:205], v224 offset:6144
	ds_read_b128 v[206:209], v224 offset:7168
	global_load_lds_dwordx4 v146, s[82:83]
	s_nop 0
	s_add_i32 m0, s22, 0xe000
	s_nop 0
	global_load_lds_dwordx4 v148, s[82:83]
	s_waitcnt vmcnt(8)
	s_waitcnt lgkmcnt(0)
	s_barrier
	s_setprio 1
	s_waitcnt lgkmcnt(0)
	v_mfma_f32_16x16x32_bf16 v[134:137], v[98:101], v[178:181], v[134:137]
	v_mfma_f32_16x16x32_bf16 v[130:133], v[154:157], v[178:181], v[130:133]
	v_mfma_f32_16x16x32_bf16 v[126:129], v[98:101], v[186:189], v[126:129]
	v_mfma_f32_16x16x32_bf16 v[122:125], v[154:157], v[186:189], v[122:125]
	v_mfma_f32_16x16x32_bf16 v[118:121], v[98:101], v[194:197], v[118:121]
	v_mfma_f32_16x16x32_bf16 v[114:117], v[154:157], v[194:197], v[114:117]
	v_mfma_f32_16x16x32_bf16 v[110:113], v[98:101], v[202:205], v[110:113]
	v_mfma_f32_16x16x32_bf16 v[106:109], v[154:157], v[202:205], v[106:109]
	v_mfma_f32_16x16x32_bf16 v[134:137], v[102:105], v[182:185], v[134:137]
	v_mfma_f32_16x16x32_bf16 v[130:133], v[158:161], v[182:185], v[130:133]
	v_mfma_f32_16x16x32_bf16 v[126:129], v[102:105], v[190:193], v[126:129]
	v_mfma_f32_16x16x32_bf16 v[122:125], v[158:161], v[190:193], v[122:125]
	v_mfma_f32_16x16x32_bf16 v[118:121], v[102:105], v[198:201], v[118:121]
	v_mfma_f32_16x16x32_bf16 v[114:117], v[158:161], v[198:201], v[114:117]
	v_mfma_f32_16x16x32_bf16 v[110:113], v[102:105], v[206:209], v[110:113]
	v_mfma_f32_16x16x32_bf16 v[106:109], v[158:161], v[206:209], v[106:109]
	s_setprio 0
	s_setprio 1
	v_mfma_f32_16x16x32_bf16 v[62:65], v[162:165], v[178:181], v[62:65]
	v_mfma_f32_16x16x32_bf16 v[58:61], v[170:173], v[178:181], v[58:61]
	v_mfma_f32_16x16x32_bf16 v[54:57], v[162:165], v[186:189], v[54:57]
	v_mfma_f32_16x16x32_bf16 v[50:53], v[170:173], v[186:189], v[50:53]
	v_mfma_f32_16x16x32_bf16 v[46:49], v[162:165], v[194:197], v[46:49]
	v_mfma_f32_16x16x32_bf16 v[42:45], v[170:173], v[194:197], v[42:45]
	v_mfma_f32_16x16x32_bf16 v[38:41], v[162:165], v[202:205], v[38:41]
	v_mfma_f32_16x16x32_bf16 v[34:37], v[170:173], v[202:205], v[34:37]
	v_mfma_f32_16x16x32_bf16 v[62:65], v[166:169], v[182:185], v[62:65]
	v_mfma_f32_16x16x32_bf16 v[58:61], v[174:177], v[182:185], v[58:61]
	v_mfma_f32_16x16x32_bf16 v[54:57], v[166:169], v[190:193], v[54:57]
	v_mfma_f32_16x16x32_bf16 v[50:53], v[174:177], v[190:193], v[50:53]
	v_mfma_f32_16x16x32_bf16 v[46:49], v[166:169], v[198:201], v[46:49]
	v_mfma_f32_16x16x32_bf16 v[42:45], v[174:177], v[198:201], v[42:45]
	v_mfma_f32_16x16x32_bf16 v[38:41], v[166:169], v[206:209], v[38:41]
	v_mfma_f32_16x16x32_bf16 v[34:37], v[174:177], v[206:209], v[34:37]
	s_setprio 0
	s_barrier
	s_add_i32 s3, s93, s5
	s_nop 0
	s_mov_b32 m0, s3
	ds_read_b128 v[178:181], v224 offset:16384
	ds_read_b128 v[182:185], v224 offset:17408
	ds_read_b128 v[186:189], v224 offset:18432
	ds_read_b128 v[190:193], v224 offset:19456
	ds_read_b128 v[194:197], v224 offset:20480
	ds_read_b128 v[198:201], v224 offset:21504
	ds_read_b128 v[202:205], v224 offset:22528
	ds_read_b128 v[206:209], v224 offset:23552
	global_load_lds_dwordx4 v140, s[84:85]
	s_add_i32 m0, s3, 0x2000
	s_add_u32 s24, s84, 0x40000
	s_nop 0
	s_addc_u32 s25, s85, 0
	s_add_i32 s3, s48, s5
	global_load_lds_dwordx4 v144, s[84:85]
	s_nop 0
	s_mov_b32 m0, s3
	s_nop 0
	global_load_lds_dwordx4 v140, s[24:25]
	s_nop 0
	s_add_i32 m0, s3, 0x2000
	s_nop 0
	global_load_lds_dwordx4 v144, s[24:25]
	s_nop 0
	s_mov_b32 m0, s22
	s_nop 0
	global_load_lds_dwordx4 v138, s[86:87]
	s_mov_b32 m0, s23
	s_nop 0
	global_load_lds_dwordx4 v142, s[86:87]
	s_waitcnt vmcnt(8)
	s_waitcnt lgkmcnt(0)
	s_barrier
	s_setprio 1
	s_waitcnt lgkmcnt(0)
	v_mfma_f32_16x16x32_bf16 v[94:97], v[98:101], v[178:181], v[94:97]
	v_mfma_f32_16x16x32_bf16 v[90:93], v[154:157], v[178:181], v[90:93]
	v_mfma_f32_16x16x32_bf16 v[86:89], v[98:101], v[186:189], v[86:89]
	v_mfma_f32_16x16x32_bf16 v[82:85], v[154:157], v[186:189], v[82:85]
	v_mfma_f32_16x16x32_bf16 v[78:81], v[98:101], v[194:197], v[78:81]
	v_mfma_f32_16x16x32_bf16 v[74:77], v[154:157], v[194:197], v[74:77]
	v_mfma_f32_16x16x32_bf16 v[70:73], v[98:101], v[202:205], v[70:73]
	v_mfma_f32_16x16x32_bf16 v[66:69], v[154:157], v[202:205], v[66:69]
	v_mfma_f32_16x16x32_bf16 v[94:97], v[102:105], v[182:185], v[94:97]
	v_mfma_f32_16x16x32_bf16 v[90:93], v[158:161], v[182:185], v[90:93]
	v_mfma_f32_16x16x32_bf16 v[86:89], v[102:105], v[190:193], v[86:89]
	v_mfma_f32_16x16x32_bf16 v[82:85], v[158:161], v[190:193], v[82:85]
	v_mfma_f32_16x16x32_bf16 v[78:81], v[102:105], v[198:201], v[78:81]
	v_mfma_f32_16x16x32_bf16 v[74:77], v[158:161], v[198:201], v[74:77]
	v_mfma_f32_16x16x32_bf16 v[70:73], v[102:105], v[206:209], v[70:73]
	v_mfma_f32_16x16x32_bf16 v[66:69], v[158:161], v[206:209], v[66:69]
	s_setprio 0
	s_setprio 1
	v_mfma_f32_16x16x32_bf16 v[30:33], v[162:165], v[178:181], v[30:33]
	v_mfma_f32_16x16x32_bf16 v[26:29], v[170:173], v[178:181], v[26:29]
	v_mfma_f32_16x16x32_bf16 v[22:25], v[162:165], v[186:189], v[22:25]
	v_mfma_f32_16x16x32_bf16 v[18:21], v[170:173], v[186:189], v[18:21]
	v_mfma_f32_16x16x32_bf16 v[14:17], v[162:165], v[194:197], v[14:17]
	v_mfma_f32_16x16x32_bf16 v[10:13], v[170:173], v[194:197], v[10:13]
	v_mfma_f32_16x16x32_bf16 v[6:9], v[162:165], v[202:205], v[6:9]
	v_mfma_f32_16x16x32_bf16 v[2:5], v[170:173], v[202:205], v[2:5]
	v_mfma_f32_16x16x32_bf16 v[30:33], v[166:169], v[182:185], v[30:33]
	v_mfma_f32_16x16x32_bf16 v[26:29], v[174:177], v[182:185], v[26:29]
	v_mfma_f32_16x16x32_bf16 v[22:25], v[166:169], v[190:193], v[22:25]
	v_mfma_f32_16x16x32_bf16 v[18:21], v[174:177], v[190:193], v[18:21]
	v_mfma_f32_16x16x32_bf16 v[14:17], v[166:169], v[198:201], v[14:17]
	v_mfma_f32_16x16x32_bf16 v[10:13], v[174:177], v[198:201], v[10:13]
	v_mfma_f32_16x16x32_bf16 v[6:9], v[166:169], v[206:209], v[6:9]
	v_mfma_f32_16x16x32_bf16 v[2:5], v[174:177], v[206:209], v[2:5]
	s_setprio 0
	s_barrier
	s_add_i32 s3, 0, 0x18000
	s_add_i32 s13, 0, 0x1c000
	v_add_u32_e32 v158, s3, v220
	v_add_u32_e32 v174, s13, v220
	ds_read_b128 v[98:101], v158
	ds_read_b128 v[102:105], v158 offset:1024
	ds_read_b128 v[154:157], v158 offset:2048
	ds_read_b128 v[158:161], v158 offset:3072
	ds_read_b128 v[162:165], v174
	ds_read_b128 v[166:169], v174 offset:1024
	ds_read_b128 v[170:173], v174 offset:2048
	ds_read_b128 v[174:177], v174 offset:3072
	s_add_u32 s24, s86, 0x40000
	s_addc_u32 s25, s87, 0
	s_mov_b32 m0, s33
	s_nop 0
	ds_read_b128 v[178:181], v224 offset:32768
	ds_read_b128 v[182:185], v224 offset:33792
	ds_read_b128 v[186:189], v224 offset:34816
	ds_read_b128 v[190:193], v224 offset:35840
	ds_read_b128 v[194:197], v224 offset:36864
	ds_read_b128 v[198:201], v224 offset:37888
	ds_read_b128 v[202:205], v224 offset:38912
	ds_read_b128 v[206:209], v224 offset:39936
	global_load_lds_dwordx4 v138, s[24:25]
	s_nop 0
	s_mov_b32 m0, s44
	s_nop 0
	global_load_lds_dwordx4 v142, s[24:25]
	s_waitcnt vmcnt(8)
	s_waitcnt lgkmcnt(0)
	s_barrier
	s_setprio 1
	s_waitcnt lgkmcnt(0)
	v_mfma_f32_16x16x32_bf16 v[134:137], v[98:101], v[178:181], v[134:137]
	v_mfma_f32_16x16x32_bf16 v[130:133], v[154:157], v[178:181], v[130:133]
	v_mfma_f32_16x16x32_bf16 v[126:129], v[98:101], v[186:189], v[126:129]
	v_mfma_f32_16x16x32_bf16 v[122:125], v[154:157], v[186:189], v[122:125]
	v_mfma_f32_16x16x32_bf16 v[118:121], v[98:101], v[194:197], v[118:121]
	v_mfma_f32_16x16x32_bf16 v[114:117], v[154:157], v[194:197], v[114:117]
	v_mfma_f32_16x16x32_bf16 v[110:113], v[98:101], v[202:205], v[110:113]
	v_mfma_f32_16x16x32_bf16 v[106:109], v[154:157], v[202:205], v[106:109]
	v_mfma_f32_16x16x32_bf16 v[134:137], v[102:105], v[182:185], v[134:137]
	v_mfma_f32_16x16x32_bf16 v[130:133], v[158:161], v[182:185], v[130:133]
	v_mfma_f32_16x16x32_bf16 v[126:129], v[102:105], v[190:193], v[126:129]
	v_mfma_f32_16x16x32_bf16 v[122:125], v[158:161], v[190:193], v[122:125]
	v_mfma_f32_16x16x32_bf16 v[118:121], v[102:105], v[198:201], v[118:121]
	v_mfma_f32_16x16x32_bf16 v[114:117], v[158:161], v[198:201], v[114:117]
	v_mfma_f32_16x16x32_bf16 v[110:113], v[102:105], v[206:209], v[110:113]
	v_mfma_f32_16x16x32_bf16 v[106:109], v[158:161], v[206:209], v[106:109]
	s_setprio 0
	s_setprio 1
	v_mfma_f32_16x16x32_bf16 v[62:65], v[162:165], v[178:181], v[62:65]
	v_mfma_f32_16x16x32_bf16 v[58:61], v[170:173], v[178:181], v[58:61]
	v_mfma_f32_16x16x32_bf16 v[54:57], v[162:165], v[186:189], v[54:57]
	v_mfma_f32_16x16x32_bf16 v[50:53], v[170:173], v[186:189], v[50:53]
	v_mfma_f32_16x16x32_bf16 v[46:49], v[162:165], v[194:197], v[46:49]
	v_mfma_f32_16x16x32_bf16 v[42:45], v[170:173], v[194:197], v[42:45]
	v_mfma_f32_16x16x32_bf16 v[38:41], v[162:165], v[202:205], v[38:41]
	v_mfma_f32_16x16x32_bf16 v[34:37], v[170:173], v[202:205], v[34:37]
	v_mfma_f32_16x16x32_bf16 v[62:65], v[166:169], v[182:185], v[62:65]
	v_mfma_f32_16x16x32_bf16 v[58:61], v[174:177], v[182:185], v[58:61]
	v_mfma_f32_16x16x32_bf16 v[54:57], v[166:169], v[190:193], v[54:57]
	v_mfma_f32_16x16x32_bf16 v[50:53], v[174:177], v[190:193], v[50:53]
	v_mfma_f32_16x16x32_bf16 v[46:49], v[166:169], v[198:201], v[46:49]
	v_mfma_f32_16x16x32_bf16 v[42:45], v[174:177], v[198:201], v[42:45]
	v_mfma_f32_16x16x32_bf16 v[38:41], v[166:169], v[206:209], v[38:41]
	v_mfma_f32_16x16x32_bf16 v[34:37], v[174:177], v[206:209], v[34:37]
	s_setprio 0
	s_barrier
	s_add_i32 s3, s3, s5
	s_nop 0
	s_mov_b32 m0, s3
	ds_read_b128 v[178:181], v224 offset:49152
	ds_read_b128 v[182:185], v224 offset:50176
	ds_read_b128 v[186:189], v224 offset:51200
	ds_read_b128 v[190:193], v224 offset:52224
	ds_read_b128 v[194:197], v224 offset:53248
	ds_read_b128 v[198:201], v224 offset:54272
	ds_read_b128 v[202:205], v224 offset:55296
	ds_read_b128 v[206:209], v224 offset:56320
	global_load_lds_dwordx4 v251, s[84:85]
	s_add_i32 m0, s3, 0x2000
	s_add_u32 s24, s84, 0x40080
	s_nop 0
	s_addc_u32 s25, s85, 0
	s_add_i32 s3, s13, s5
	global_load_lds_dwordx4 v252, s[84:85]
	s_nop 0
	s_mov_b32 m0, s3
	s_nop 0
	global_load_lds_dwordx4 v140, s[24:25]
	s_nop 0
	s_add_i32 m0, s3, 0x2000
	s_nop 0
	global_load_lds_dwordx4 v144, s[24:25]
	s_nop 0
	s_mov_b32 m0, s90
	s_nop 0
	global_load_lds_dwordx4 v253, s[86:87]
	s_nop 0
	s_mov_b32 m0, s91
	s_nop 0
	global_load_lds_dwordx4 v254, s[86:87]
	s_waitcnt vmcnt(8)
	s_waitcnt lgkmcnt(0)
	s_barrier
	s_setprio 1
	s_waitcnt lgkmcnt(0)
	v_mfma_f32_16x16x32_bf16 v[94:97], v[98:101], v[178:181], v[94:97]
	v_mfma_f32_16x16x32_bf16 v[90:93], v[154:157], v[178:181], v[90:93]
	v_mfma_f32_16x16x32_bf16 v[86:89], v[98:101], v[186:189], v[86:89]
	v_mfma_f32_16x16x32_bf16 v[82:85], v[154:157], v[186:189], v[82:85]
	v_mfma_f32_16x16x32_bf16 v[78:81], v[98:101], v[194:197], v[78:81]
	v_mfma_f32_16x16x32_bf16 v[74:77], v[154:157], v[194:197], v[74:77]
	v_mfma_f32_16x16x32_bf16 v[70:73], v[98:101], v[202:205], v[70:73]
	v_mfma_f32_16x16x32_bf16 v[66:69], v[154:157], v[202:205], v[66:69]
	v_mfma_f32_16x16x32_bf16 v[94:97], v[102:105], v[182:185], v[94:97]
	v_mfma_f32_16x16x32_bf16 v[90:93], v[158:161], v[182:185], v[90:93]
	v_mfma_f32_16x16x32_bf16 v[86:89], v[102:105], v[190:193], v[86:89]
	v_mfma_f32_16x16x32_bf16 v[82:85], v[158:161], v[190:193], v[82:85]
	v_mfma_f32_16x16x32_bf16 v[78:81], v[102:105], v[198:201], v[78:81]
	v_mfma_f32_16x16x32_bf16 v[74:77], v[158:161], v[198:201], v[74:77]
	v_mfma_f32_16x16x32_bf16 v[70:73], v[102:105], v[206:209], v[70:73]
	v_mfma_f32_16x16x32_bf16 v[66:69], v[158:161], v[206:209], v[66:69]
	s_setprio 0
	s_setprio 1
	v_mfma_f32_16x16x32_bf16 v[30:33], v[162:165], v[178:181], v[30:33]
	v_mfma_f32_16x16x32_bf16 v[26:29], v[170:173], v[178:181], v[26:29]
	v_mfma_f32_16x16x32_bf16 v[22:25], v[162:165], v[186:189], v[22:25]
	v_mfma_f32_16x16x32_bf16 v[18:21], v[170:173], v[186:189], v[18:21]
	v_mfma_f32_16x16x32_bf16 v[14:17], v[162:165], v[194:197], v[14:17]
	v_mfma_f32_16x16x32_bf16 v[10:13], v[170:173], v[194:197], v[10:13]
	v_mfma_f32_16x16x32_bf16 v[6:9], v[162:165], v[202:205], v[6:9]
	v_mfma_f32_16x16x32_bf16 v[2:5], v[170:173], v[202:205], v[2:5]
	v_mfma_f32_16x16x32_bf16 v[30:33], v[166:169], v[182:185], v[30:33]
	v_mfma_f32_16x16x32_bf16 v[26:29], v[174:177], v[182:185], v[26:29]
	v_mfma_f32_16x16x32_bf16 v[22:25], v[166:169], v[190:193], v[22:25]
	v_mfma_f32_16x16x32_bf16 v[18:21], v[174:177], v[190:193], v[18:21]
	v_mfma_f32_16x16x32_bf16 v[14:17], v[166:169], v[198:201], v[14:17]
	v_mfma_f32_16x16x32_bf16 v[10:13], v[174:177], v[198:201], v[10:13]
	v_mfma_f32_16x16x32_bf16 v[6:9], v[166:169], v[206:209], v[6:9]
	v_mfma_f32_16x16x32_bf16 v[2:5], v[174:177], v[206:209], v[2:5]
	s_setprio 0
	s_barrier
	s_add_i32 s12, s12, 2
	s_add_u32 s82, s82, 0x100
	s_addc_u32 s83, s83, 0
	s_add_u32 s79, s79, 0x100
	s_addc_u32 vcc_lo, vcc_lo, 0
	s_cmp_gt_u32 s12, 13
	s_cbranch_scc0 .LBB0_663
	s_ashr_i32 s3, s78, 3
	s_ashr_i32 s79, s78, 31
	s_mul_hi_i32 s37, s3, 0x6000
	s_mulk_i32 s3, 0x6000
	s_add_u32 s12, s88, s3
	s_addc_u32 s13, s89, s37
	s_lshl_b64 s[24:25], s[78:79], 20
	s_add_u32 s24, s16, s24
	s_addc_u32 s25, s17, s25
	s_lshl_b64 s[82:83], s[78:79], 19
	s_add_u32 s82, s61, s82
	s_addc_u32 s83, s62, s83
	v_lshl_or_b32 v154, s80, 8, v221
	s_add_u32 s84, s63, s3
	v_ashrrev_i32_e32 v155, 31, v154
	v_mov_b32_e32 v98, v1
	s_addc_u32 s85, s81, s37
	v_lshlrev_b64 v[158:159], 2, v[154:155]
	v_lshl_add_u64 v[160:161], s[84:85], 0, v[158:159]
	v_lshl_add_u64 v[162:163], s[30:31], 0, v[158:159]
	v_lshl_add_u64 v[156:157], s[12:13], 0, v[158:159]
	v_add_u32_e32 v216, s60, v98
	global_load_dwordx4 v[98:101], v[160:161], off offset:16
	global_load_dwordx4 v[102:105], v[160:161], off
	global_load_dwordx4 v[164:167], v[162:163], off offset:16
	global_load_dwordx4 v[168:171], v[162:163], off
	global_load_dwordx4 v[172:175], v[156:157], off offset:16
	global_load_dwordx4 v[176:179], v[156:157], off
	v_ashrrev_i32_e32 v217, 31, v216
	v_lshl_add_u64 v[214:215], s[24:25], 0, v[158:159]
	v_lshlrev_b64 v[186:187], 1, v[154:155]
	v_lshlrev_b64 v[154:155], 12, v[216:217]
	v_lshl_add_u64 v[198:199], s[82:83], 0, v[186:187]
	s_lshl_b32 s49, s78, 8
	v_add_u32_e32 v218, 0x90, v216
	v_ashrrev_i32_e32 v219, 31, v218
	v_add_u32_e32 v204, 0xa0, v216
	v_ashrrev_i32_e32 v205, 31, v204
	s_waitcnt vmcnt(0)
	v_pk_add_f32 v[178:179], v[178:179], 1.0 op_sel_hi:[1,0]
	v_pk_add_f32 v[176:177], v[176:177], 1.0 op_sel_hi:[1,0]
	v_pk_mul_f32 v[188:189], v[170:171], v[178:179]
	v_pk_add_f32 v[170:171], v[172:173], 1.0 op_sel_hi:[1,0]
	v_pk_mul_f32 v[190:191], v[168:169], v[176:177]
	v_pk_add_f32 v[168:169], v[174:175], 1.0 op_sel_hi:[1,0]
	v_pk_mul_f32 v[194:195], v[164:165], v[170:171]
	v_lshl_add_u64 v[164:165], v[214:215], 0, v[154:155]
	v_pk_mul_f32 v[192:193], v[166:167], v[168:169]
	global_load_dwordx4 v[166:169], v[164:165], off offset:16 nt
	global_load_dwordx4 v[170:173], v[164:165], off nt
	v_add_u32_e32 v154, 16, v216
	v_ashrrev_i32_e32 v155, 31, v154
	v_lshlrev_b64 v[158:159], 12, v[154:155]
	v_lshl_add_u64 v[158:159], v[214:215], 0, v[158:159]
	global_load_dwordx4 v[174:177], v[158:159], off offset:16 nt
	global_load_dwordx4 v[178:181], v[158:159], off nt
	s_waitcnt vmcnt(3)
	v_pk_fma_f32 v[166:167], v[130:131], v[98:99], v[166:167]
	s_waitcnt vmcnt(2)
	v_pk_fma_f32 v[136:137], v[136:137], v[104:105], v[172:173]
	v_pk_fma_f32 v[134:135], v[134:135], v[102:103], v[170:171]
	v_pk_fma_f32 v[170:171], v[132:133], v[100:101], v[168:169]
	v_lshlrev_b64 v[168:169], 11, v[216:217]
	v_cvt_pk_f16_f32 v133, v170, v171
	v_cvt_pk_f16_f32 v131, v136, v137
	v_cvt_pk_f16_f32 v132, v166, v167
	v_cvt_pk_f16_f32 v130, v134, v135
	v_lshl_add_u64 v[168:169], v[198:199], 0, v[168:169]
	global_store_dwordx4 v[168:169], v[130:133], off
	s_waitcnt vmcnt(1)
	v_pk_fma_f32 v[128:129], v[128:129], v[104:105], v[180:181]
	v_pk_fma_f32 v[126:127], v[126:127], v[102:103], v[178:179]
	v_mul_f32_e32 v130, v135, v135
	v_mul_f32_e32 v131, v137, v137
	v_fmac_f32_e32 v130, v134, v134
	v_fmac_f32_e32 v131, v136, v136
	v_add_f32_e32 v130, v130, v131
	v_mul_f32_e32 v131, v167, v167
	v_mul_f32_e32 v132, v171, v171
	v_fmac_f32_e32 v131, v166, v166
	v_fmac_f32_e32 v132, v170, v170
	v_add_f32_e32 v131, v131, v132
	v_add_f32_e32 v226, v130, v131
	v_pk_mul_f32 v[130:131], v[188:189], v[136:137]
	v_pk_mul_f32 v[132:133], v[190:191], v[134:135]
	v_pk_mul_f32 v[136:137], v[192:193], v[170:171]
	v_cvt_pk_bf16_f32 v132, v132, v133
	v_cvt_pk_bf16_f32 v133, v130, v131
	v_add_u32_e32 v130, s49, v216
	v_pk_mul_f32 v[134:135], v[194:195], v[166:167]
	v_ashrrev_i32_e32 v131, 31, v130
	v_cvt_pk_bf16_f32 v134, v134, v135
	v_cvt_pk_bf16_f32 v135, v136, v137
	v_lshlrev_b64 v[136:137], 11, v[130:131]
	v_lshl_add_u64 v[136:137], s[0:1], 0, v[136:137]
	v_lshl_add_u64 v[170:171], v[136:137], 0, v[186:187]
	v_pk_fma_f32 v[124:125], v[124:125], v[100:101], v[176:177]
	v_pk_fma_f32 v[122:123], v[122:123], v[98:99], v[174:175]
	v_lshlrev_b64 v[136:137], 11, v[154:155]
	global_store_dwordx4 v[170:171], v[132:135], off
	v_lshl_add_u64 v[172:173], v[198:199], 0, v[136:137]
	v_pk_mul_f32 v[136:137], v[192:193], v[124:125]
	v_cvt_pk_f16_f32 v135, v124, v125
	v_cvt_pk_f16_f32 v133, v128, v129
	v_cvt_pk_f16_f32 v134, v122, v123
	v_cvt_pk_f16_f32 v132, v126, v127
	global_store_dwordx4 v[172:173], v[132:135], off
	v_pk_mul_f32 v[166:167], v[194:195], v[122:123]
	s_nop 0
	v_pk_mul_f32 v[134:135], v[188:189], v[128:129]
	v_pk_mul_f32 v[132:133], v[190:191], v[126:127]
	s_nop 0
	v_cvt_pk_bf16_f32 v132, v132, v133
	v_cvt_pk_bf16_f32 v133, v134, v135
	v_cvt_pk_bf16_f32 v134, v166, v167
	v_cvt_pk_bf16_f32 v135, v136, v137
	v_add_u32_e32 v136, s49, v154
	v_ashrrev_i32_e32 v137, 31, v136
	v_lshlrev_b64 v[136:137], 11, v[136:137]
	v_lshl_add_u64 v[136:137], s[0:1], 0, v[136:137]
	v_lshl_add_u64 v[178:179], v[136:137], 0, v[186:187]
	v_add_u32_e32 v136, 32, v216
	v_ashrrev_i32_e32 v137, 31, v136
	global_store_dwordx4 v[178:179], v[132:135], off
	v_add_u32_e32 v154, 48, v216
	v_ashrrev_i32_e32 v155, 31, v154
	v_lshlrev_b64 v[132:133], 12, v[136:137]
	v_lshl_add_u64 v[180:181], v[214:215], 0, v[132:133]
	global_load_dwordx4 v[132:135], v[180:181], off offset:16 nt
	global_load_dwordx4 v[174:177], v[180:181], off nt
	v_lshlrev_b64 v[166:167], 12, v[154:155]
	v_lshl_add_u64 v[182:183], v[214:215], 0, v[166:167]
	global_load_dwordx4 v[200:203], v[182:183], off offset:16 nt
	global_load_dwordx4 v[206:209], v[182:183], off nt
	v_lshlrev_b64 v[166:167], 11, v[136:137]
	v_add_u32_e32 v136, s49, v136
	v_ashrrev_i32_e32 v137, 31, v136
	v_lshlrev_b64 v[136:137], 11, v[136:137]
	v_lshl_add_u64 v[136:137], s[0:1], 0, v[136:137]
	v_lshl_add_u64 v[184:185], v[136:137], 0, v[186:187]
	v_lshlrev_b64 v[136:137], 11, v[154:155]
	s_waitcnt vmcnt(3)
	v_pk_fma_f32 v[116:117], v[116:117], v[100:101], v[134:135]
	s_waitcnt vmcnt(2)
	v_pk_fma_f32 v[120:121], v[120:121], v[104:105], v[176:177]
	v_pk_fma_f32 v[118:119], v[118:119], v[102:103], v[174:175]
	v_pk_fma_f32 v[114:115], v[114:115], v[98:99], v[132:133]
	v_cvt_pk_f16_f32 v135, v116, v117
	v_cvt_pk_f16_f32 v133, v120, v121
	v_cvt_pk_f16_f32 v134, v114, v115
	v_cvt_pk_f16_f32 v132, v118, v119
	v_lshl_add_u64 v[176:177], v[198:199], 0, v[166:167]
	global_store_dwordx4 v[176:177], v[132:135], off
	v_pk_mul_f32 v[166:167], v[192:193], v[116:117]
	v_pk_mul_f32 v[174:175], v[194:195], v[114:115]
	v_pk_mul_f32 v[134:135], v[188:189], v[120:121]
	v_pk_mul_f32 v[132:133], v[190:191], v[118:119]
	s_waitcnt vmcnt(1)
	v_pk_fma_f32 v[112:113], v[112:113], v[104:105], v[208:209]
	v_cvt_pk_bf16_f32 v132, v132, v133
	v_cvt_pk_bf16_f32 v133, v134, v135
	v_cvt_pk_bf16_f32 v134, v174, v175
	v_cvt_pk_bf16_f32 v135, v166, v167
	v_pk_fma_f32 v[110:111], v[110:111], v[102:103], v[206:207]
	v_pk_fma_f32 v[108:109], v[108:109], v[100:101], v[202:203]
	v_pk_fma_f32 v[106:107], v[106:107], v[98:99], v[200:201]
	global_store_dwordx4 v[184:185], v[132:135], off
	v_lshl_add_u64 v[174:175], v[198:199], 0, v[136:137]
	v_pk_mul_f32 v[136:137], v[192:193], v[108:109]
	v_cvt_pk_f16_f32 v135, v108, v109
	v_cvt_pk_f16_f32 v133, v112, v113
	v_cvt_pk_f16_f32 v134, v106, v107
	v_cvt_pk_f16_f32 v132, v110, v111
	global_store_dwordx4 v[174:175], v[132:135], off
	v_pk_mul_f32 v[166:167], v[194:195], v[106:107]
	v_add_u32_e32 v206, 0x80, v216
	v_pk_mul_f32 v[134:135], v[188:189], v[112:113]
	v_pk_mul_f32 v[132:133], v[190:191], v[110:111]
	v_ashrrev_i32_e32 v207, 31, v206
	v_cvt_pk_bf16_f32 v132, v132, v133
	v_cvt_pk_bf16_f32 v133, v134, v135
	v_cvt_pk_bf16_f32 v134, v166, v167
	v_cvt_pk_bf16_f32 v135, v136, v137
	v_add_u32_e32 v136, s49, v154
	v_ashrrev_i32_e32 v137, 31, v136
	v_lshlrev_b64 v[136:137], 11, v[136:137]
	v_lshl_add_u64 v[136:137], s[0:1], 0, v[136:137]
	v_lshl_add_u64 v[166:167], v[136:137], 0, v[186:187]
	global_store_dwordx4 v[166:167], v[132:135], off
	v_lshlrev_b64 v[136:137], 12, v[218:219]
	v_lshl_add_u64 v[210:211], v[214:215], 0, v[136:137]
	v_lshlrev_b64 v[132:133], 12, v[206:207]
	v_lshl_add_u64 v[196:197], v[214:215], 0, v[132:133]
	global_load_dwordx4 v[200:203], v[196:197], off offset:16 nt
	global_load_dwordx4 v[132:135], v[196:197], off nt
	global_load_dwordx4 v[228:231], v[210:211], off offset:16 nt
	global_load_dwordx4 v[232:235], v[210:211], off nt
	s_waitcnt vmcnt(2)
	v_pk_fma_f32 v[136:137], v[96:97], v[104:105], v[134:135]
	v_pk_fma_f32 v[154:155], v[94:95], v[102:103], v[132:133]
	v_pk_fma_f32 v[132:133], v[92:93], v[100:101], v[202:203]
	v_pk_fma_f32 v[134:135], v[90:91], v[98:99], v[200:201]
	v_lshlrev_b64 v[94:95], 11, v[206:207]
	v_cvt_pk_f16_f32 v93, v132, v133
	v_cvt_pk_f16_f32 v91, v136, v137
	v_cvt_pk_f16_f32 v92, v134, v135
	v_cvt_pk_f16_f32 v90, v154, v155
	v_lshl_add_u64 v[208:209], v[198:199], 0, v[94:95]
	global_store_dwordx4 v[208:209], v[90:93], off
	v_pk_mul_f32 v[94:95], v[192:193], v[132:133]
	v_pk_mul_f32 v[96:97], v[194:195], v[134:135]
	v_pk_mul_f32 v[92:93], v[188:189], v[136:137]
	v_pk_mul_f32 v[90:91], v[190:191], v[154:155]
	s_nop 0
	v_cvt_pk_bf16_f32 v90, v90, v91
	v_cvt_pk_bf16_f32 v91, v92, v93
	v_cvt_pk_bf16_f32 v92, v96, v97
	v_cvt_pk_bf16_f32 v93, v94, v95
	v_add_u32_e32 v94, s49, v206
	v_ashrrev_i32_e32 v95, 31, v94
	v_lshlrev_b64 v[94:95], 11, v[94:95]
	v_lshl_add_u64 v[94:95], s[0:1], 0, v[94:95]
	v_lshl_add_u64 v[212:213], v[94:95], 0, v[186:187]
	global_store_dwordx4 v[212:213], v[90:93], off
	s_waitcnt vmcnt(2)
	v_pk_fma_f32 v[94:95], v[88:89], v[104:105], v[234:235]
	v_pk_fma_f32 v[96:97], v[86:87], v[102:103], v[232:233]
	v_pk_fma_f32 v[90:91], v[84:85], v[100:101], v[230:231]
	v_pk_fma_f32 v[92:93], v[82:83], v[98:99], v[228:229]
	v_lshlrev_b64 v[86:87], 11, v[218:219]
	v_cvt_pk_f16_f32 v85, v90, v91
	v_cvt_pk_f16_f32 v83, v94, v95
	v_cvt_pk_f16_f32 v84, v92, v93
	v_cvt_pk_f16_f32 v82, v96, v97
	v_lshl_add_u64 v[206:207], v[198:199], 0, v[86:87]
	global_store_dwordx4 v[206:207], v[82:85], off
	v_pk_mul_f32 v[86:87], v[192:193], v[90:91]
	v_pk_mul_f32 v[88:89], v[194:195], v[92:93]
	v_pk_mul_f32 v[84:85], v[188:189], v[94:95]
	v_pk_mul_f32 v[82:83], v[190:191], v[96:97]
	s_nop 0
	v_cvt_pk_bf16_f32 v82, v82, v83
	v_cvt_pk_bf16_f32 v83, v84, v85
	v_cvt_pk_bf16_f32 v84, v88, v89
	v_cvt_pk_bf16_f32 v85, v86, v87
	v_add_u32_e32 v86, s49, v218
	v_ashrrev_i32_e32 v87, 31, v86
	v_lshlrev_b64 v[86:87], 11, v[86:87]
	v_lshl_add_u64 v[86:87], s[0:1], 0, v[86:87]
	v_lshl_add_u64 v[202:203], v[86:87], 0, v[186:187]
	global_store_dwordx4 v[202:203], v[82:85], off
	v_add_u32_e32 v218, 0xb0, v216
	v_ashrrev_i32_e32 v219, 31, v218
	v_lshlrev_b64 v[82:83], 12, v[204:205]
	v_lshl_add_u64 v[200:201], v[214:215], 0, v[82:83]
	global_load_dwordx4 v[82:85], v[200:201], off offset:16 nt
	global_load_dwordx4 v[86:89], v[200:201], off nt
	v_lshlrev_b64 v[216:217], 12, v[218:219]
	v_lshl_add_u64 v[214:215], v[214:215], 0, v[216:217]
	global_load_dwordx4 v[228:231], v[214:215], off offset:16 nt
	global_load_dwordx4 v[232:235], v[214:215], off nt
	s_waitcnt vmcnt(3)
	v_pk_fma_f32 v[76:77], v[76:77], v[100:101], v[84:85]
	s_waitcnt vmcnt(2)
	v_pk_fma_f32 v[80:81], v[80:81], v[104:105], v[88:89]
	v_pk_fma_f32 v[78:79], v[78:79], v[102:103], v[86:87]
	v_pk_fma_f32 v[74:75], v[74:75], v[98:99], v[82:83]
	v_lshlrev_b64 v[86:87], 11, v[204:205]
	v_cvt_pk_f16_f32 v85, v76, v77
	v_cvt_pk_f16_f32 v83, v80, v81
	v_cvt_pk_f16_f32 v84, v74, v75
	v_cvt_pk_f16_f32 v82, v78, v79
	v_lshl_add_u64 v[216:217], v[198:199], 0, v[86:87]
	global_store_dwordx4 v[216:217], v[82:85], off
	v_pk_mul_f32 v[86:87], v[192:193], v[76:77]
	v_pk_mul_f32 v[88:89], v[194:195], v[74:75]
	v_pk_mul_f32 v[84:85], v[188:189], v[80:81]
	v_pk_mul_f32 v[82:83], v[190:191], v[78:79]
	s_nop 0
	v_cvt_pk_bf16_f32 v82, v82, v83
	v_cvt_pk_bf16_f32 v83, v84, v85
	v_cvt_pk_bf16_f32 v84, v88, v89
	v_cvt_pk_bf16_f32 v85, v86, v87
	v_add_u32_e32 v86, s49, v204
	v_ashrrev_i32_e32 v87, 31, v86
	v_lshlrev_b64 v[86:87], 11, v[86:87]
	v_lshl_add_u64 v[86:87], s[0:1], 0, v[86:87]
	v_lshl_add_u64 v[204:205], v[86:87], 0, v[186:187]
	global_store_dwordx4 v[204:205], v[82:85], off
	s_waitcnt vmcnt(2)
	v_pk_fma_f32 v[86:87], v[72:73], v[104:105], v[234:235]
	v_pk_fma_f32 v[88:89], v[70:71], v[102:103], v[232:233]
	v_pk_fma_f32 v[82:83], v[68:69], v[100:101], v[230:231]
	v_pk_fma_f32 v[84:85], v[66:67], v[98:99], v[228:229]
	v_lshlrev_b64 v[70:71], 11, v[218:219]
	v_cvt_pk_f16_f32 v69, v82, v83
	v_cvt_pk_f16_f32 v67, v86, v87
	v_cvt_pk_f16_f32 v68, v84, v85
	v_cvt_pk_f16_f32 v66, v88, v89
	v_lshl_add_u64 v[98:99], v[198:199], 0, v[70:71]
	global_store_dwordx4 v[98:99], v[66:69], off
	v_pk_mul_f32 v[70:71], v[192:193], v[82:83]
	v_pk_mul_f32 v[72:73], v[194:195], v[84:85]
	v_pk_mul_f32 v[68:69], v[188:189], v[86:87]
	v_pk_mul_f32 v[66:67], v[190:191], v[88:89]
	s_nop 0
	v_cvt_pk_bf16_f32 v66, v66, v67
	v_cvt_pk_bf16_f32 v67, v68, v69
	v_cvt_pk_bf16_f32 v68, v72, v73
	v_cvt_pk_bf16_f32 v69, v70, v71
	v_add_u32_e32 v70, s49, v218
	v_ashrrev_i32_e32 v71, 31, v70
	v_lshlrev_b64 v[70:71], 11, v[70:71]
	v_lshl_add_u64 v[70:71], s[0:1], 0, v[70:71]
	v_lshl_add_u64 v[100:101], v[70:71], 0, v[186:187]
	global_store_dwordx4 v[100:101], v[66:69], off
	global_load_dwordx4 v[66:69], v[160:161], off offset:528
	s_nop 0
	global_load_dwordx4 v[70:73], v[160:161], off offset:512
	global_load_dwordx4 v[186:189], v[162:163], off offset:528
	s_nop 0
	global_load_dwordx4 v[160:163], v[162:163], off offset:512
	s_nop 0
	global_load_dwordx4 v[190:193], v[156:157], off offset:528
	global_load_dwordx4 v[102:105], v[156:157], off offset:512
	s_waitcnt vmcnt(0)
	v_pk_add_f32 v[104:105], v[104:105], 1.0 op_sel_hi:[1,0]
	v_pk_add_f32 v[156:157], v[102:103], 1.0 op_sel_hi:[1,0]
	v_pk_mul_f32 v[102:103], v[162:163], v[104:105]
	v_pk_mul_f32 v[104:105], v[160:161], v[156:157]
	v_pk_add_f32 v[156:157], v[192:193], 1.0 op_sel_hi:[1,0]
	v_pk_add_f32 v[160:161], v[190:191], 1.0 op_sel_hi:[1,0]
	v_pk_mul_f32 v[156:157], v[188:189], v[156:157]
	v_pk_mul_f32 v[160:161], v[186:187], v[160:161]
	global_load_dwordx4 v[186:189], v[164:165], off offset:528 nt
	s_nop 0
	global_load_dwordx4 v[162:165], v[164:165], off offset:512 nt
	s_nop 0
	global_load_dwordx4 v[190:193], v[158:159], off offset:528 nt
	global_load_dwordx4 v[228:231], v[158:159], off offset:512 nt
	s_waitcnt vmcnt(3)
	v_pk_fma_f32 v[158:159], v[60:61], v[68:69], v[188:189]
	s_waitcnt vmcnt(2)
	v_pk_fma_f32 v[64:65], v[64:65], v[72:73], v[164:165]
	v_pk_fma_f32 v[62:63], v[62:63], v[70:71], v[162:163]
	v_pk_fma_f32 v[162:163], v[58:59], v[66:67], v[186:187]
	v_cvt_pk_f16_f32 v61, v158, v159
	v_cvt_pk_f16_f32 v59, v64, v65
	v_cvt_pk_f16_f32 v60, v162, v163
	v_cvt_pk_f16_f32 v58, v62, v63
	global_store_dwordx4 v[168:169], v[58:61], off offset:256
	s_waitcnt vmcnt(1)
	v_pk_fma_f32 v[56:57], v[56:57], v[72:73], v[230:231]
	v_pk_fma_f32 v[54:55], v[54:55], v[70:71], v[228:229]
	v_mul_f32_e32 v58, v63, v63
	v_mul_f32_e32 v59, v65, v65
	v_fmac_f32_e32 v58, v62, v62
	v_fmac_f32_e32 v59, v64, v64
	v_add_f32_e32 v58, v58, v59
	v_mul_f32_e32 v59, v163, v163
	v_mul_f32_e32 v60, v159, v159
	v_fmac_f32_e32 v59, v162, v162
	v_fmac_f32_e32 v60, v158, v158
	v_add_f32_e32 v59, v59, v60
	v_pk_mul_f32 v[60:61], v[104:105], v[62:63]
	v_pk_mul_f32 v[62:63], v[160:161], v[162:163]
	v_pk_mul_f32 v[64:65], v[102:103], v[64:65]
	v_pk_mul_f32 v[158:159], v[156:157], v[158:159]
	v_cvt_pk_bf16_f32 v60, v60, v61
	v_cvt_pk_bf16_f32 v61, v64, v65
	v_cvt_pk_bf16_f32 v62, v62, v63
	v_pk_fma_f32 v[52:53], v[52:53], v[68:69], v[192:193]
	v_cvt_pk_bf16_f32 v63, v158, v159
	v_pk_fma_f32 v[50:51], v[50:51], v[66:67], v[190:191]
	global_store_dwordx4 v[170:171], v[60:63], off offset:256
	v_pk_mul_f32 v[64:65], v[156:157], v[52:53]
	v_pk_mul_f32 v[158:159], v[160:161], v[50:51]
	v_cvt_pk_f16_f32 v63, v52, v53
	v_cvt_pk_f16_f32 v61, v56, v57
	v_cvt_pk_f16_f32 v62, v50, v51
	v_cvt_pk_f16_f32 v60, v54, v55
	global_store_dwordx4 v[172:173], v[60:63], off offset:256
	v_add_f32_e32 v58, v58, v59
	v_xor_b32_e32 v59, 16, v225
	v_pk_mul_f32 v[62:63], v[102:103], v[56:57]
	v_pk_mul_f32 v[60:61], v[104:105], v[54:55]
	v_add_f32_e32 v58, v226, v58
	v_cvt_pk_bf16_f32 v60, v60, v61
	v_cvt_pk_bf16_f32 v61, v62, v63
	v_cvt_pk_bf16_f32 v62, v158, v159
	v_cvt_pk_bf16_f32 v63, v64, v65
	global_store_dwordx4 v[178:179], v[60:63], off offset:256
	global_load_dwordx4 v[60:63], v[180:181], off offset:528 nt
	s_nop 0
	global_load_dwordx4 v[162:165], v[180:181], off offset:512 nt
	global_load_dwordx4 v[168:171], v[182:183], off offset:528 nt
	s_nop 0
	global_load_dwordx4 v[178:181], v[182:183], off offset:512 nt
	s_waitcnt vmcnt(3)
	v_pk_fma_f32 v[44:45], v[44:45], v[68:69], v[62:63]
	s_waitcnt vmcnt(2)
	v_pk_fma_f32 v[48:49], v[48:49], v[72:73], v[164:165]
	v_pk_fma_f32 v[46:47], v[46:47], v[70:71], v[162:163]
	v_pk_fma_f32 v[42:43], v[42:43], v[66:67], v[60:61]
	v_cvt_pk_f16_f32 v63, v44, v45
	v_cvt_pk_f16_f32 v61, v48, v49
	v_cvt_pk_f16_f32 v62, v42, v43
	v_cvt_pk_f16_f32 v60, v46, v47
	global_store_dwordx4 v[176:177], v[60:63], off offset:256
	v_pk_mul_f32 v[64:65], v[156:157], v[44:45]
	v_pk_mul_f32 v[158:159], v[160:161], v[42:43]
	v_pk_mul_f32 v[62:63], v[102:103], v[48:49]
	v_pk_mul_f32 v[60:61], v[104:105], v[46:47]
	s_waitcnt vmcnt(1)
	v_pk_fma_f32 v[40:41], v[40:41], v[72:73], v[180:181]
	v_cvt_pk_bf16_f32 v60, v60, v61
	v_cvt_pk_bf16_f32 v61, v62, v63
	v_cvt_pk_bf16_f32 v62, v158, v159
	v_cvt_pk_bf16_f32 v63, v64, v65
	v_pk_fma_f32 v[38:39], v[38:39], v[70:71], v[178:179]
	v_pk_fma_f32 v[36:37], v[36:37], v[68:69], v[170:171]
	v_pk_fma_f32 v[34:35], v[34:35], v[66:67], v[168:169]
	global_store_dwordx4 v[184:185], v[60:63], off offset:256
	v_pk_mul_f32 v[64:65], v[156:157], v[36:37]
	v_pk_mul_f32 v[158:159], v[160:161], v[34:35]
	v_cvt_pk_f16_f32 v63, v36, v37
	v_cvt_pk_f16_f32 v61, v40, v41
	v_cvt_pk_f16_f32 v62, v34, v35
	v_cvt_pk_f16_f32 v60, v38, v39
	global_store_dwordx4 v[174:175], v[60:63], off offset:256
	s_nop 1
	v_pk_mul_f32 v[62:63], v[102:103], v[40:41]
	v_pk_mul_f32 v[60:61], v[104:105], v[38:39]
	s_nop 0
	v_cvt_pk_bf16_f32 v60, v60, v61
	v_cvt_pk_bf16_f32 v61, v62, v63
	v_cvt_pk_bf16_f32 v62, v158, v159
	v_cvt_pk_bf16_f32 v63, v64, v65
	global_store_dwordx4 v[166:167], v[60:63], off offset:256
	global_load_dwordx4 v[60:63], v[196:197], off offset:528 nt
	s_nop 0
	global_load_dwordx4 v[162:165], v[196:197], off offset:512 nt
	global_load_dwordx4 v[166:169], v[210:211], off offset:528 nt
	global_load_dwordx4 v[170:173], v[210:211], off offset:512 nt
	s_waitcnt vmcnt(3)
	v_pk_fma_f32 v[28:29], v[28:29], v[68:69], v[62:63]
	s_waitcnt vmcnt(2)
	v_pk_fma_f32 v[32:33], v[32:33], v[72:73], v[164:165]
	v_pk_fma_f32 v[30:31], v[30:31], v[70:71], v[162:163]
	v_pk_fma_f32 v[26:27], v[26:27], v[66:67], v[60:61]
	v_cvt_pk_f16_f32 v63, v28, v29
	v_cvt_pk_f16_f32 v61, v32, v33
	v_cvt_pk_f16_f32 v62, v26, v27
	v_cvt_pk_f16_f32 v60, v30, v31
	global_store_dwordx4 v[208:209], v[60:63], off offset:256
	v_pk_mul_f32 v[64:65], v[156:157], v[28:29]
	v_pk_mul_f32 v[158:159], v[160:161], v[26:27]
	v_pk_mul_f32 v[62:63], v[102:103], v[32:33]
	v_pk_mul_f32 v[60:61], v[104:105], v[30:31]
	s_waitcnt vmcnt(1)
	v_pk_fma_f32 v[24:25], v[24:25], v[72:73], v[172:173]
	v_cvt_pk_bf16_f32 v60, v60, v61
	v_cvt_pk_bf16_f32 v61, v62, v63
	v_cvt_pk_bf16_f32 v62, v158, v159
	v_cvt_pk_bf16_f32 v63, v64, v65
	v_pk_fma_f32 v[22:23], v[22:23], v[70:71], v[170:171]
	v_pk_fma_f32 v[20:21], v[20:21], v[68:69], v[168:169]
	v_pk_fma_f32 v[18:19], v[18:19], v[66:67], v[166:167]
	global_store_dwordx4 v[212:213], v[60:63], off offset:256
	v_pk_mul_f32 v[64:65], v[156:157], v[20:21]
	v_pk_mul_f32 v[158:159], v[160:161], v[18:19]
	v_cvt_pk_f16_f32 v63, v20, v21
	v_cvt_pk_f16_f32 v61, v24, v25
	v_cvt_pk_f16_f32 v62, v18, v19
	v_cvt_pk_f16_f32 v60, v22, v23
	global_store_dwordx4 v[206:207], v[60:63], off offset:256
	s_nop 1
	v_pk_mul_f32 v[62:63], v[102:103], v[24:25]
	v_pk_mul_f32 v[60:61], v[104:105], v[22:23]
	s_nop 0
	v_cvt_pk_bf16_f32 v60, v60, v61
	v_cvt_pk_bf16_f32 v61, v62, v63
	v_cvt_pk_bf16_f32 v62, v158, v159
	v_cvt_pk_bf16_f32 v63, v64, v65
	global_store_dwordx4 v[202:203], v[60:63], off offset:256
	global_load_dwordx4 v[60:63], v[200:201], off offset:528 nt
	s_nop 0
	global_load_dwordx4 v[162:165], v[200:201], off offset:512 nt
	global_load_dwordx4 v[166:169], v[214:215], off offset:528 nt
	global_load_dwordx4 v[170:173], v[214:215], off offset:512 nt
	s_waitcnt vmcnt(3)
	v_pk_fma_f32 v[12:13], v[12:13], v[68:69], v[62:63]
	s_waitcnt vmcnt(2)
	v_pk_fma_f32 v[16:17], v[16:17], v[72:73], v[164:165]
	v_pk_fma_f32 v[14:15], v[14:15], v[70:71], v[162:163]
	v_pk_fma_f32 v[10:11], v[10:11], v[66:67], v[60:61]
	v_cvt_pk_f16_f32 v63, v12, v13
	v_cvt_pk_f16_f32 v61, v16, v17
	v_cvt_pk_f16_f32 v62, v10, v11
	v_cvt_pk_f16_f32 v60, v14, v15
	global_store_dwordx4 v[216:217], v[60:63], off offset:256
	v_pk_mul_f32 v[64:65], v[156:157], v[12:13]
	v_pk_mul_f32 v[158:159], v[160:161], v[10:11]
	v_pk_mul_f32 v[62:63], v[102:103], v[16:17]
	v_pk_mul_f32 v[60:61], v[104:105], v[14:15]
	s_waitcnt vmcnt(1)
	v_pk_fma_f32 v[8:9], v[8:9], v[72:73], v[172:173]
	v_cvt_pk_bf16_f32 v60, v60, v61
	v_cvt_pk_bf16_f32 v61, v62, v63
	v_cvt_pk_bf16_f32 v62, v158, v159
	v_cvt_pk_bf16_f32 v63, v64, v65
	v_pk_fma_f32 v[6:7], v[6:7], v[70:71], v[170:171]
	v_pk_fma_f32 v[4:5], v[4:5], v[68:69], v[168:169]
	v_pk_fma_f32 v[2:3], v[2:3], v[66:67], v[166:167]
	global_store_dwordx4 v[204:205], v[60:63], off offset:256
	v_pk_mul_f32 v[64:65], v[156:157], v[4:5]
	v_pk_mul_f32 v[66:67], v[160:161], v[2:3]
	v_cvt_pk_f16_f32 v63, v4, v5
	v_cvt_pk_f16_f32 v61, v8, v9
	v_cvt_pk_f16_f32 v62, v2, v3
	v_cvt_pk_f16_f32 v60, v6, v7
	global_store_dwordx4 v[98:99], v[60:63], off offset:256
	s_nop 1
	v_pk_mul_f32 v[60:61], v[104:105], v[6:7]
	v_pk_mul_f32 v[62:63], v[102:103], v[8:9]
	v_cvt_pk_bf16_f32 v60, v60, v61
	s_nop 0
	v_cvt_pk_bf16_f32 v61, v62, v63
	v_cvt_pk_bf16_f32 v62, v66, v67
	v_cvt_pk_bf16_f32 v63, v64, v65
	global_store_dwordx4 v[100:101], v[60:63], off offset:256
	s_nop 1
	v_and_b32_e32 v60, 64, v225
	v_add_u32_e32 v60, 64, v60
	v_cmp_lt_i32_e32 vcc, v59, v60
	v_xor_b32_e32 v61, 32, v225
	s_nop 0
	v_cndmask_b32_e32 v59, v225, v59, vcc
	v_lshlrev_b32_e32 v59, 2, v59
	v_cmp_lt_i32_e32 vcc, v61, v60
	s_nop 1
	v_cndmask_b32_e32 v60, v225, v61, vcc
	ds_bpermute_b32 v61, v59, v58
	v_lshlrev_b32_e32 v60, 2, v60
	s_waitcnt lgkmcnt(0)
	v_add_f32_e32 v58, v58, v61
	ds_bpermute_b32 v61, v60, v58
	s_and_saveexec_b64 s[78:79], s[6:7]
	s_cbranch_execz .LBB0_666
	v_lshl_add_u64 v[62:63], v[130:131], 2, s[52:53]
	s_waitcnt lgkmcnt(0)
	v_add_f32_e32 v58, v58, v61
	global_atomic_add_f32 v[62:63], v58, off

.LBB0_777:
	ds_read_b128 v[50:53], v182
	ds_read_b128 v[54:57], v182 offset:1024
	ds_read_b128 v[58:61], v182 offset:2048
	ds_read_b128 v[62:65], v182 offset:3072
	ds_read_b128 v[166:169], v183
	ds_read_b128 v[188:191], v183 offset:1024
	ds_read_b128 v[192:195], v183 offset:2048
	ds_read_b128 v[196:199], v183 offset:3072
	s_add_u32 s3, s84, 0xfffc0080
	s_addc_u32 s13, s85, -1
	s_cmp_eq_u32 s12, 12
	s_cselect_b32 s89, s11, s13
	s_cselect_b32 s88, s37, s3
	s_cselect_b32 s87, s75, s93
	s_cselect_b32 s86, s77, s92
	s_nop 0
	s_add_i32 m0, s33, 0xc000
	ds_read_b128 v[200:203], v184
	ds_read_b128 v[204:207], v184 offset:1024
	ds_read_b128 v[208:211], v184 offset:2048
	ds_read_b128 v[212:215], v184 offset:3072
	ds_read_b128 v[216:219], v184 offset:4096
	ds_read_b128 v[220:223], v184 offset:5120
	ds_read_b128 v[224:227], v184 offset:6144
	ds_read_b128 v[228:231], v184 offset:7168
	global_load_lds_dwordx4 v158, s[84:85]
	s_nop 0
	s_add_i32 m0, s33, 0xe000
	s_nop 0
	global_load_lds_dwordx4 v160, s[84:85]
	s_waitcnt vmcnt(8)
	s_waitcnt lgkmcnt(0)
	s_barrier
	s_setprio 1
	s_waitcnt lgkmcnt(0)
	v_mfma_f32_16x16x32_bf16 v[142:145], v[50:53], v[200:203], v[142:145]
	v_mfma_f32_16x16x32_bf16 v[138:141], v[58:61], v[200:203], v[138:141]
	v_mfma_f32_16x16x32_bf16 v[126:129], v[50:53], v[208:211], v[126:129]
	v_mfma_f32_16x16x32_bf16 v[122:125], v[58:61], v[208:211], v[122:125]
	v_mfma_f32_16x16x32_bf16 v[110:113], v[50:53], v[216:219], v[110:113]
	v_mfma_f32_16x16x32_bf16 v[106:109], v[58:61], v[216:219], v[106:109]
	v_mfma_f32_16x16x32_bf16 v[94:97], v[50:53], v[224:227], v[94:97]
	v_mfma_f32_16x16x32_bf16 v[90:93], v[58:61], v[224:227], v[90:93]
	v_mfma_f32_16x16x32_bf16 v[142:145], v[54:57], v[204:207], v[142:145]
	v_mfma_f32_16x16x32_bf16 v[138:141], v[62:65], v[204:207], v[138:141]
	v_mfma_f32_16x16x32_bf16 v[126:129], v[54:57], v[212:215], v[126:129]
	v_mfma_f32_16x16x32_bf16 v[122:125], v[62:65], v[212:215], v[122:125]
	v_mfma_f32_16x16x32_bf16 v[110:113], v[54:57], v[220:223], v[110:113]
	v_mfma_f32_16x16x32_bf16 v[106:109], v[62:65], v[220:223], v[106:109]
	v_mfma_f32_16x16x32_bf16 v[94:97], v[54:57], v[228:231], v[94:97]
	v_mfma_f32_16x16x32_bf16 v[90:93], v[62:65], v[228:231], v[90:93]
	s_setprio 0
	s_setprio 1
	v_mfma_f32_16x16x32_bf16 v[134:137], v[166:169], v[200:203], v[134:137]
	v_mfma_f32_16x16x32_bf16 v[130:133], v[192:195], v[200:203], v[130:133]
	v_mfma_f32_16x16x32_bf16 v[118:121], v[166:169], v[208:211], v[118:121]
	v_mfma_f32_16x16x32_bf16 v[114:117], v[192:195], v[208:211], v[114:117]
	v_mfma_f32_16x16x32_bf16 v[102:105], v[166:169], v[216:219], v[102:105]
	v_mfma_f32_16x16x32_bf16 v[98:101], v[192:195], v[216:219], v[98:101]
	v_mfma_f32_16x16x32_bf16 v[86:89], v[166:169], v[224:227], v[86:89]
	v_mfma_f32_16x16x32_bf16 v[82:85], v[192:195], v[224:227], v[82:85]
	v_mfma_f32_16x16x32_bf16 v[134:137], v[188:191], v[204:207], v[134:137]
	v_mfma_f32_16x16x32_bf16 v[130:133], v[196:199], v[204:207], v[130:133]
	v_mfma_f32_16x16x32_bf16 v[118:121], v[188:191], v[212:215], v[118:121]
	v_mfma_f32_16x16x32_bf16 v[114:117], v[196:199], v[212:215], v[114:117]
	v_mfma_f32_16x16x32_bf16 v[102:105], v[188:191], v[220:223], v[102:105]
	v_mfma_f32_16x16x32_bf16 v[98:101], v[196:199], v[220:223], v[98:101]
	v_mfma_f32_16x16x32_bf16 v[86:89], v[188:191], v[228:231], v[86:89]
	v_mfma_f32_16x16x32_bf16 v[82:85], v[196:199], v[228:231], v[82:85]
	s_setprio 0
	s_barrier
	s_add_i32 s3, s66, s23
	s_nop 0
	s_mov_b32 m0, s3
	ds_read_b128 v[200:203], v184 offset:16384
	ds_read_b128 v[204:207], v184 offset:17408
	ds_read_b128 v[208:211], v184 offset:18432
	ds_read_b128 v[212:215], v184 offset:19456
	ds_read_b128 v[216:219], v184 offset:20480
	ds_read_b128 v[220:223], v184 offset:21504
	ds_read_b128 v[224:227], v184 offset:22528
	ds_read_b128 v[228:231], v184 offset:23552
	global_load_lds_dwordx4 v150, s[86:87]
	s_add_i32 m0, s3, 0x2000
	s_add_u32 s24, s86, 0x40000
	s_nop 0
	s_addc_u32 s25, s87, 0
	s_add_i32 s3, s67, s23
	global_load_lds_dwordx4 v154, s[86:87]
	s_nop 0
	s_mov_b32 m0, s3
	s_nop 0
	global_load_lds_dwordx4 v150, s[24:25]
	s_nop 0
	s_add_i32 m0, s3, 0x2000
	s_nop 0
	global_load_lds_dwordx4 v154, s[24:25]
	s_nop 0
	s_mov_b32 m0, s33
	s_nop 0
	global_load_lds_dwordx4 v148, s[88:89]
	s_mov_b32 m0, s44
	s_nop 0
	global_load_lds_dwordx4 v152, s[88:89]
	s_waitcnt vmcnt(8)
	s_waitcnt lgkmcnt(0)
	s_barrier
	s_setprio 1
	s_waitcnt lgkmcnt(0)
	v_mfma_f32_16x16x32_bf16 v[78:81], v[50:53], v[200:203], v[78:81]
	v_mfma_f32_16x16x32_bf16 v[74:77], v[58:61], v[200:203], v[74:77]
	v_mfma_f32_16x16x32_bf16 v[46:49], v[50:53], v[208:211], v[46:49]
	v_mfma_f32_16x16x32_bf16 v[42:45], v[58:61], v[208:211], v[42:45]
	v_mfma_f32_16x16x32_bf16 v[30:33], v[50:53], v[216:219], v[30:33]
	v_mfma_f32_16x16x32_bf16 v[26:29], v[58:61], v[216:219], v[26:29]
	v_mfma_f32_16x16x32_bf16 v[14:17], v[50:53], v[224:227], v[14:17]
	v_mfma_f32_16x16x32_bf16 v[10:13], v[58:61], v[224:227], v[10:13]
	v_mfma_f32_16x16x32_bf16 v[78:81], v[54:57], v[204:207], v[78:81]
	v_mfma_f32_16x16x32_bf16 v[74:77], v[62:65], v[204:207], v[74:77]
	v_mfma_f32_16x16x32_bf16 v[46:49], v[54:57], v[212:215], v[46:49]
	v_mfma_f32_16x16x32_bf16 v[42:45], v[62:65], v[212:215], v[42:45]
	v_mfma_f32_16x16x32_bf16 v[30:33], v[54:57], v[220:223], v[30:33]
	v_mfma_f32_16x16x32_bf16 v[26:29], v[62:65], v[220:223], v[26:29]
	v_mfma_f32_16x16x32_bf16 v[14:17], v[54:57], v[228:231], v[14:17]
	v_mfma_f32_16x16x32_bf16 v[10:13], v[62:65], v[228:231], v[10:13]
	s_setprio 0
	s_setprio 1
	v_mfma_f32_16x16x32_bf16 v[38:41], v[166:169], v[208:211], v[38:41]
	v_mfma_f32_16x16x32_bf16 v[34:37], v[192:195], v[208:211], v[34:37]
	v_mfma_f32_16x16x32_bf16 v[22:25], v[166:169], v[216:219], v[22:25]
	v_mfma_f32_16x16x32_bf16 v[18:21], v[192:195], v[216:219], v[18:21]
	v_mfma_f32_16x16x32_bf16 v[6:9], v[166:169], v[224:227], v[6:9]
	v_mfma_f32_16x16x32_bf16 v[2:5], v[192:195], v[224:227], v[2:5]
	v_mfma_f32_16x16x32_bf16 v[50:53], v[166:169], v[200:203], v[70:73]
	v_mfma_f32_16x16x32_bf16 v[54:57], v[192:195], v[200:203], v[66:69]
	v_mfma_f32_16x16x32_bf16 v[38:41], v[188:191], v[212:215], v[38:41]
	v_mfma_f32_16x16x32_bf16 v[34:37], v[196:199], v[212:215], v[34:37]
	v_mfma_f32_16x16x32_bf16 v[22:25], v[188:191], v[220:223], v[22:25]
	v_mfma_f32_16x16x32_bf16 v[18:21], v[196:199], v[220:223], v[18:21]
	v_mfma_f32_16x16x32_bf16 v[6:9], v[188:191], v[228:231], v[6:9]
	v_mfma_f32_16x16x32_bf16 v[2:5], v[196:199], v[228:231], v[2:5]
	v_mfma_f32_16x16x32_bf16 v[50:53], v[188:191], v[204:207], v[50:53]
	v_mfma_f32_16x16x32_bf16 v[54:57], v[196:199], v[204:207], v[54:57]
	s_setprio 0
	s_barrier
	s_add_i32 s3, 0, 0x18000
	s_add_i32 s13, 0, 0x1c000
	v_add_u32_e32 v70, s3, v173
	v_add_u32_e32 v187, s13, v173
	ds_read_b128 v[58:61], v70
	ds_read_b128 v[62:65], v70 offset:1024
	ds_read_b128 v[66:69], v70 offset:2048
	ds_read_b128 v[70:73], v70 offset:3072
	ds_read_b128 v[166:169], v187
	ds_read_b128 v[188:191], v187 offset:1024
	ds_read_b128 v[192:195], v187 offset:2048
	ds_read_b128 v[196:199], v187 offset:3072
	s_add_u32 s24, s88, 0x40000
	s_addc_u32 s25, s89, 0
	s_mov_b32 m0, s45
	s_nop 0
	ds_read_b128 v[200:203], v184 offset:32768
	ds_read_b128 v[204:207], v184 offset:33792
	ds_read_b128 v[208:211], v184 offset:34816
	ds_read_b128 v[212:215], v184 offset:35840
	ds_read_b128 v[216:219], v184 offset:36864
	ds_read_b128 v[220:223], v184 offset:37888
	ds_read_b128 v[224:227], v184 offset:38912
	ds_read_b128 v[228:231], v184 offset:39936
	global_load_lds_dwordx4 v148, s[24:25]
	s_nop 0
	s_mov_b32 m0, s48
	s_nop 0
	global_load_lds_dwordx4 v152, s[24:25]
	s_waitcnt vmcnt(8)
	s_waitcnt lgkmcnt(0)
	s_barrier
	s_setprio 1
	s_waitcnt lgkmcnt(0)
	v_mfma_f32_16x16x32_bf16 v[142:145], v[58:61], v[200:203], v[142:145]
	v_mfma_f32_16x16x32_bf16 v[138:141], v[66:69], v[200:203], v[138:141]
	v_mfma_f32_16x16x32_bf16 v[126:129], v[58:61], v[208:211], v[126:129]
	v_mfma_f32_16x16x32_bf16 v[122:125], v[66:69], v[208:211], v[122:125]
	v_mfma_f32_16x16x32_bf16 v[110:113], v[58:61], v[216:219], v[110:113]
	v_mfma_f32_16x16x32_bf16 v[106:109], v[66:69], v[216:219], v[106:109]
	v_mfma_f32_16x16x32_bf16 v[94:97], v[58:61], v[224:227], v[94:97]
	v_mfma_f32_16x16x32_bf16 v[90:93], v[66:69], v[224:227], v[90:93]
	v_mfma_f32_16x16x32_bf16 v[142:145], v[62:65], v[204:207], v[142:145]
	v_mfma_f32_16x16x32_bf16 v[138:141], v[70:73], v[204:207], v[138:141]
	v_mfma_f32_16x16x32_bf16 v[126:129], v[62:65], v[212:215], v[126:129]
	v_mfma_f32_16x16x32_bf16 v[122:125], v[70:73], v[212:215], v[122:125]
	v_mfma_f32_16x16x32_bf16 v[110:113], v[62:65], v[220:223], v[110:113]
	v_mfma_f32_16x16x32_bf16 v[106:109], v[70:73], v[220:223], v[106:109]
	v_mfma_f32_16x16x32_bf16 v[94:97], v[62:65], v[228:231], v[94:97]
	v_mfma_f32_16x16x32_bf16 v[90:93], v[70:73], v[228:231], v[90:93]
	s_setprio 0
	s_setprio 1
	v_mfma_f32_16x16x32_bf16 v[134:137], v[166:169], v[200:203], v[134:137]
	v_mfma_f32_16x16x32_bf16 v[130:133], v[192:195], v[200:203], v[130:133]
	v_mfma_f32_16x16x32_bf16 v[118:121], v[166:169], v[208:211], v[118:121]
	v_mfma_f32_16x16x32_bf16 v[114:117], v[192:195], v[208:211], v[114:117]
	v_mfma_f32_16x16x32_bf16 v[102:105], v[166:169], v[216:219], v[102:105]
	v_mfma_f32_16x16x32_bf16 v[98:101], v[192:195], v[216:219], v[98:101]
	v_mfma_f32_16x16x32_bf16 v[86:89], v[166:169], v[224:227], v[86:89]
	v_mfma_f32_16x16x32_bf16 v[82:85], v[192:195], v[224:227], v[82:85]
	v_mfma_f32_16x16x32_bf16 v[134:137], v[188:191], v[204:207], v[134:137]
	v_mfma_f32_16x16x32_bf16 v[130:133], v[196:199], v[204:207], v[130:133]
	v_mfma_f32_16x16x32_bf16 v[118:121], v[188:191], v[212:215], v[118:121]
	v_mfma_f32_16x16x32_bf16 v[114:117], v[196:199], v[212:215], v[114:117]
	v_mfma_f32_16x16x32_bf16 v[102:105], v[188:191], v[220:223], v[102:105]
	v_mfma_f32_16x16x32_bf16 v[98:101], v[196:199], v[220:223], v[98:101]
	v_mfma_f32_16x16x32_bf16 v[86:89], v[188:191], v[228:231], v[86:89]
	v_mfma_f32_16x16x32_bf16 v[82:85], v[196:199], v[228:231], v[82:85]
	s_setprio 0
	s_barrier
	s_add_i32 s3, s3, s23
	s_nop 0
	s_mov_b32 m0, s3
	ds_read_b128 v[200:203], v184 offset:49152
	ds_read_b128 v[204:207], v184 offset:50176
	ds_read_b128 v[208:211], v184 offset:51200
	ds_read_b128 v[212:215], v184 offset:52224
	ds_read_b128 v[216:219], v184 offset:53248
	ds_read_b128 v[220:223], v184 offset:54272
	ds_read_b128 v[224:227], v184 offset:55296
	ds_read_b128 v[228:231], v184 offset:56320
	global_load_lds_dwordx4 v251, s[86:87]
	s_add_i32 m0, s3, 0x2000
	s_add_u32 s24, s86, 0x40080
	s_nop 0
	s_addc_u32 s25, s87, 0
	s_add_i32 s3, s13, s23
	global_load_lds_dwordx4 v252, s[86:87]
	s_nop 0
	s_mov_b32 m0, s3
	s_nop 0
	global_load_lds_dwordx4 v150, s[24:25]
	s_nop 0
	s_add_i32 m0, s3, 0x2000
	s_nop 0
	global_load_lds_dwordx4 v154, s[24:25]
	s_nop 0
	s_mov_b32 m0, s60
	s_nop 0
	global_load_lds_dwordx4 v253, s[88:89]
	s_nop 0
	s_mov_b32 m0, s61
	s_nop 0
	global_load_lds_dwordx4 v254, s[88:89]
	s_waitcnt vmcnt(8)
	s_waitcnt lgkmcnt(0)
	s_barrier
	s_setprio 1
	s_waitcnt lgkmcnt(0)
	v_mfma_f32_16x16x32_bf16 v[78:81], v[58:61], v[200:203], v[78:81]
	v_mfma_f32_16x16x32_bf16 v[74:77], v[66:69], v[200:203], v[74:77]
	v_mfma_f32_16x16x32_bf16 v[46:49], v[58:61], v[208:211], v[46:49]
	v_mfma_f32_16x16x32_bf16 v[42:45], v[66:69], v[208:211], v[42:45]
	v_mfma_f32_16x16x32_bf16 v[30:33], v[58:61], v[216:219], v[30:33]
	v_mfma_f32_16x16x32_bf16 v[26:29], v[66:69], v[216:219], v[26:29]
	v_mfma_f32_16x16x32_bf16 v[14:17], v[58:61], v[224:227], v[14:17]
	v_mfma_f32_16x16x32_bf16 v[10:13], v[66:69], v[224:227], v[10:13]
	v_mfma_f32_16x16x32_bf16 v[78:81], v[62:65], v[204:207], v[78:81]
	v_mfma_f32_16x16x32_bf16 v[74:77], v[70:73], v[204:207], v[74:77]
	v_mfma_f32_16x16x32_bf16 v[46:49], v[62:65], v[212:215], v[46:49]
	v_mfma_f32_16x16x32_bf16 v[42:45], v[70:73], v[212:215], v[42:45]
	v_mfma_f32_16x16x32_bf16 v[30:33], v[62:65], v[220:223], v[30:33]
	v_mfma_f32_16x16x32_bf16 v[26:29], v[70:73], v[220:223], v[26:29]
	v_mfma_f32_16x16x32_bf16 v[14:17], v[62:65], v[228:231], v[14:17]
	v_mfma_f32_16x16x32_bf16 v[10:13], v[70:73], v[228:231], v[10:13]
	s_setprio 0
	s_setprio 1
	v_mfma_f32_16x16x32_bf16 v[50:53], v[166:169], v[200:203], v[50:53]
	v_mfma_f32_16x16x32_bf16 v[70:73], v[188:191], v[204:207], v[50:53]
	v_mfma_f32_16x16x32_bf16 v[50:53], v[192:195], v[200:203], v[54:57]
	v_mfma_f32_16x16x32_bf16 v[38:41], v[166:169], v[208:211], v[38:41]
	v_mfma_f32_16x16x32_bf16 v[34:37], v[192:195], v[208:211], v[34:37]
	v_mfma_f32_16x16x32_bf16 v[22:25], v[166:169], v[216:219], v[22:25]
	v_mfma_f32_16x16x32_bf16 v[18:21], v[192:195], v[216:219], v[18:21]
	v_mfma_f32_16x16x32_bf16 v[6:9], v[166:169], v[224:227], v[6:9]
	v_mfma_f32_16x16x32_bf16 v[2:5], v[192:195], v[224:227], v[2:5]
	v_mfma_f32_16x16x32_bf16 v[66:69], v[196:199], v[204:207], v[50:53]
	v_mfma_f32_16x16x32_bf16 v[38:41], v[188:191], v[212:215], v[38:41]
	v_mfma_f32_16x16x32_bf16 v[34:37], v[196:199], v[212:215], v[34:37]
	v_mfma_f32_16x16x32_bf16 v[22:25], v[188:191], v[220:223], v[22:25]
	v_mfma_f32_16x16x32_bf16 v[18:21], v[196:199], v[220:223], v[18:21]
	v_mfma_f32_16x16x32_bf16 v[6:9], v[188:191], v[228:231], v[6:9]
	v_mfma_f32_16x16x32_bf16 v[2:5], v[196:199], v[228:231], v[2:5]
	s_setprio 0
	s_barrier
	s_add_i32 s12, s12, 2
	s_add_u32 s84, s84, 0x100
	s_addc_u32 s85, s85, 0
	s_add_u32 s92, s92, 0x100
	s_addc_u32 s93, s93, 0
	s_cmp_gt_u32 s12, 13
	s_cbranch_scc0 .LBB0_777
	s_and_b64 vcc, exec, s[70:71]
	s_cbranch_vccz .LBB0_780
	s_barrier

.LBB0_818:
	ds_read_b128 v[152:155], v148
	ds_read_b128 v[156:159], v148 offset:1024
	ds_read_b128 v[160:163], v148 offset:2048
	ds_read_b128 v[164:167], v148 offset:3072
	ds_read_b128 v[168:171], v149
	ds_read_b128 v[172:175], v149 offset:1024
	ds_read_b128 v[176:179], v149 offset:2048
	ds_read_b128 v[180:183], v149 offset:3072
	s_add_i32 s13, s12, 2
	s_add_u32 s70, s68, 0x100
	s_addc_u32 s71, s69, 0
	s_cmp_eq_u32 s80, s12
	s_cselect_b32 s75, s7, s71
	s_cselect_b32 s74, s6, s70
	s_cselect_b32 s73, s53, s82
	s_cselect_b32 s72, s52, s81
	v_lshl_add_u64 v[216:217], s[68:69], 0, v[140:141]
	s_add_i32 m0, s36, 0xc000
	ds_read_b128 v[184:187], v150
	ds_read_b128 v[188:191], v150 offset:1024
	ds_read_b128 v[192:195], v150 offset:2048
	ds_read_b128 v[196:199], v150 offset:3072
	ds_read_b128 v[200:203], v150 offset:4096
	ds_read_b128 v[204:207], v150 offset:5120
	ds_read_b128 v[208:211], v150 offset:6144
	ds_read_b128 v[212:215], v150 offset:7168
	global_load_lds_dwordx4 v[216:217], off
	v_lshl_add_u64 v[216:217], s[68:69], 0, v[142:143]
	s_add_i32 m0, s36, 0xe000
	s_nop 0
	global_load_lds_dwordx4 v[216:217], off
	s_waitcnt vmcnt(8)
	s_waitcnt lgkmcnt(0)
	s_barrier
	s_setprio 1
	s_waitcnt lgkmcnt(0)
	v_mfma_f32_16x16x32_bf16 v[126:129], v[152:155], v[184:187], v[126:129]
	v_mfma_f32_16x16x32_bf16 v[122:125], v[160:163], v[184:187], v[122:125]
	v_mfma_f32_16x16x32_bf16 v[118:121], v[152:155], v[192:195], v[118:121]
	v_mfma_f32_16x16x32_bf16 v[114:117], v[160:163], v[192:195], v[114:117]
	v_mfma_f32_16x16x32_bf16 v[110:113], v[152:155], v[200:203], v[110:113]
	v_mfma_f32_16x16x32_bf16 v[102:105], v[160:163], v[200:203], v[102:105]
	v_mfma_f32_16x16x32_bf16 v[94:97], v[152:155], v[208:211], v[94:97]
	v_mfma_f32_16x16x32_bf16 v[86:89], v[160:163], v[208:211], v[86:89]
	v_mfma_f32_16x16x32_bf16 v[126:129], v[156:159], v[188:191], v[126:129]
	v_mfma_f32_16x16x32_bf16 v[122:125], v[164:167], v[188:191], v[122:125]
	v_mfma_f32_16x16x32_bf16 v[118:121], v[156:159], v[196:199], v[118:121]
	v_mfma_f32_16x16x32_bf16 v[114:117], v[164:167], v[196:199], v[114:117]
	v_mfma_f32_16x16x32_bf16 v[110:113], v[156:159], v[204:207], v[110:113]
	v_mfma_f32_16x16x32_bf16 v[102:105], v[164:167], v[204:207], v[102:105]
	v_mfma_f32_16x16x32_bf16 v[94:97], v[156:159], v[212:215], v[94:97]
	v_mfma_f32_16x16x32_bf16 v[86:89], v[164:167], v[212:215], v[86:89]
	s_setprio 0
	s_setprio 1
	v_mfma_f32_16x16x32_bf16 v[106:109], v[168:171], v[184:187], v[106:109]
	v_mfma_f32_16x16x32_bf16 v[98:101], v[176:179], v[184:187], v[98:101]
	v_mfma_f32_16x16x32_bf16 v[90:93], v[168:171], v[192:195], v[90:93]
	v_mfma_f32_16x16x32_bf16 v[82:85], v[176:179], v[192:195], v[82:85]
	v_mfma_f32_16x16x32_bf16 v[78:81], v[168:171], v[200:203], v[78:81]
	v_mfma_f32_16x16x32_bf16 v[74:77], v[176:179], v[200:203], v[74:77]
	v_mfma_f32_16x16x32_bf16 v[70:73], v[168:171], v[208:211], v[70:73]
	v_mfma_f32_16x16x32_bf16 v[66:69], v[176:179], v[208:211], v[66:69]
	v_mfma_f32_16x16x32_bf16 v[106:109], v[172:175], v[188:191], v[106:109]
	v_mfma_f32_16x16x32_bf16 v[98:101], v[180:183], v[188:191], v[98:101]
	v_mfma_f32_16x16x32_bf16 v[90:93], v[172:175], v[196:199], v[90:93]
	v_mfma_f32_16x16x32_bf16 v[82:85], v[180:183], v[196:199], v[82:85]
	v_mfma_f32_16x16x32_bf16 v[78:81], v[172:175], v[204:207], v[78:81]
	v_mfma_f32_16x16x32_bf16 v[74:77], v[180:183], v[204:207], v[74:77]
	v_mfma_f32_16x16x32_bf16 v[70:73], v[172:175], v[212:215], v[70:73]
	v_mfma_f32_16x16x32_bf16 v[66:69], v[180:183], v[212:215], v[66:69]
	s_setprio 0
	s_barrier
	s_add_i32 s3, s63, s27
	s_nop 0
	s_mov_b32 m0, s3
	ds_read_b128 v[184:187], v150 offset:16384
	ds_read_b128 v[188:191], v150 offset:17408
	ds_read_b128 v[192:195], v150 offset:18432
	ds_read_b128 v[196:199], v150 offset:19456
	ds_read_b128 v[200:203], v150 offset:20480
	ds_read_b128 v[204:207], v150 offset:21504
	ds_read_b128 v[208:211], v150 offset:22528
	ds_read_b128 v[212:215], v150 offset:23552
	global_load_lds_dwordx4 v134, s[72:73]
	s_add_i32 m0, s3, 0x2000
	s_add_u32 s24, s72, 0xb0000
	s_nop 0
	s_addc_u32 s25, s73, 0
	s_add_i32 s3, s66, s27
	global_load_lds_dwordx4 v130, s[72:73]
	s_nop 0
	s_mov_b32 m0, s3
	s_nop 0
	global_load_lds_dwordx4 v134, s[24:25]
	s_nop 0
	s_add_i32 m0, s3, 0x2000
	s_nop 0
	global_load_lds_dwordx4 v130, s[24:25]
	s_nop 0
	s_mov_b32 m0, s36
	s_nop 0
	global_load_lds_dwordx4 v136, s[74:75]
	s_mov_b32 m0, s37
	s_nop 0
	global_load_lds_dwordx4 v132, s[74:75]
	s_waitcnt vmcnt(8)
	s_waitcnt lgkmcnt(0)
	s_barrier
	s_setprio 1
	s_waitcnt lgkmcnt(0)
	v_mfma_f32_16x16x32_bf16 v[62:65], v[152:155], v[184:187], v[62:65]
	v_mfma_f32_16x16x32_bf16 v[58:61], v[160:163], v[184:187], v[58:61]
	v_mfma_f32_16x16x32_bf16 v[54:57], v[152:155], v[192:195], v[54:57]
	v_mfma_f32_16x16x32_bf16 v[50:53], v[160:163], v[192:195], v[50:53]
	v_mfma_f32_16x16x32_bf16 v[46:49], v[152:155], v[200:203], v[46:49]
	v_mfma_f32_16x16x32_bf16 v[38:41], v[160:163], v[200:203], v[38:41]
	v_mfma_f32_16x16x32_bf16 v[30:33], v[152:155], v[208:211], v[30:33]
	v_mfma_f32_16x16x32_bf16 v[22:25], v[160:163], v[208:211], v[22:25]
	v_mfma_f32_16x16x32_bf16 v[62:65], v[156:159], v[188:191], v[62:65]
	v_mfma_f32_16x16x32_bf16 v[58:61], v[164:167], v[188:191], v[58:61]
	v_mfma_f32_16x16x32_bf16 v[54:57], v[156:159], v[196:199], v[54:57]
	v_mfma_f32_16x16x32_bf16 v[50:53], v[164:167], v[196:199], v[50:53]
	v_mfma_f32_16x16x32_bf16 v[46:49], v[156:159], v[204:207], v[46:49]
	v_mfma_f32_16x16x32_bf16 v[38:41], v[164:167], v[204:207], v[38:41]
	v_mfma_f32_16x16x32_bf16 v[30:33], v[156:159], v[212:215], v[30:33]
	v_mfma_f32_16x16x32_bf16 v[22:25], v[164:167], v[212:215], v[22:25]
	s_setprio 0
	s_setprio 1
	v_mfma_f32_16x16x32_bf16 v[42:45], v[168:171], v[184:187], v[42:45]
	v_mfma_f32_16x16x32_bf16 v[34:37], v[176:179], v[184:187], v[34:37]
	v_mfma_f32_16x16x32_bf16 v[26:29], v[168:171], v[192:195], v[26:29]
	v_mfma_f32_16x16x32_bf16 v[18:21], v[176:179], v[192:195], v[18:21]
	v_mfma_f32_16x16x32_bf16 v[14:17], v[168:171], v[200:203], v[14:17]
	v_mfma_f32_16x16x32_bf16 v[10:13], v[176:179], v[200:203], v[10:13]
	v_mfma_f32_16x16x32_bf16 v[6:9], v[168:171], v[208:211], v[6:9]
	v_mfma_f32_16x16x32_bf16 v[2:5], v[176:179], v[208:211], v[2:5]
	v_mfma_f32_16x16x32_bf16 v[42:45], v[172:175], v[188:191], v[42:45]
	v_mfma_f32_16x16x32_bf16 v[34:37], v[180:183], v[188:191], v[34:37]
	v_mfma_f32_16x16x32_bf16 v[26:29], v[172:175], v[196:199], v[26:29]
	v_mfma_f32_16x16x32_bf16 v[18:21], v[180:183], v[196:199], v[18:21]
	v_mfma_f32_16x16x32_bf16 v[14:17], v[172:175], v[204:207], v[14:17]
	v_mfma_f32_16x16x32_bf16 v[10:13], v[180:183], v[204:207], v[10:13]
	v_mfma_f32_16x16x32_bf16 v[6:9], v[172:175], v[212:215], v[6:9]
	v_mfma_f32_16x16x32_bf16 v[2:5], v[180:183], v[212:215], v[2:5]
	s_setprio 0
	s_barrier
	s_add_i32 s3, 0, 0x18000
	v_add_u32_e32 v151, s3, v1
	s_add_i32 s12, 0, 0x1c000
	ds_read_b128 v[152:155], v151
	ds_read_b128 v[156:159], v151 offset:1024
	ds_read_b128 v[160:163], v151 offset:2048
	ds_read_b128 v[164:167], v151 offset:3072
	v_add_u32_e32 v151, s12, v1
	ds_read_b128 v[168:171], v151
	ds_read_b128 v[172:175], v151 offset:1024
	ds_read_b128 v[176:179], v151 offset:2048
	ds_read_b128 v[180:183], v151 offset:3072
	s_add_u32 s24, s74, 0xb0000
	s_addc_u32 s25, s75, 0
	s_mov_b32 m0, s44
	s_nop 0
	ds_read_b128 v[184:187], v150 offset:32768
	ds_read_b128 v[188:191], v150 offset:33792
	ds_read_b128 v[192:195], v150 offset:34816
	ds_read_b128 v[196:199], v150 offset:35840
	ds_read_b128 v[200:203], v150 offset:36864
	ds_read_b128 v[204:207], v150 offset:37888
	ds_read_b128 v[208:211], v150 offset:38912
	ds_read_b128 v[212:215], v150 offset:39936
	global_load_lds_dwordx4 v136, s[24:25]
	s_nop 0
	s_mov_b32 m0, s45
	s_nop 0
	global_load_lds_dwordx4 v132, s[24:25]
	s_waitcnt vmcnt(8)
	s_waitcnt lgkmcnt(0)
	s_barrier
	s_setprio 1
	s_waitcnt lgkmcnt(0)
	v_mfma_f32_16x16x32_bf16 v[126:129], v[152:155], v[184:187], v[126:129]
	v_mfma_f32_16x16x32_bf16 v[122:125], v[160:163], v[184:187], v[122:125]
	v_mfma_f32_16x16x32_bf16 v[118:121], v[152:155], v[192:195], v[118:121]
	v_mfma_f32_16x16x32_bf16 v[114:117], v[160:163], v[192:195], v[114:117]
	v_mfma_f32_16x16x32_bf16 v[110:113], v[152:155], v[200:203], v[110:113]
	v_mfma_f32_16x16x32_bf16 v[102:105], v[160:163], v[200:203], v[102:105]
	v_mfma_f32_16x16x32_bf16 v[94:97], v[152:155], v[208:211], v[94:97]
	v_mfma_f32_16x16x32_bf16 v[86:89], v[160:163], v[208:211], v[86:89]
	v_mfma_f32_16x16x32_bf16 v[126:129], v[156:159], v[188:191], v[126:129]
	v_mfma_f32_16x16x32_bf16 v[122:125], v[164:167], v[188:191], v[122:125]
	v_mfma_f32_16x16x32_bf16 v[118:121], v[156:159], v[196:199], v[118:121]
	v_mfma_f32_16x16x32_bf16 v[114:117], v[164:167], v[196:199], v[114:117]
	v_mfma_f32_16x16x32_bf16 v[110:113], v[156:159], v[204:207], v[110:113]
	v_mfma_f32_16x16x32_bf16 v[102:105], v[164:167], v[204:207], v[102:105]
	v_mfma_f32_16x16x32_bf16 v[94:97], v[156:159], v[212:215], v[94:97]
	v_mfma_f32_16x16x32_bf16 v[86:89], v[164:167], v[212:215], v[86:89]
	s_setprio 0
	s_setprio 1
	v_mfma_f32_16x16x32_bf16 v[106:109], v[168:171], v[184:187], v[106:109]
	v_mfma_f32_16x16x32_bf16 v[98:101], v[176:179], v[184:187], v[98:101]
	v_mfma_f32_16x16x32_bf16 v[90:93], v[168:171], v[192:195], v[90:93]
	v_mfma_f32_16x16x32_bf16 v[82:85], v[176:179], v[192:195], v[82:85]
	v_mfma_f32_16x16x32_bf16 v[78:81], v[168:171], v[200:203], v[78:81]
	v_mfma_f32_16x16x32_bf16 v[74:77], v[176:179], v[200:203], v[74:77]
	v_mfma_f32_16x16x32_bf16 v[70:73], v[168:171], v[208:211], v[70:73]
	v_mfma_f32_16x16x32_bf16 v[66:69], v[176:179], v[208:211], v[66:69]
	v_mfma_f32_16x16x32_bf16 v[106:109], v[172:175], v[188:191], v[106:109]
	v_mfma_f32_16x16x32_bf16 v[98:101], v[180:183], v[188:191], v[98:101]
	v_mfma_f32_16x16x32_bf16 v[90:93], v[172:175], v[196:199], v[90:93]
	v_mfma_f32_16x16x32_bf16 v[82:85], v[180:183], v[196:199], v[82:85]
	v_mfma_f32_16x16x32_bf16 v[78:81], v[172:175], v[204:207], v[78:81]
	v_mfma_f32_16x16x32_bf16 v[74:77], v[180:183], v[204:207], v[74:77]
	v_mfma_f32_16x16x32_bf16 v[70:73], v[172:175], v[212:215], v[70:73]
	v_mfma_f32_16x16x32_bf16 v[66:69], v[180:183], v[212:215], v[66:69]
	s_setprio 0
	s_barrier
	s_add_i32 s3, s3, s27
	s_nop 0
	s_mov_b32 m0, s3
	ds_read_b128 v[184:187], v150 offset:49152
	ds_read_b128 v[188:191], v150 offset:50176
	ds_read_b128 v[192:195], v150 offset:51200
	ds_read_b128 v[196:199], v150 offset:52224
	ds_read_b128 v[200:203], v150 offset:53248
	ds_read_b128 v[204:207], v150 offset:54272
	ds_read_b128 v[208:211], v150 offset:55296
	ds_read_b128 v[212:215], v150 offset:56320
	global_load_lds_dwordx4 v251, s[72:73]
	s_add_i32 m0, s3, 0x2000
	s_add_u32 s24, s72, 0xb0080
	s_nop 0
	s_addc_u32 s25, s73, 0
	s_add_i32 s3, s12, s27
	global_load_lds_dwordx4 v252, s[72:73]
	s_nop 0
	s_mov_b32 m0, s3
	s_nop 0
	global_load_lds_dwordx4 v134, s[24:25]
	s_nop 0
	s_add_i32 m0, s3, 0x2000
	s_nop 0
	global_load_lds_dwordx4 v130, s[24:25]
	s_nop 0
	s_mov_b32 m0, s60
	s_nop 0
	global_load_lds_dwordx4 v253, s[74:75]
	s_nop 0
	s_mov_b32 m0, s61
	s_nop 0
	global_load_lds_dwordx4 v254, s[74:75]
	s_waitcnt vmcnt(8)
	s_waitcnt lgkmcnt(0)
	s_barrier
	s_setprio 1
	s_waitcnt lgkmcnt(0)
	v_mfma_f32_16x16x32_bf16 v[62:65], v[152:155], v[184:187], v[62:65]
	v_mfma_f32_16x16x32_bf16 v[58:61], v[160:163], v[184:187], v[58:61]
	v_mfma_f32_16x16x32_bf16 v[54:57], v[152:155], v[192:195], v[54:57]
	v_mfma_f32_16x16x32_bf16 v[50:53], v[160:163], v[192:195], v[50:53]
	v_mfma_f32_16x16x32_bf16 v[46:49], v[152:155], v[200:203], v[46:49]
	v_mfma_f32_16x16x32_bf16 v[38:41], v[160:163], v[200:203], v[38:41]
	v_mfma_f32_16x16x32_bf16 v[30:33], v[152:155], v[208:211], v[30:33]
	v_mfma_f32_16x16x32_bf16 v[22:25], v[160:163], v[208:211], v[22:25]
	v_mfma_f32_16x16x32_bf16 v[62:65], v[156:159], v[188:191], v[62:65]
	v_mfma_f32_16x16x32_bf16 v[58:61], v[164:167], v[188:191], v[58:61]
	v_mfma_f32_16x16x32_bf16 v[54:57], v[156:159], v[196:199], v[54:57]
	v_mfma_f32_16x16x32_bf16 v[50:53], v[164:167], v[196:199], v[50:53]
	v_mfma_f32_16x16x32_bf16 v[46:49], v[156:159], v[204:207], v[46:49]
	v_mfma_f32_16x16x32_bf16 v[38:41], v[164:167], v[204:207], v[38:41]
	v_mfma_f32_16x16x32_bf16 v[30:33], v[156:159], v[212:215], v[30:33]
	v_mfma_f32_16x16x32_bf16 v[22:25], v[164:167], v[212:215], v[22:25]
	s_setprio 0
	s_setprio 1
	v_mfma_f32_16x16x32_bf16 v[42:45], v[168:171], v[184:187], v[42:45]
	v_mfma_f32_16x16x32_bf16 v[34:37], v[176:179], v[184:187], v[34:37]
	v_mfma_f32_16x16x32_bf16 v[26:29], v[168:171], v[192:195], v[26:29]
	v_mfma_f32_16x16x32_bf16 v[18:21], v[176:179], v[192:195], v[18:21]
	v_mfma_f32_16x16x32_bf16 v[14:17], v[168:171], v[200:203], v[14:17]
	v_mfma_f32_16x16x32_bf16 v[10:13], v[176:179], v[200:203], v[10:13]
	v_mfma_f32_16x16x32_bf16 v[6:9], v[168:171], v[208:211], v[6:9]
	v_mfma_f32_16x16x32_bf16 v[2:5], v[176:179], v[208:211], v[2:5]
	v_mfma_f32_16x16x32_bf16 v[42:45], v[172:175], v[188:191], v[42:45]
	v_mfma_f32_16x16x32_bf16 v[34:37], v[180:183], v[188:191], v[34:37]
	v_mfma_f32_16x16x32_bf16 v[26:29], v[172:175], v[196:199], v[26:29]
	v_mfma_f32_16x16x32_bf16 v[18:21], v[180:183], v[196:199], v[18:21]
	v_mfma_f32_16x16x32_bf16 v[14:17], v[172:175], v[204:207], v[14:17]
	v_mfma_f32_16x16x32_bf16 v[10:13], v[180:183], v[204:207], v[10:13]
	v_mfma_f32_16x16x32_bf16 v[6:9], v[172:175], v[212:215], v[6:9]
	v_mfma_f32_16x16x32_bf16 v[2:5], v[180:183], v[212:215], v[2:5]
	s_setprio 0
	s_barrier
	s_add_u32 s81, s81, 0x100
	s_addc_u32 s82, s82, 0
	s_cmp_ge_i32 s13, s21
	s_mov_b64 s[68:69], s[70:71]
	s_mov_b32 s12, s13
	s_cbranch_scc0 .LBB0_818
	s_and_b64 vcc, exec, s[16:17]
	s_cbranch_vccz .LBB0_821
	s_barrier

.LBB0_904:
	ds_read_b128 v[130:133], v228
	ds_read_b128 v[134:137], v228 offset:1024
	ds_read_b128 v[154:157], v228 offset:2048
	ds_read_b128 v[158:161], v228 offset:3072
	ds_read_b128 v[162:165], v229
	ds_read_b128 v[166:169], v229 offset:1024
	ds_read_b128 v[170:173], v229 offset:2048
	ds_read_b128 v[174:177], v229 offset:3072
	s_add_u32 s72, s70, 0x100
	s_addc_u32 s73, s71, 0
	s_cmp_eq_u32 s12, 40
	s_cselect_b32 s77, s1, s73
	s_cselect_b32 s76, s0, s72
	s_cselect_b32 s75, s11, s87
	s_cselect_b32 s74, s10, s69
	v_lshl_add_u64 v[210:211], s[70:71], 0, v[146:147]
	s_add_i32 m0, s33, 0xc000
	ds_read_b128 v[178:181], v230
	ds_read_b128 v[182:185], v230 offset:1024
	ds_read_b128 v[186:189], v230 offset:2048
	ds_read_b128 v[190:193], v230 offset:3072
	ds_read_b128 v[194:197], v230 offset:4096
	ds_read_b128 v[198:201], v230 offset:5120
	ds_read_b128 v[202:205], v230 offset:6144
	ds_read_b128 v[206:209], v230 offset:7168
	global_load_lds_dwordx4 v[210:211], off
	v_lshl_add_u64 v[210:211], s[70:71], 0, v[148:149]
	s_add_i32 m0, s33, 0xe000
	s_nop 0
	global_load_lds_dwordx4 v[210:211], off
	s_waitcnt vmcnt(8)
	s_waitcnt lgkmcnt(0)
	s_barrier
	s_setprio 1
	s_waitcnt lgkmcnt(0)
	v_mfma_f32_16x16x32_bf16 v[126:129], v[130:133], v[178:181], v[126:129]
	v_mfma_f32_16x16x32_bf16 v[122:125], v[154:157], v[178:181], v[122:125]
	v_mfma_f32_16x16x32_bf16 v[118:121], v[130:133], v[186:189], v[118:121]
	v_mfma_f32_16x16x32_bf16 v[114:117], v[154:157], v[186:189], v[114:117]
	v_mfma_f32_16x16x32_bf16 v[110:113], v[130:133], v[194:197], v[110:113]
	v_mfma_f32_16x16x32_bf16 v[106:109], v[154:157], v[194:197], v[106:109]
	v_mfma_f32_16x16x32_bf16 v[102:105], v[130:133], v[202:205], v[102:105]
	v_mfma_f32_16x16x32_bf16 v[98:101], v[154:157], v[202:205], v[98:101]
	v_mfma_f32_16x16x32_bf16 v[126:129], v[134:137], v[182:185], v[126:129]
	v_mfma_f32_16x16x32_bf16 v[122:125], v[158:161], v[182:185], v[122:125]
	v_mfma_f32_16x16x32_bf16 v[118:121], v[134:137], v[190:193], v[118:121]
	v_mfma_f32_16x16x32_bf16 v[114:117], v[158:161], v[190:193], v[114:117]
	v_mfma_f32_16x16x32_bf16 v[110:113], v[134:137], v[198:201], v[110:113]
	v_mfma_f32_16x16x32_bf16 v[106:109], v[158:161], v[198:201], v[106:109]
	v_mfma_f32_16x16x32_bf16 v[102:105], v[134:137], v[206:209], v[102:105]
	v_mfma_f32_16x16x32_bf16 v[98:101], v[158:161], v[206:209], v[98:101]
	s_setprio 0
	s_setprio 1
	v_mfma_f32_16x16x32_bf16 v[62:65], v[162:165], v[178:181], v[62:65]
	v_mfma_f32_16x16x32_bf16 v[58:61], v[170:173], v[178:181], v[58:61]
	v_mfma_f32_16x16x32_bf16 v[54:57], v[162:165], v[186:189], v[54:57]
	v_mfma_f32_16x16x32_bf16 v[50:53], v[170:173], v[186:189], v[50:53]
	v_mfma_f32_16x16x32_bf16 v[46:49], v[162:165], v[194:197], v[46:49]
	v_mfma_f32_16x16x32_bf16 v[42:45], v[170:173], v[194:197], v[42:45]
	v_mfma_f32_16x16x32_bf16 v[38:41], v[162:165], v[202:205], v[38:41]
	v_mfma_f32_16x16x32_bf16 v[34:37], v[170:173], v[202:205], v[34:37]
	v_mfma_f32_16x16x32_bf16 v[62:65], v[166:169], v[182:185], v[62:65]
	v_mfma_f32_16x16x32_bf16 v[58:61], v[174:177], v[182:185], v[58:61]
	v_mfma_f32_16x16x32_bf16 v[54:57], v[166:169], v[190:193], v[54:57]
	v_mfma_f32_16x16x32_bf16 v[50:53], v[174:177], v[190:193], v[50:53]
	v_mfma_f32_16x16x32_bf16 v[46:49], v[166:169], v[198:201], v[46:49]
	v_mfma_f32_16x16x32_bf16 v[42:45], v[174:177], v[198:201], v[42:45]
	v_mfma_f32_16x16x32_bf16 v[38:41], v[166:169], v[206:209], v[38:41]
	v_mfma_f32_16x16x32_bf16 v[34:37], v[174:177], v[206:209], v[34:37]
	s_setprio 0
	s_barrier
	s_add_i32 s3, s82, s27
	s_nop 0
	s_mov_b32 m0, s3
	ds_read_b128 v[178:181], v230 offset:16384
	ds_read_b128 v[182:185], v230 offset:17408
	ds_read_b128 v[186:189], v230 offset:18432
	ds_read_b128 v[190:193], v230 offset:19456
	ds_read_b128 v[194:197], v230 offset:20480
	ds_read_b128 v[198:201], v230 offset:21504
	ds_read_b128 v[202:205], v230 offset:22528
	ds_read_b128 v[206:209], v230 offset:23552
	global_load_lds_dwordx4 v140, s[74:75]
	s_add_i32 m0, s3, 0x2000
	s_add_u32 s24, s74, 0xb0000
	s_nop 0
	s_addc_u32 s25, s75, 0
	s_add_i32 s3, s83, s27
	global_load_lds_dwordx4 v144, s[74:75]
	s_nop 0
	s_mov_b32 m0, s3
	s_nop 0
	global_load_lds_dwordx4 v140, s[24:25]
	s_nop 0
	s_add_i32 m0, s3, 0x2000
	s_nop 0
	global_load_lds_dwordx4 v144, s[24:25]
	s_nop 0
	s_mov_b32 m0, s33
	s_nop 0
	global_load_lds_dwordx4 v138, s[76:77]
	s_mov_b32 m0, s36
	s_nop 0
	global_load_lds_dwordx4 v142, s[76:77]
	s_waitcnt vmcnt(8)
	s_waitcnt lgkmcnt(0)
	s_barrier
	s_setprio 1
	s_waitcnt lgkmcnt(0)
	v_mfma_f32_16x16x32_bf16 v[94:97], v[130:133], v[178:181], v[94:97]
	v_mfma_f32_16x16x32_bf16 v[90:93], v[154:157], v[178:181], v[90:93]
	v_mfma_f32_16x16x32_bf16 v[86:89], v[130:133], v[186:189], v[86:89]
	v_mfma_f32_16x16x32_bf16 v[82:85], v[154:157], v[186:189], v[82:85]
	v_mfma_f32_16x16x32_bf16 v[78:81], v[130:133], v[194:197], v[78:81]
	v_mfma_f32_16x16x32_bf16 v[74:77], v[154:157], v[194:197], v[74:77]
	v_mfma_f32_16x16x32_bf16 v[70:73], v[130:133], v[202:205], v[70:73]
	v_mfma_f32_16x16x32_bf16 v[66:69], v[154:157], v[202:205], v[66:69]
	v_mfma_f32_16x16x32_bf16 v[94:97], v[134:137], v[182:185], v[94:97]
	v_mfma_f32_16x16x32_bf16 v[90:93], v[158:161], v[182:185], v[90:93]
	v_mfma_f32_16x16x32_bf16 v[86:89], v[134:137], v[190:193], v[86:89]
	v_mfma_f32_16x16x32_bf16 v[82:85], v[158:161], v[190:193], v[82:85]
	v_mfma_f32_16x16x32_bf16 v[78:81], v[134:137], v[198:201], v[78:81]
	v_mfma_f32_16x16x32_bf16 v[74:77], v[158:161], v[198:201], v[74:77]
	v_mfma_f32_16x16x32_bf16 v[70:73], v[134:137], v[206:209], v[70:73]
	v_mfma_f32_16x16x32_bf16 v[66:69], v[158:161], v[206:209], v[66:69]
	s_setprio 0
	s_setprio 1
	v_mfma_f32_16x16x32_bf16 v[30:33], v[162:165], v[178:181], v[30:33]
	v_mfma_f32_16x16x32_bf16 v[26:29], v[170:173], v[178:181], v[26:29]
	v_mfma_f32_16x16x32_bf16 v[22:25], v[162:165], v[186:189], v[22:25]
	v_mfma_f32_16x16x32_bf16 v[18:21], v[170:173], v[186:189], v[18:21]
	v_mfma_f32_16x16x32_bf16 v[14:17], v[162:165], v[194:197], v[14:17]
	v_mfma_f32_16x16x32_bf16 v[10:13], v[170:173], v[194:197], v[10:13]
	v_mfma_f32_16x16x32_bf16 v[6:9], v[162:165], v[202:205], v[6:9]
	v_mfma_f32_16x16x32_bf16 v[2:5], v[170:173], v[202:205], v[2:5]
	v_mfma_f32_16x16x32_bf16 v[30:33], v[166:169], v[182:185], v[30:33]
	v_mfma_f32_16x16x32_bf16 v[26:29], v[174:177], v[182:185], v[26:29]
	v_mfma_f32_16x16x32_bf16 v[22:25], v[166:169], v[190:193], v[22:25]
	v_mfma_f32_16x16x32_bf16 v[18:21], v[174:177], v[190:193], v[18:21]
	v_mfma_f32_16x16x32_bf16 v[14:17], v[166:169], v[198:201], v[14:17]
	v_mfma_f32_16x16x32_bf16 v[10:13], v[174:177], v[198:201], v[10:13]
	v_mfma_f32_16x16x32_bf16 v[6:9], v[166:169], v[206:209], v[6:9]
	v_mfma_f32_16x16x32_bf16 v[2:5], v[174:177], v[206:209], v[2:5]
	s_setprio 0
	s_barrier
	s_add_i32 s3, 0, 0x18000
	s_add_i32 s13, 0, 0x1c000
	v_add_u32_e32 v158, s3, v226
	v_add_u32_e32 v174, s13, v226
	ds_read_b128 v[130:133], v158
	ds_read_b128 v[134:137], v158 offset:1024
	ds_read_b128 v[154:157], v158 offset:2048
	ds_read_b128 v[158:161], v158 offset:3072
	ds_read_b128 v[162:165], v174
	ds_read_b128 v[166:169], v174 offset:1024
	ds_read_b128 v[170:173], v174 offset:2048
	ds_read_b128 v[174:177], v174 offset:3072
	s_add_u32 s24, s76, 0xb0000
	s_addc_u32 s25, s77, 0
	s_mov_b32 m0, s37
	s_nop 0
	ds_read_b128 v[178:181], v230 offset:32768
	ds_read_b128 v[182:185], v230 offset:33792
	ds_read_b128 v[186:189], v230 offset:34816
	ds_read_b128 v[190:193], v230 offset:35840
	ds_read_b128 v[194:197], v230 offset:36864
	ds_read_b128 v[198:201], v230 offset:37888
	ds_read_b128 v[202:205], v230 offset:38912
	ds_read_b128 v[206:209], v230 offset:39936
	global_load_lds_dwordx4 v138, s[24:25]
	s_nop 0
	s_mov_b32 m0, s44
	s_nop 0
	global_load_lds_dwordx4 v142, s[24:25]
	s_waitcnt vmcnt(8)
	s_waitcnt lgkmcnt(0)
	s_barrier
	s_setprio 1
	s_waitcnt lgkmcnt(0)
	v_mfma_f32_16x16x32_bf16 v[126:129], v[130:133], v[178:181], v[126:129]
	v_mfma_f32_16x16x32_bf16 v[122:125], v[154:157], v[178:181], v[122:125]
	v_mfma_f32_16x16x32_bf16 v[118:121], v[130:133], v[186:189], v[118:121]
	v_mfma_f32_16x16x32_bf16 v[114:117], v[154:157], v[186:189], v[114:117]
	v_mfma_f32_16x16x32_bf16 v[110:113], v[130:133], v[194:197], v[110:113]
	v_mfma_f32_16x16x32_bf16 v[106:109], v[154:157], v[194:197], v[106:109]
	v_mfma_f32_16x16x32_bf16 v[102:105], v[130:133], v[202:205], v[102:105]
	v_mfma_f32_16x16x32_bf16 v[98:101], v[154:157], v[202:205], v[98:101]
	v_mfma_f32_16x16x32_bf16 v[126:129], v[134:137], v[182:185], v[126:129]
	v_mfma_f32_16x16x32_bf16 v[122:125], v[158:161], v[182:185], v[122:125]
	v_mfma_f32_16x16x32_bf16 v[118:121], v[134:137], v[190:193], v[118:121]
	v_mfma_f32_16x16x32_bf16 v[114:117], v[158:161], v[190:193], v[114:117]
	v_mfma_f32_16x16x32_bf16 v[110:113], v[134:137], v[198:201], v[110:113]
	v_mfma_f32_16x16x32_bf16 v[106:109], v[158:161], v[198:201], v[106:109]
	v_mfma_f32_16x16x32_bf16 v[102:105], v[134:137], v[206:209], v[102:105]
	v_mfma_f32_16x16x32_bf16 v[98:101], v[158:161], v[206:209], v[98:101]
	s_setprio 0
	s_setprio 1
	v_mfma_f32_16x16x32_bf16 v[62:65], v[162:165], v[178:181], v[62:65]
	v_mfma_f32_16x16x32_bf16 v[58:61], v[170:173], v[178:181], v[58:61]
	v_mfma_f32_16x16x32_bf16 v[54:57], v[162:165], v[186:189], v[54:57]
	v_mfma_f32_16x16x32_bf16 v[50:53], v[170:173], v[186:189], v[50:53]
	v_mfma_f32_16x16x32_bf16 v[46:49], v[162:165], v[194:197], v[46:49]
	v_mfma_f32_16x16x32_bf16 v[42:45], v[170:173], v[194:197], v[42:45]
	v_mfma_f32_16x16x32_bf16 v[38:41], v[162:165], v[202:205], v[38:41]
	v_mfma_f32_16x16x32_bf16 v[34:37], v[170:173], v[202:205], v[34:37]
	v_mfma_f32_16x16x32_bf16 v[62:65], v[166:169], v[182:185], v[62:65]
	v_mfma_f32_16x16x32_bf16 v[58:61], v[174:177], v[182:185], v[58:61]
	v_mfma_f32_16x16x32_bf16 v[54:57], v[166:169], v[190:193], v[54:57]
	v_mfma_f32_16x16x32_bf16 v[50:53], v[174:177], v[190:193], v[50:53]
	v_mfma_f32_16x16x32_bf16 v[46:49], v[166:169], v[198:201], v[46:49]
	v_mfma_f32_16x16x32_bf16 v[42:45], v[174:177], v[198:201], v[42:45]
	v_mfma_f32_16x16x32_bf16 v[38:41], v[166:169], v[206:209], v[38:41]
	v_mfma_f32_16x16x32_bf16 v[34:37], v[174:177], v[206:209], v[34:37]
	s_setprio 0
	s_barrier
	s_add_i32 s3, s3, s27
	s_nop 0
	s_mov_b32 m0, s3
	ds_read_b128 v[178:181], v230 offset:49152
	ds_read_b128 v[182:185], v230 offset:50176
	ds_read_b128 v[186:189], v230 offset:51200
	ds_read_b128 v[190:193], v230 offset:52224
	ds_read_b128 v[194:197], v230 offset:53248
	ds_read_b128 v[198:201], v230 offset:54272
	ds_read_b128 v[202:205], v230 offset:55296
	ds_read_b128 v[206:209], v230 offset:56320
	global_load_lds_dwordx4 v251, s[74:75]
	s_add_i32 m0, s3, 0x2000
	s_add_u32 s24, s74, 0xb0080
	s_nop 0
	s_addc_u32 s25, s75, 0
	s_add_i32 s3, s13, s27
	global_load_lds_dwordx4 v252, s[74:75]
	s_nop 0
	s_mov_b32 m0, s3
	s_nop 0
	global_load_lds_dwordx4 v140, s[24:25]
	s_nop 0
	s_add_i32 m0, s3, 0x2000
	s_nop 0
	global_load_lds_dwordx4 v144, s[24:25]
	s_nop 0
	s_mov_b32 m0, s79
	s_nop 0
	global_load_lds_dwordx4 v253, s[76:77]
	s_nop 0
	s_mov_b32 m0, s80
	s_nop 0
	global_load_lds_dwordx4 v254, s[76:77]
	s_waitcnt vmcnt(8)
	s_waitcnt lgkmcnt(0)
	s_barrier
	s_setprio 1
	s_waitcnt lgkmcnt(0)
	v_mfma_f32_16x16x32_bf16 v[94:97], v[130:133], v[178:181], v[94:97]
	v_mfma_f32_16x16x32_bf16 v[90:93], v[154:157], v[178:181], v[90:93]
	v_mfma_f32_16x16x32_bf16 v[86:89], v[130:133], v[186:189], v[86:89]
	v_mfma_f32_16x16x32_bf16 v[82:85], v[154:157], v[186:189], v[82:85]
	v_mfma_f32_16x16x32_bf16 v[78:81], v[130:133], v[194:197], v[78:81]
	v_mfma_f32_16x16x32_bf16 v[74:77], v[154:157], v[194:197], v[74:77]
	v_mfma_f32_16x16x32_bf16 v[70:73], v[130:133], v[202:205], v[70:73]
	v_mfma_f32_16x16x32_bf16 v[66:69], v[154:157], v[202:205], v[66:69]
	v_mfma_f32_16x16x32_bf16 v[94:97], v[134:137], v[182:185], v[94:97]
	v_mfma_f32_16x16x32_bf16 v[90:93], v[158:161], v[182:185], v[90:93]
	v_mfma_f32_16x16x32_bf16 v[86:89], v[134:137], v[190:193], v[86:89]
	v_mfma_f32_16x16x32_bf16 v[82:85], v[158:161], v[190:193], v[82:85]
	v_mfma_f32_16x16x32_bf16 v[78:81], v[134:137], v[198:201], v[78:81]
	v_mfma_f32_16x16x32_bf16 v[74:77], v[158:161], v[198:201], v[74:77]
	v_mfma_f32_16x16x32_bf16 v[70:73], v[134:137], v[206:209], v[70:73]
	v_mfma_f32_16x16x32_bf16 v[66:69], v[158:161], v[206:209], v[66:69]
	s_setprio 0
	s_setprio 1
	v_mfma_f32_16x16x32_bf16 v[30:33], v[162:165], v[178:181], v[30:33]
	v_mfma_f32_16x16x32_bf16 v[26:29], v[170:173], v[178:181], v[26:29]
	v_mfma_f32_16x16x32_bf16 v[22:25], v[162:165], v[186:189], v[22:25]
	v_mfma_f32_16x16x32_bf16 v[18:21], v[170:173], v[186:189], v[18:21]
	v_mfma_f32_16x16x32_bf16 v[14:17], v[162:165], v[194:197], v[14:17]
	v_mfma_f32_16x16x32_bf16 v[10:13], v[170:173], v[194:197], v[10:13]
	v_mfma_f32_16x16x32_bf16 v[6:9], v[162:165], v[202:205], v[6:9]
	v_mfma_f32_16x16x32_bf16 v[2:5], v[170:173], v[202:205], v[2:5]
	v_mfma_f32_16x16x32_bf16 v[30:33], v[166:169], v[182:185], v[30:33]
	v_mfma_f32_16x16x32_bf16 v[26:29], v[174:177], v[182:185], v[26:29]
	v_mfma_f32_16x16x32_bf16 v[22:25], v[166:169], v[190:193], v[22:25]
	v_mfma_f32_16x16x32_bf16 v[18:21], v[174:177], v[190:193], v[18:21]
	v_mfma_f32_16x16x32_bf16 v[14:17], v[166:169], v[198:201], v[14:17]
	v_mfma_f32_16x16x32_bf16 v[10:13], v[174:177], v[198:201], v[10:13]
	v_mfma_f32_16x16x32_bf16 v[6:9], v[166:169], v[206:209], v[6:9]
	v_mfma_f32_16x16x32_bf16 v[2:5], v[174:177], v[206:209], v[2:5]
	s_setprio 0
	s_barrier
	s_add_i32 s12, s12, 2
	s_add_u32 s69, s69, 0x100
	s_addc_u32 s87, s87, 0
	s_cmp_gt_u32 s12, 41
	s_mov_b64 s[70:71], s[72:73]
	s_cbranch_scc0 .LBB0_904
	s_ashr_i32 s3, s68, 3
	s_ashr_i32 s69, s68, 31
	s_mul_hi_i32 s72, s3, 0x6000
	s_mulk_i32 s3, 0x6000
	s_add_u32 s12, s66, s3
	v_mov_b32_e32 v130, v1
	s_addc_u32 s13, s67, s72
	s_lshl_b64 s[24:25], s[68:69], 19
	v_lshl_or_b32 v166, s86, 8, v227
	s_add_u32 s70, s48, s24
	v_add_u32_e32 v160, s78, v130
	v_ashrrev_i32_e32 v167, 31, v166
	s_addc_u32 s71, s49, s25
	v_lshlrev_b64 v[156:157], 1, v[166:167]
	v_ashrrev_i32_e32 v161, 31, v160
	v_lshlrev_b64 v[130:131], 2, v[166:167]
	v_lshl_add_u64 v[162:163], s[70:71], 0, v[156:157]
	v_lshlrev_b64 v[154:155], 11, v[160:161]
	v_add_u32_e32 v170, 16, v160
	v_lshl_add_u64 v[172:173], s[12:13], 0, v[130:131]
	v_lshl_add_u64 v[174:175], v[162:163], 0, v[154:155]
	v_ashrrev_i32_e32 v171, 31, v170
	s_add_u32 s12, s60, s24
	v_lshl_add_u64 v[132:133], s[16:17], 0, v[130:131]
	global_load_dwordx4 v[180:183], v[172:173], off offset:16
	global_load_dwordx4 v[184:187], v[172:173], off
	global_load_dwordx4 v[188:191], v[132:133], off offset:16
	global_load_dwordx4 v[192:195], v[132:133], off
	global_load_dwordx4 v[196:199], v[174:175], off nt
	v_lshlrev_b64 v[204:205], 11, v[170:171]
	s_addc_u32 s13, s61, s25
	v_lshl_add_u64 v[178:179], v[162:163], 0, v[204:205]
	s_add_u32 s24, s62, s3
	global_load_dwordx4 v[200:203], v[178:179], off nt
	s_addc_u32 s25, s63, s72
	v_lshl_add_u64 v[176:177], s[24:25], 0, v[130:131]
	global_load_dwordx4 v[134:137], v[176:177], off
	global_load_dwordx4 v[130:133], v[176:177], off offset:16
	v_lshl_add_u64 v[158:159], s[12:13], 0, v[156:157]
	s_lshl_b32 s12, s68, 8
	v_lshl_add_u64 v[164:165], v[158:159], 0, v[154:155]
	v_add_u32_e32 v154, s12, v160
	v_ashrrev_i32_e32 v155, 31, v154
	v_lshlrev_b64 v[168:169], 11, v[154:155]
	v_lshl_add_u64 v[168:169], s[20:21], 0, v[168:169]
	v_add_u32_e32 v170, s12, v170
	v_lshl_add_u64 v[168:169], v[168:169], 0, v[156:157]
	v_ashrrev_i32_e32 v171, 31, v170
	v_lshlrev_b64 v[170:171], 11, v[170:171]
	v_lshl_add_u64 v[170:171], s[20:21], 0, v[170:171]
	s_waitcnt vmcnt(0)
	v_pk_add_f32 v[182:183], v[182:183], 1.0 op_sel_hi:[1,0]
	v_pk_add_f32 v[186:187], v[186:187], 1.0 op_sel_hi:[1,0]
	v_pk_add_f32 v[184:185], v[184:185], 1.0 op_sel_hi:[1,0]
	v_pk_add_f32 v[180:181], v[180:181], 1.0 op_sel_hi:[1,0]
	v_pk_mul_f32 v[216:217], v[194:195], v[186:187]
	v_pk_mul_f32 v[218:219], v[192:193], v[184:185]
	v_pk_mul_f32 v[220:221], v[190:191], v[182:183]
	v_pk_mul_f32 v[222:223], v[188:189], v[180:181]
	v_cvt_f32_f16_e32 v180, v198
	v_cvt_f32_f16_sdwa v181, v198 dst_sel:DWORD dst_unused:UNUSED_PAD src0_sel:WORD_1
	v_cvt_f32_f16_e32 v182, v199
	v_cvt_f32_f16_sdwa v183, v199 dst_sel:DWORD dst_unused:UNUSED_PAD src0_sel:WORD_1
	v_cvt_f32_f16_e32 v184, v196
	v_cvt_f32_f16_sdwa v185, v196 dst_sel:DWORD dst_unused:UNUSED_PAD src0_sel:WORD_1
	v_cvt_f32_f16_e32 v186, v197
	v_cvt_f32_f16_sdwa v187, v197 dst_sel:DWORD dst_unused:UNUSED_PAD src0_sel:WORD_1
	v_cvt_f32_f16_e32 v188, v202
	v_cvt_f32_f16_sdwa v189, v202 dst_sel:DWORD dst_unused:UNUSED_PAD src0_sel:WORD_1
	v_cvt_f32_f16_e32 v190, v203
	v_cvt_f32_f16_sdwa v191, v203 dst_sel:DWORD dst_unused:UNUSED_PAD src0_sel:WORD_1
	v_cvt_f32_f16_e32 v192, v200
	v_cvt_f32_f16_sdwa v193, v200 dst_sel:DWORD dst_unused:UNUSED_PAD src0_sel:WORD_1
	v_cvt_f32_f16_e32 v194, v201
	v_cvt_f32_f16_sdwa v195, v201 dst_sel:DWORD dst_unused:UNUSED_PAD src0_sel:WORD_1
	v_pk_fma_f32 v[128:129], v[128:129], v[136:137], v[186:187]
	v_pk_fma_f32 v[126:127], v[126:127], v[134:135], v[184:185]
	v_pk_fma_f32 v[124:125], v[124:125], v[132:133], v[182:183]
	v_pk_fma_f32 v[122:123], v[122:123], v[130:131], v[180:181]
	v_cvt_pk_f16_f32 v183, v124, v125
	v_cvt_pk_f16_f32 v181, v128, v129
	v_cvt_pk_f16_f32 v182, v122, v123
	v_cvt_pk_f16_f32 v180, v126, v127
	v_pk_fma_f32 v[120:121], v[120:121], v[136:137], v[194:195]
	v_pk_fma_f32 v[118:119], v[118:119], v[134:135], v[192:193]
	v_pk_fma_f32 v[116:117], v[116:117], v[132:133], v[190:191]
	v_pk_fma_f32 v[114:115], v[114:115], v[130:131], v[188:189]
	v_pk_mul_f32 v[188:189], v[216:217], v[128:129]
	v_pk_mul_f32 v[190:191], v[218:219], v[126:127]
	global_store_dwordx4 v[164:165], v[180:183], off
	v_pk_mul_f32 v[192:193], v[220:221], v[124:125]
	v_pk_mul_f32 v[194:195], v[222:223], v[122:123]
	v_cvt_pk_bf16_f32 v180, v190, v191
	v_cvt_pk_bf16_f32 v181, v188, v189
	v_cvt_pk_f16_f32 v187, v116, v117
	v_cvt_pk_f16_f32 v185, v120, v121
	v_cvt_pk_f16_f32 v186, v114, v115
	v_cvt_pk_bf16_f32 v182, v194, v195
	v_cvt_pk_bf16_f32 v183, v192, v193
	global_store_dwordx4 v[168:169], v[180:183], off
	v_cvt_pk_f16_f32 v184, v118, v119
	v_pk_mul_f32 v[188:189], v[222:223], v[114:115]
	v_lshl_add_u64 v[180:181], v[158:159], 0, v[204:205]
	global_store_dwordx4 v[180:181], v[184:187], off
	v_pk_mul_f32 v[182:183], v[218:219], v[118:119]
	v_add_u32_e32 v192, 48, v160
	v_pk_mul_f32 v[184:185], v[216:217], v[120:121]
	v_pk_mul_f32 v[186:187], v[220:221], v[116:117]
	v_cvt_pk_bf16_f32 v182, v182, v183
	v_cvt_pk_bf16_f32 v183, v184, v185
	v_cvt_pk_bf16_f32 v184, v188, v189
	v_ashrrev_i32_e32 v193, 31, v192
	v_cvt_pk_bf16_f32 v185, v186, v187
	v_lshl_add_u64 v[186:187], v[170:171], 0, v[156:157]
	global_store_dwordx4 v[186:187], v[182:185], off
	v_mul_f32_e32 v127, v127, v127
	v_mul_f32_e32 v129, v129, v129
	v_add_u32_e32 v182, 32, v160
	v_ashrrev_i32_e32 v183, 31, v182
	v_lshlrev_b64 v[170:171], 11, v[182:183]
	v_lshl_add_u64 v[188:189], v[162:163], 0, v[170:171]
	global_load_dwordx4 v[194:197], v[188:189], off nt
	v_lshlrev_b64 v[184:185], 11, v[192:193]
	v_lshl_add_u64 v[190:191], v[162:163], 0, v[184:185]
	global_load_dwordx4 v[198:201], v[190:191], off nt
	v_add_u32_e32 v182, s12, v182
	v_add_u32_e32 v192, s12, v192
	v_ashrrev_i32_e32 v183, 31, v182
	v_ashrrev_i32_e32 v193, 31, v192
	v_lshlrev_b64 v[182:183], 11, v[182:183]
	v_lshlrev_b64 v[192:193], 11, v[192:193]
	v_lshl_add_u64 v[182:183], s[20:21], 0, v[182:183]
	v_lshl_add_u64 v[202:203], s[20:21], 0, v[192:193]
	v_lshl_add_u64 v[192:193], v[182:183], 0, v[156:157]
	v_lshl_add_u64 v[170:171], v[158:159], 0, v[170:171]
	v_lshl_add_u64 v[184:185], v[158:159], 0, v[184:185]
	v_mul_f32_e32 v123, v123, v123
	v_mul_f32_e32 v125, v125, v125
	v_fmac_f32_e32 v127, v126, v126
	v_fmac_f32_e32 v129, v128, v128
	v_fmac_f32_e32 v123, v122, v122
	v_fmac_f32_e32 v125, v124, v124
	v_add_f32_e32 v122, v127, v129
	v_add_f32_e32 v123, v123, v125
	v_add_f32_e32 v122, v122, v123
	s_waitcnt vmcnt(1)
	v_cvt_f32_f16_e32 v182, v196
	v_cvt_f32_f16_sdwa v183, v196 dst_sel:DWORD dst_unused:UNUSED_PAD src0_sel:WORD_1
	v_cvt_f32_f16_e32 v196, v197
	v_cvt_f32_f16_sdwa v197, v197 dst_sel:DWORD dst_unused:UNUSED_PAD src0_sel:WORD_1
	v_cvt_f32_f16_e32 v204, v194
	v_cvt_f32_f16_sdwa v205, v194 dst_sel:DWORD dst_unused:UNUSED_PAD src0_sel:WORD_1
	v_cvt_f32_f16_e32 v194, v195
	v_cvt_f32_f16_sdwa v195, v195 dst_sel:DWORD dst_unused:UNUSED_PAD src0_sel:WORD_1
	s_waitcnt vmcnt(0)
	v_cvt_f32_f16_e32 v206, v200
	v_cvt_f32_f16_sdwa v207, v200 dst_sel:DWORD dst_unused:UNUSED_PAD src0_sel:WORD_1
	v_cvt_f32_f16_e32 v208, v198
	v_cvt_f32_f16_sdwa v209, v198 dst_sel:DWORD dst_unused:UNUSED_PAD src0_sel:WORD_1
	v_cvt_f32_f16_e32 v198, v199
	v_cvt_f32_f16_sdwa v199, v199 dst_sel:DWORD dst_unused:UNUSED_PAD src0_sel:WORD_1
	v_cvt_f32_f16_e32 v200, v201
	v_cvt_f32_f16_sdwa v201, v201 dst_sel:DWORD dst_unused:UNUSED_PAD src0_sel:WORD_1
	v_pk_fma_f32 v[112:113], v[112:113], v[136:137], v[194:195]
	v_pk_fma_f32 v[110:111], v[110:111], v[134:135], v[204:205]
	v_pk_fma_f32 v[108:109], v[108:109], v[132:133], v[196:197]
	v_pk_fma_f32 v[106:107], v[106:107], v[130:131], v[182:183]
	v_cvt_pk_f16_f32 v197, v108, v109
	v_cvt_pk_f16_f32 v195, v112, v113
	v_cvt_pk_f16_f32 v196, v106, v107
	v_cvt_pk_f16_f32 v194, v110, v111
	v_pk_mul_f32 v[182:183], v[216:217], v[112:113]
	v_pk_fma_f32 v[104:105], v[104:105], v[136:137], v[198:199]
	v_pk_fma_f32 v[102:103], v[102:103], v[134:135], v[208:209]
	v_pk_fma_f32 v[98:99], v[98:99], v[130:131], v[206:207]
	v_pk_mul_f32 v[204:205], v[218:219], v[110:111]
	v_pk_mul_f32 v[206:207], v[220:221], v[108:109]
	global_store_dwordx4 v[170:171], v[194:197], off
	v_pk_fma_f32 v[100:101], v[100:101], v[132:133], v[200:201]
	v_pk_mul_f32 v[208:209], v[222:223], v[106:107]
	v_cvt_pk_bf16_f32 v194, v204, v205
	v_cvt_pk_bf16_f32 v195, v182, v183
	v_add_u32_e32 v182, 0x80, v160
	v_cvt_pk_f16_f32 v199, v104, v105
	v_cvt_pk_f16_f32 v198, v102, v103
	v_cvt_pk_bf16_f32 v196, v208, v209
	v_cvt_pk_bf16_f32 v197, v206, v207
	v_ashrrev_i32_e32 v183, 31, v182
	v_add_u32_e32 v206, 0x90, v160
	v_cvt_pk_f16_f32 v201, v100, v101
	v_cvt_pk_f16_f32 v200, v98, v99
	v_pk_mul_f32 v[210:211], v[216:217], v[104:105]
	v_pk_mul_f32 v[212:213], v[218:219], v[102:103]
	global_store_dwordx4 v[192:193], v[194:197], off
	global_store_dwordx4 v[184:185], v[198:201], off
	v_ashrrev_i32_e32 v207, 31, v206
	v_lshl_add_u64 v[196:197], v[202:203], 0, v[156:157]
	v_cvt_pk_bf16_f32 v198, v212, v213
	v_cvt_pk_bf16_f32 v199, v210, v211
	v_lshlrev_b64 v[194:195], 11, v[182:183]
	v_pk_mul_f32 v[214:215], v[220:221], v[100:101]
	v_pk_mul_f32 v[224:225], v[222:223], v[98:99]
	v_lshlrev_b64 v[208:209], 11, v[206:207]
	v_cvt_pk_bf16_f32 v200, v224, v225
	v_cvt_pk_bf16_f32 v201, v214, v215
	global_store_dwordx4 v[196:197], v[198:201], off
	v_lshl_add_u64 v[204:205], v[162:163], 0, v[208:209]
	global_load_dwordx4 v[236:239], v[204:205], off nt
	v_lshl_add_u64 v[198:199], v[162:163], 0, v[194:195]
	global_load_dwordx4 v[232:235], v[198:199], off nt
	v_lshl_add_u64 v[212:213], v[158:159], 0, v[194:195]
	v_add_u32_e32 v182, s12, v182
	v_add_u32_e32 v194, s12, v206
	v_ashrrev_i32_e32 v183, 31, v182
	v_ashrrev_i32_e32 v195, 31, v194
	v_lshlrev_b64 v[182:183], 11, v[182:183]
	v_lshlrev_b64 v[194:195], 11, v[194:195]
	v_lshl_add_u64 v[182:183], s[20:21], 0, v[182:183]
	v_lshl_add_u64 v[194:195], s[20:21], 0, v[194:195]
	v_lshl_add_u64 v[210:211], v[158:159], 0, v[208:209]
	v_lshl_add_u64 v[214:215], v[182:183], 0, v[156:157]
	v_lshl_add_u64 v[208:209], v[194:195], 0, v[156:157]
	v_add_u32_e32 v200, 0xa0, v160
	v_ashrrev_i32_e32 v201, 31, v200
	v_lshlrev_b64 v[240:241], 11, v[200:201]
	v_lshl_add_u64 v[202:203], v[162:163], 0, v[240:241]
	s_waitcnt vmcnt(0)
	v_cvt_f32_f16_e32 v182, v234
	v_cvt_f32_f16_sdwa v183, v234 dst_sel:DWORD dst_unused:UNUSED_PAD src0_sel:WORD_1
	v_cvt_f32_f16_e32 v194, v235
	v_cvt_f32_f16_sdwa v195, v235 dst_sel:DWORD dst_unused:UNUSED_PAD src0_sel:WORD_1
	v_cvt_f32_f16_e32 v206, v232
	v_cvt_f32_f16_sdwa v207, v232 dst_sel:DWORD dst_unused:UNUSED_PAD src0_sel:WORD_1
	v_cvt_f32_f16_e32 v224, v233
	v_cvt_f32_f16_sdwa v225, v233 dst_sel:DWORD dst_unused:UNUSED_PAD src0_sel:WORD_1
	v_cvt_f32_f16_e32 v232, v238
	v_cvt_f32_f16_sdwa v233, v238 dst_sel:DWORD dst_unused:UNUSED_PAD src0_sel:WORD_1
	v_cvt_f32_f16_e32 v234, v239
	v_cvt_f32_f16_sdwa v235, v239 dst_sel:DWORD dst_unused:UNUSED_PAD src0_sel:WORD_1
	v_cvt_f32_f16_e32 v238, v236
	v_cvt_f32_f16_sdwa v239, v236 dst_sel:DWORD dst_unused:UNUSED_PAD src0_sel:WORD_1
	v_cvt_f32_f16_e32 v236, v237
	v_cvt_f32_f16_sdwa v237, v237 dst_sel:DWORD dst_unused:UNUSED_PAD src0_sel:WORD_1
	v_pk_fma_f32 v[96:97], v[96:97], v[136:137], v[224:225]
	v_pk_fma_f32 v[94:95], v[94:95], v[134:135], v[206:207]
	v_pk_fma_f32 v[92:93], v[92:93], v[132:133], v[194:195]
	v_pk_fma_f32 v[90:91], v[90:91], v[130:131], v[182:183]
	v_pk_fma_f32 v[84:85], v[84:85], v[132:133], v[234:235]
	v_pk_fma_f32 v[82:83], v[82:83], v[130:131], v[232:233]
	v_cvt_pk_f16_f32 v235, v92, v93
	v_cvt_pk_f16_f32 v233, v96, v97
	v_cvt_pk_f16_f32 v234, v90, v91
	v_cvt_pk_f16_f32 v232, v94, v95
	v_pk_mul_f32 v[206:207], v[220:221], v[92:93]
	v_pk_mul_f32 v[182:183], v[216:217], v[96:97]
	v_pk_mul_f32 v[194:195], v[218:219], v[94:95]
	v_pk_mul_f32 v[224:225], v[222:223], v[90:91]
	global_store_dwordx4 v[212:213], v[232:235], off
	v_pk_fma_f32 v[88:89], v[88:89], v[136:137], v[236:237]
	v_pk_fma_f32 v[86:87], v[86:87], v[134:135], v[238:239]
	v_cvt_pk_bf16_f32 v232, v194, v195
	v_cvt_pk_bf16_f32 v233, v182, v183
	v_cvt_pk_bf16_f32 v234, v224, v225
	v_cvt_pk_bf16_f32 v235, v206, v207
	v_add_u32_e32 v206, 0xb0, v160
	v_ashrrev_i32_e32 v207, 31, v206
	v_cvt_pk_f16_f32 v239, v84, v85
	v_cvt_pk_f16_f32 v237, v88, v89
	v_cvt_pk_f16_f32 v238, v82, v83
	v_cvt_pk_f16_f32 v236, v86, v87
	v_pk_mul_f32 v[242:243], v[216:217], v[88:89]
	v_pk_mul_f32 v[244:245], v[218:219], v[86:87]
	v_pk_mul_f32 v[246:247], v[220:221], v[84:85]
	v_pk_mul_f32 v[248:249], v[222:223], v[82:83]
	global_store_dwordx4 v[214:215], v[232:235], off
	global_store_dwordx4 v[210:211], v[236:239], off
	v_lshlrev_b64 v[194:195], 11, v[206:207]
	v_cvt_pk_bf16_f32 v232, v244, v245
	v_cvt_pk_bf16_f32 v233, v242, v243
	v_cvt_pk_bf16_f32 v234, v248, v249
	v_cvt_pk_bf16_f32 v235, v246, v247
	global_store_dwordx4 v[208:209], v[232:235], off
	global_load_dwordx4 v[232:235], v[202:203], off nt
	v_lshl_add_u64 v[224:225], v[162:163], 0, v[194:195]
	global_load_dwordx4 v[160:163], v[224:225], off nt
	v_lshl_add_u64 v[182:183], v[158:159], 0, v[240:241]
	v_lshl_add_u64 v[194:195], v[158:159], 0, v[194:195]
	v_add_u32_e32 v158, s12, v200
	v_add_u32_e32 v200, s12, v206
	v_ashrrev_i32_e32 v159, 31, v158
	v_ashrrev_i32_e32 v201, 31, v200
	v_lshlrev_b64 v[158:159], 11, v[158:159]
	v_lshlrev_b64 v[200:201], 11, v[200:201]
	v_lshl_add_u64 v[158:159], s[20:21], 0, v[158:159]
	v_lshl_add_u64 v[200:201], s[20:21], 0, v[200:201]
	v_lshl_add_u64 v[206:207], v[158:159], 0, v[156:157]
	v_lshl_add_u64 v[200:201], v[200:201], 0, v[156:157]
	s_waitcnt vmcnt(1)
	v_cvt_f32_f16_e32 v158, v234
	v_cvt_f32_f16_sdwa v159, v234 dst_sel:DWORD dst_unused:UNUSED_PAD src0_sel:WORD_1
	v_cvt_f32_f16_e32 v156, v235
	v_cvt_f32_f16_sdwa v157, v235 dst_sel:DWORD dst_unused:UNUSED_PAD src0_sel:WORD_1
	v_cvt_f32_f16_e32 v234, v232
	v_cvt_f32_f16_sdwa v235, v232 dst_sel:DWORD dst_unused:UNUSED_PAD src0_sel:WORD_1
	v_cvt_f32_f16_e32 v232, v233
	v_cvt_f32_f16_sdwa v233, v233 dst_sel:DWORD dst_unused:UNUSED_PAD src0_sel:WORD_1
	s_waitcnt vmcnt(0)
	v_cvt_f32_f16_e32 v236, v162
	v_cvt_f32_f16_sdwa v237, v162 dst_sel:DWORD dst_unused:UNUSED_PAD src0_sel:WORD_1
	v_cvt_f32_f16_e32 v238, v163
	v_cvt_f32_f16_sdwa v239, v163 dst_sel:DWORD dst_unused:UNUSED_PAD src0_sel:WORD_1
	v_cvt_f32_f16_e32 v240, v160
	v_cvt_f32_f16_sdwa v241, v160 dst_sel:DWORD dst_unused:UNUSED_PAD src0_sel:WORD_1
	v_cvt_f32_f16_e32 v242, v161
	v_cvt_f32_f16_sdwa v243, v161 dst_sel:DWORD dst_unused:UNUSED_PAD src0_sel:WORD_1
	v_pk_fma_f32 v[160:161], v[80:81], v[136:137], v[232:233]
	v_pk_fma_f32 v[162:163], v[78:79], v[134:135], v[234:235]
	v_pk_fma_f32 v[156:157], v[76:77], v[132:133], v[156:157]
	v_pk_fma_f32 v[158:159], v[74:75], v[130:131], v[158:159]
	v_pk_fma_f32 v[74:75], v[68:69], v[132:133], v[238:239]
	v_pk_fma_f32 v[76:77], v[66:67], v[130:131], v[236:237]
	v_cvt_pk_f16_f32 v69, v156, v157
	v_cvt_pk_f16_f32 v67, v160, v161
	v_cvt_pk_f16_f32 v68, v158, v159
	v_cvt_pk_f16_f32 v66, v162, v163
	v_pk_fma_f32 v[78:79], v[72:73], v[136:137], v[242:243]
	v_pk_fma_f32 v[80:81], v[70:71], v[134:135], v[240:241]
	v_pk_mul_f32 v[130:131], v[216:217], v[160:161]
	v_pk_mul_f32 v[132:133], v[218:219], v[162:163]
	v_pk_mul_f32 v[134:135], v[220:221], v[156:157]
	v_pk_mul_f32 v[136:137], v[222:223], v[158:159]
	global_store_dwordx4 v[182:183], v[66:69], off
	v_cvt_pk_f16_f32 v73, v74, v75
	v_cvt_pk_f16_f32 v71, v78, v79
	v_cvt_pk_bf16_f32 v66, v132, v133
	v_cvt_pk_bf16_f32 v67, v130, v131
	v_cvt_pk_bf16_f32 v68, v136, v137
	v_cvt_pk_bf16_f32 v69, v134, v135
	v_cvt_pk_f16_f32 v72, v76, v77
	v_cvt_pk_f16_f32 v70, v80, v81
	v_pk_mul_f32 v[216:217], v[216:217], v[78:79]
	v_pk_mul_f32 v[218:219], v[218:219], v[80:81]
	v_pk_mul_f32 v[220:221], v[220:221], v[74:75]
	v_pk_mul_f32 v[222:223], v[222:223], v[76:77]
	global_store_dwordx4 v[206:207], v[66:69], off
	global_store_dwordx4 v[194:195], v[70:73], off
	s_nop 0
	v_cvt_pk_bf16_f32 v66, v218, v219
	v_cvt_pk_bf16_f32 v67, v216, v217
	v_cvt_pk_bf16_f32 v68, v222, v223
	v_cvt_pk_bf16_f32 v69, v220, v221
	global_store_dwordx4 v[200:201], v[66:69], off
	global_load_dwordx4 v[130:133], v[172:173], off offset:512
	global_load_dwordx4 v[134:137], v[172:173], off offset:528
	s_nop 0
	global_load_dwordx4 v[172:175], v[174:175], off offset:256 nt
	s_nop 0
	global_load_dwordx4 v[216:219], v[178:179], off offset:256 nt
	v_or_b32_e32 v66, 0x80, v166
	v_ashrrev_i32_e32 v67, 31, v66
	v_lshl_add_u64 v[66:67], v[66:67], 2, s[16:17]
	global_load_dwordx4 v[220:223], v[66:67], off
	global_load_dwordx4 v[232:235], v[66:67], off offset:16
	global_load_dwordx4 v[70:73], v[176:177], off offset:512
	s_nop 0
	global_load_dwordx4 v[66:69], v[176:177], off offset:528
	s_waitcnt vmcnt(7)
	v_pk_add_f32 v[132:133], v[132:133], 1.0 op_sel_hi:[1,0]
	v_pk_add_f32 v[166:167], v[130:131], 1.0 op_sel_hi:[1,0]
	s_waitcnt vmcnt(5)
	v_cvt_f32_f16_e32 v178, v174
	v_cvt_f32_f16_sdwa v179, v174 dst_sel:DWORD dst_unused:UNUSED_PAD src0_sel:WORD_1
	v_cvt_f32_f16_e32 v174, v175
	v_cvt_f32_f16_sdwa v175, v175 dst_sel:DWORD dst_unused:UNUSED_PAD src0_sel:WORD_1
	v_cvt_f32_f16_e32 v236, v172
	v_cvt_f32_f16_sdwa v237, v172 dst_sel:DWORD dst_unused:UNUSED_PAD src0_sel:WORD_1
	v_cvt_f32_f16_e32 v172, v173
	v_cvt_f32_f16_sdwa v173, v173 dst_sel:DWORD dst_unused:UNUSED_PAD src0_sel:WORD_1
	s_waitcnt vmcnt(4)
	v_cvt_f32_f16_e32 v238, v218
	v_cvt_f32_f16_sdwa v239, v218 dst_sel:DWORD dst_unused:UNUSED_PAD src0_sel:WORD_1
	v_cvt_f32_f16_e32 v218, v219
	v_cvt_f32_f16_sdwa v219, v219 dst_sel:DWORD dst_unused:UNUSED_PAD src0_sel:WORD_1
	v_cvt_f32_f16_e32 v240, v216
	v_cvt_f32_f16_sdwa v241, v216 dst_sel:DWORD dst_unused:UNUSED_PAD src0_sel:WORD_1
	v_cvt_f32_f16_e32 v216, v217
	v_cvt_f32_f16_sdwa v217, v217 dst_sel:DWORD dst_unused:UNUSED_PAD src0_sel:WORD_1
	v_pk_add_f32 v[136:137], v[136:137], 1.0 op_sel_hi:[1,0]
	v_pk_add_f32 v[176:177], v[134:135], 1.0 op_sel_hi:[1,0]
	s_waitcnt vmcnt(3)
	v_pk_mul_f32 v[130:131], v[222:223], v[132:133]
	s_waitcnt vmcnt(1)
	v_pk_fma_f32 v[64:65], v[64:65], v[72:73], v[172:173]
	v_pk_fma_f32 v[62:63], v[62:63], v[70:71], v[236:237]
	s_waitcnt vmcnt(0)
	v_pk_fma_f32 v[60:61], v[60:61], v[68:69], v[174:175]
	v_pk_fma_f32 v[58:59], v[58:59], v[66:67], v[178:179]
	v_pk_mul_f32 v[132:133], v[220:221], v[166:167]
	v_pk_mul_f32 v[134:135], v[234:235], v[136:137]
	v_pk_mul_f32 v[136:137], v[232:233], v[176:177]
	v_cvt_pk_f16_f32 v175, v60, v61
	v_cvt_pk_f16_f32 v173, v64, v65
	v_cvt_pk_f16_f32 v174, v58, v59
	v_cvt_pk_f16_f32 v172, v62, v63
	v_pk_mul_f32 v[166:167], v[130:131], v[64:65]
	v_pk_fma_f32 v[56:57], v[56:57], v[72:73], v[216:217]
	v_pk_fma_f32 v[54:55], v[54:55], v[70:71], v[240:241]
	v_pk_fma_f32 v[52:53], v[52:53], v[68:69], v[218:219]
	v_pk_fma_f32 v[50:51], v[50:51], v[66:67], v[238:239]
	v_pk_mul_f32 v[216:217], v[132:133], v[62:63]
	v_pk_mul_f32 v[218:219], v[134:135], v[60:61]
	v_pk_mul_f32 v[220:221], v[136:137], v[58:59]
	global_store_dwordx4 v[164:165], v[172:175], off offset:256
	v_cvt_pk_bf16_f32 v164, v216, v217
	v_cvt_pk_bf16_f32 v165, v166, v167
	v_cvt_pk_bf16_f32 v166, v220, v221
	v_cvt_pk_bf16_f32 v167, v218, v219
	v_cvt_pk_f16_f32 v179, v52, v53
	v_cvt_pk_f16_f32 v177, v56, v57
	v_cvt_pk_f16_f32 v178, v50, v51
	v_cvt_pk_f16_f32 v176, v54, v55
	v_pk_mul_f32 v[222:223], v[130:131], v[56:57]
	v_pk_mul_f32 v[232:233], v[132:133], v[54:55]
	v_pk_mul_f32 v[234:235], v[134:135], v[52:53]
	v_pk_mul_f32 v[236:237], v[136:137], v[50:51]
	global_store_dwordx4 v[168:169], v[164:167], off offset:256
	global_store_dwordx4 v[180:181], v[176:179], off offset:256
	v_mul_f32_e32 v63, v63, v63
	v_cvt_pk_bf16_f32 v164, v232, v233
	v_cvt_pk_bf16_f32 v165, v222, v223
	v_cvt_pk_bf16_f32 v166, v236, v237
	v_cvt_pk_bf16_f32 v167, v234, v235
	global_store_dwordx4 v[186:187], v[164:167], off offset:256
	global_load_dwordx4 v[164:167], v[188:189], off offset:256 nt
	s_nop 0
	global_load_dwordx4 v[172:175], v[190:191], off offset:256 nt
	v_mul_f32_e32 v65, v65, v65
	v_mul_f32_e32 v59, v59, v59
	v_mul_f32_e32 v61, v61, v61
	v_fmac_f32_e32 v63, v62, v62
	v_fmac_f32_e32 v65, v64, v64
	v_fmac_f32_e32 v59, v58, v58
	v_fmac_f32_e32 v61, v60, v60
	v_add_f32_e32 v58, v63, v65
	v_add_f32_e32 v59, v59, v61
	v_add_f32_e32 v58, v58, v59
	v_add_f32_e32 v59, v122, v58
	v_xor_b32_e32 v58, 32, v231
	s_waitcnt vmcnt(1)
	v_cvt_f32_f16_e32 v168, v166
	v_cvt_f32_f16_sdwa v169, v166 dst_sel:DWORD dst_unused:UNUSED_PAD src0_sel:WORD_1
	v_cvt_f32_f16_e32 v166, v167
	v_cvt_f32_f16_sdwa v167, v167 dst_sel:DWORD dst_unused:UNUSED_PAD src0_sel:WORD_1
	v_cvt_f32_f16_e32 v176, v164
	v_cvt_f32_f16_sdwa v177, v164 dst_sel:DWORD dst_unused:UNUSED_PAD src0_sel:WORD_1
	v_cvt_f32_f16_e32 v164, v165
	v_cvt_f32_f16_sdwa v165, v165 dst_sel:DWORD dst_unused:UNUSED_PAD src0_sel:WORD_1
	s_waitcnt vmcnt(0)
	v_cvt_f32_f16_e32 v178, v174
	v_cvt_f32_f16_sdwa v179, v174 dst_sel:DWORD dst_unused:UNUSED_PAD src0_sel:WORD_1
	v_cvt_f32_f16_e32 v174, v175
	v_cvt_f32_f16_sdwa v175, v175 dst_sel:DWORD dst_unused:UNUSED_PAD src0_sel:WORD_1
	v_cvt_f32_f16_e32 v180, v172
	v_cvt_f32_f16_sdwa v181, v172 dst_sel:DWORD dst_unused:UNUSED_PAD src0_sel:WORD_1
	v_cvt_f32_f16_e32 v172, v173
	v_cvt_f32_f16_sdwa v173, v173 dst_sel:DWORD dst_unused:UNUSED_PAD src0_sel:WORD_1
	v_pk_fma_f32 v[48:49], v[48:49], v[72:73], v[164:165]
	v_pk_fma_f32 v[46:47], v[46:47], v[70:71], v[176:177]
	v_pk_fma_f32 v[44:45], v[44:45], v[68:69], v[166:167]
	v_pk_fma_f32 v[42:43], v[42:43], v[66:67], v[168:169]
	v_cvt_pk_f16_f32 v167, v44, v45
	v_cvt_pk_f16_f32 v165, v48, v49
	v_cvt_pk_f16_f32 v166, v42, v43
	v_cvt_pk_f16_f32 v164, v46, v47
	v_pk_fma_f32 v[40:41], v[40:41], v[72:73], v[172:173]
	v_pk_fma_f32 v[38:39], v[38:39], v[70:71], v[180:181]
	v_pk_fma_f32 v[36:37], v[36:37], v[68:69], v[174:175]
	v_pk_fma_f32 v[34:35], v[34:35], v[66:67], v[178:179]
	v_pk_mul_f32 v[168:169], v[130:131], v[48:49]
	v_pk_mul_f32 v[176:177], v[132:133], v[46:47]
	v_pk_mul_f32 v[178:179], v[134:135], v[44:45]
	v_pk_mul_f32 v[180:181], v[136:137], v[42:43]
	global_store_dwordx4 v[170:171], v[164:167], off offset:256
	v_cvt_pk_f16_f32 v175, v36, v37
	v_cvt_pk_f16_f32 v173, v40, v41
	v_cvt_pk_bf16_f32 v164, v176, v177
	v_cvt_pk_bf16_f32 v165, v168, v169
	v_cvt_pk_bf16_f32 v166, v180, v181
	v_cvt_pk_bf16_f32 v167, v178, v179
	v_cvt_pk_f16_f32 v174, v34, v35
	v_cvt_pk_f16_f32 v172, v38, v39
	v_pk_mul_f32 v[186:187], v[130:131], v[40:41]
	v_pk_mul_f32 v[188:189], v[132:133], v[38:39]
	v_pk_mul_f32 v[190:191], v[134:135], v[36:37]
	v_pk_mul_f32 v[216:217], v[136:137], v[34:35]
	global_store_dwordx4 v[192:193], v[164:167], off offset:256
	global_store_dwordx4 v[184:185], v[172:175], off offset:256
	s_nop 0
	v_cvt_pk_bf16_f32 v164, v188, v189
	v_cvt_pk_bf16_f32 v165, v186, v187
	v_cvt_pk_bf16_f32 v166, v216, v217
	v_cvt_pk_bf16_f32 v167, v190, v191
	global_store_dwordx4 v[196:197], v[164:167], off offset:256
	global_load_dwordx4 v[164:167], v[198:199], off offset:256 nt
	s_nop 0
	global_load_dwordx4 v[168:171], v[204:205], off offset:256 nt
	s_waitcnt vmcnt(1)
	v_cvt_f32_f16_e32 v172, v166
	v_cvt_f32_f16_sdwa v173, v166 dst_sel:DWORD dst_unused:UNUSED_PAD src0_sel:WORD_1
	v_cvt_f32_f16_e32 v166, v167
	v_cvt_f32_f16_sdwa v167, v167 dst_sel:DWORD dst_unused:UNUSED_PAD src0_sel:WORD_1
	v_cvt_f32_f16_e32 v174, v164
	v_cvt_f32_f16_sdwa v175, v164 dst_sel:DWORD dst_unused:UNUSED_PAD src0_sel:WORD_1
	v_cvt_f32_f16_e32 v164, v165
	v_cvt_f32_f16_sdwa v165, v165 dst_sel:DWORD dst_unused:UNUSED_PAD src0_sel:WORD_1
	s_waitcnt vmcnt(0)
	v_cvt_f32_f16_e32 v176, v170
	v_cvt_f32_f16_sdwa v177, v170 dst_sel:DWORD dst_unused:UNUSED_PAD src0_sel:WORD_1
	v_cvt_f32_f16_e32 v170, v171
	v_cvt_f32_f16_sdwa v171, v171 dst_sel:DWORD dst_unused:UNUSED_PAD src0_sel:WORD_1
	v_cvt_f32_f16_e32 v178, v168
	v_cvt_f32_f16_sdwa v179, v168 dst_sel:DWORD dst_unused:UNUSED_PAD src0_sel:WORD_1
	v_cvt_f32_f16_e32 v168, v169
	v_cvt_f32_f16_sdwa v169, v169 dst_sel:DWORD dst_unused:UNUSED_PAD src0_sel:WORD_1
	v_pk_fma_f32 v[32:33], v[32:33], v[72:73], v[164:165]
	v_pk_fma_f32 v[30:31], v[30:31], v[70:71], v[174:175]
	v_pk_fma_f32 v[28:29], v[28:29], v[68:69], v[166:167]
	v_pk_fma_f32 v[26:27], v[26:27], v[66:67], v[172:173]
	v_cvt_pk_f16_f32 v167, v28, v29
	v_cvt_pk_f16_f32 v165, v32, v33
	v_cvt_pk_f16_f32 v166, v26, v27
	v_cvt_pk_f16_f32 v164, v30, v31
	v_pk_fma_f32 v[24:25], v[24:25], v[72:73], v[168:169]
	v_pk_fma_f32 v[22:23], v[22:23], v[70:71], v[178:179]
	v_pk_fma_f32 v[20:21], v[20:21], v[68:69], v[170:171]
	v_pk_fma_f32 v[18:19], v[18:19], v[66:67], v[176:177]
	v_pk_mul_f32 v[172:173], v[130:131], v[32:33]
	v_pk_mul_f32 v[174:175], v[132:133], v[30:31]
	v_pk_mul_f32 v[176:177], v[134:135], v[28:29]
	v_pk_mul_f32 v[178:179], v[136:137], v[26:27]
	global_store_dwordx4 v[212:213], v[164:167], off offset:256
	v_cvt_pk_f16_f32 v171, v20, v21
	v_cvt_pk_f16_f32 v169, v24, v25
	v_cvt_pk_bf16_f32 v164, v174, v175
	v_cvt_pk_bf16_f32 v165, v172, v173
	v_cvt_pk_bf16_f32 v166, v178, v179
	v_cvt_pk_bf16_f32 v167, v176, v177
	v_cvt_pk_f16_f32 v170, v18, v19
	v_cvt_pk_f16_f32 v168, v22, v23
	v_pk_mul_f32 v[180:181], v[130:131], v[24:25]
	v_pk_mul_f32 v[184:185], v[132:133], v[22:23]
	v_pk_mul_f32 v[186:187], v[134:135], v[20:21]
	v_pk_mul_f32 v[188:189], v[136:137], v[18:19]
	global_store_dwordx4 v[214:215], v[164:167], off offset:256
	global_store_dwordx4 v[210:211], v[168:171], off offset:256
	s_nop 0
	v_cvt_pk_bf16_f32 v164, v184, v185
	v_cvt_pk_bf16_f32 v165, v180, v181
	v_cvt_pk_bf16_f32 v166, v188, v189
	v_cvt_pk_bf16_f32 v167, v186, v187
	global_store_dwordx4 v[208:209], v[164:167], off offset:256
	global_load_dwordx4 v[166:169], v[202:203], off offset:256 nt
	s_nop 0
	global_load_dwordx4 v[170:173], v[224:225], off offset:256 nt
	v_and_b32_e32 v165, 64, v231
	v_xor_b32_e32 v164, 16, v231
	v_add_u32_e32 v165, 64, v165
	v_cmp_lt_i32_e32 vcc, v164, v165
	s_waitcnt vmcnt(1)
	v_cvt_f32_f16_e32 v62, v168
	v_cndmask_b32_e32 v164, v231, v164, vcc
	v_lshlrev_b32_e32 v164, 2, v164
	ds_bpermute_b32 v60, v164, v59
	v_cmp_lt_i32_e32 vcc, v58, v165
	v_cvt_f32_f16_sdwa v63, v168 dst_sel:DWORD dst_unused:UNUSED_PAD src0_sel:WORD_1
	v_cvt_f32_f16_e32 v64, v169
	v_cndmask_b32_e32 v58, v231, v58, vcc
	v_cvt_f32_f16_sdwa v65, v169 dst_sel:DWORD dst_unused:UNUSED_PAD src0_sel:WORD_1
	v_cvt_f32_f16_e32 v122, v166
	v_cvt_f32_f16_sdwa v123, v166 dst_sel:DWORD dst_unused:UNUSED_PAD src0_sel:WORD_1
	v_cvt_f32_f16_e32 v124, v167
	v_cvt_f32_f16_sdwa v125, v167 dst_sel:DWORD dst_unused:UNUSED_PAD src0_sel:WORD_1
	v_lshlrev_b32_e32 v58, 2, v58
	s_waitcnt lgkmcnt(0)
	v_add_f32_e32 v59, v59, v60
	ds_bpermute_b32 v60, v58, v59
	s_waitcnt vmcnt(0)
	v_cvt_f32_f16_e32 v126, v172
	v_cvt_f32_f16_sdwa v127, v172 dst_sel:DWORD dst_unused:UNUSED_PAD src0_sel:WORD_1
	v_cvt_f32_f16_e32 v128, v173
	v_cvt_f32_f16_sdwa v129, v173 dst_sel:DWORD dst_unused:UNUSED_PAD src0_sel:WORD_1
	v_cvt_f32_f16_e32 v166, v170
	v_cvt_f32_f16_sdwa v167, v170 dst_sel:DWORD dst_unused:UNUSED_PAD src0_sel:WORD_1
	v_cvt_f32_f16_e32 v168, v171
	v_cvt_f32_f16_sdwa v169, v171 dst_sel:DWORD dst_unused:UNUSED_PAD src0_sel:WORD_1
	v_pk_fma_f32 v[16:17], v[16:17], v[72:73], v[124:125]
	v_pk_fma_f32 v[14:15], v[14:15], v[70:71], v[122:123]
	v_pk_fma_f32 v[12:13], v[12:13], v[68:69], v[64:65]
	v_pk_fma_f32 v[10:11], v[10:11], v[66:67], v[62:63]
	v_cvt_pk_f16_f32 v65, v12, v13
	v_cvt_pk_f16_f32 v63, v16, v17
	v_cvt_pk_f16_f32 v64, v10, v11
	v_cvt_pk_f16_f32 v62, v14, v15
	v_pk_fma_f32 v[8:9], v[8:9], v[72:73], v[168:169]
	v_pk_fma_f32 v[6:7], v[6:7], v[70:71], v[166:167]
	v_pk_fma_f32 v[4:5], v[4:5], v[68:69], v[128:129]
	v_pk_fma_f32 v[2:3], v[2:3], v[66:67], v[126:127]
	v_pk_mul_f32 v[70:71], v[130:131], v[16:17]
	v_pk_mul_f32 v[72:73], v[132:133], v[14:15]
	v_pk_mul_f32 v[122:123], v[134:135], v[12:13]
	v_pk_mul_f32 v[124:125], v[136:137], v[10:11]
	global_store_dwordx4 v[182:183], v[62:65], off offset:256
	v_cvt_pk_f16_f32 v69, v4, v5
	v_cvt_pk_f16_f32 v67, v8, v9
	v_cvt_pk_bf16_f32 v62, v72, v73
	v_cvt_pk_bf16_f32 v63, v70, v71
	v_cvt_pk_bf16_f32 v64, v124, v125
	v_cvt_pk_bf16_f32 v65, v122, v123
	v_cvt_pk_f16_f32 v68, v2, v3
	v_cvt_pk_f16_f32 v66, v6, v7
	v_pk_mul_f32 v[126:127], v[130:131], v[8:9]
	v_pk_mul_f32 v[128:129], v[132:133], v[6:7]
	v_pk_mul_f32 v[130:131], v[134:135], v[4:5]
	v_pk_mul_f32 v[132:133], v[136:137], v[2:3]
	global_store_dwordx4 v[206:207], v[62:65], off offset:256
	global_store_dwordx4 v[194:195], v[66:69], off offset:256
	s_nop 0
	v_cvt_pk_bf16_f32 v62, v128, v129
	v_cvt_pk_bf16_f32 v63, v126, v127
	v_cvt_pk_bf16_f32 v64, v132, v133
	v_cvt_pk_bf16_f32 v65, v130, v131
	global_store_dwordx4 v[200:201], v[62:65], off offset:256
	s_and_saveexec_b64 s[68:69], s[6:7]
	s_cbranch_execz .LBB0_907
	v_lshl_add_u64 v[62:63], v[154:155], 2, s[28:29]
	s_waitcnt lgkmcnt(0)
	v_add_f32_e32 v59, v59, v60
	global_atomic_add_f32 v[62:63], v59, off

.LBB0_991:
	ds_read_b128 v[34:37], v184
	ds_read_b128 v[38:41], v184 offset:1024
	ds_read_b128 v[42:45], v184 offset:2048
	ds_read_b128 v[46:49], v184 offset:3072
	ds_read_b128 v[166:169], v185
	ds_read_b128 v[170:173], v185 offset:1024
	ds_read_b128 v[190:193], v185 offset:2048
	ds_read_b128 v[194:197], v185 offset:3072
	s_add_u32 s3, s0, 0xfffc0080
	s_addc_u32 s13, s1, -1
	s_cmp_eq_u32 s12, 12
	s_cselect_b32 s87, s11, s13
	s_cselect_b32 s86, s23, s3
	s_cselect_b32 s85, s48, s77
	s_cselect_b32 s84, s49, s63
	s_nop 0
	s_add_i32 m0, s67, 0xc000
	ds_read_b128 v[198:201], v186
	ds_read_b128 v[202:205], v186 offset:1024
	ds_read_b128 v[206:209], v186 offset:2048
	ds_read_b128 v[210:213], v186 offset:3072
	ds_read_b128 v[214:217], v186 offset:4096
	ds_read_b128 v[218:221], v186 offset:5120
	ds_read_b128 v[222:225], v186 offset:6144
	ds_read_b128 v[226:229], v186 offset:7168
	global_load_lds_dwordx4 v158, s[0:1]
	s_nop 0
	s_add_i32 m0, s67, 0xe000
	s_nop 0
	global_load_lds_dwordx4 v160, s[0:1]
	s_waitcnt vmcnt(8)
	s_waitcnt lgkmcnt(0)
	s_barrier
	s_setprio 1
	s_waitcnt lgkmcnt(0)
	v_mfma_f32_16x16x32_bf16 v[142:145], v[34:37], v[198:201], v[142:145]
	v_mfma_f32_16x16x32_bf16 v[138:141], v[42:45], v[198:201], v[138:141]
	v_mfma_f32_16x16x32_bf16 v[126:129], v[34:37], v[206:209], v[126:129]
	v_mfma_f32_16x16x32_bf16 v[122:125], v[42:45], v[206:209], v[122:125]
	v_mfma_f32_16x16x32_bf16 v[110:113], v[34:37], v[214:217], v[110:113]
	v_mfma_f32_16x16x32_bf16 v[106:109], v[42:45], v[214:217], v[106:109]
	v_mfma_f32_16x16x32_bf16 v[94:97], v[34:37], v[222:225], v[94:97]
	v_mfma_f32_16x16x32_bf16 v[90:93], v[42:45], v[222:225], v[90:93]
	v_mfma_f32_16x16x32_bf16 v[142:145], v[38:41], v[202:205], v[142:145]
	v_mfma_f32_16x16x32_bf16 v[138:141], v[46:49], v[202:205], v[138:141]
	v_mfma_f32_16x16x32_bf16 v[126:129], v[38:41], v[210:213], v[126:129]
	v_mfma_f32_16x16x32_bf16 v[122:125], v[46:49], v[210:213], v[122:125]
	v_mfma_f32_16x16x32_bf16 v[110:113], v[38:41], v[218:221], v[110:113]
	v_mfma_f32_16x16x32_bf16 v[106:109], v[46:49], v[218:221], v[106:109]
	v_mfma_f32_16x16x32_bf16 v[94:97], v[38:41], v[226:229], v[94:97]
	v_mfma_f32_16x16x32_bf16 v[90:93], v[46:49], v[226:229], v[90:93]
	s_setprio 0
	s_setprio 1
	v_mfma_f32_16x16x32_bf16 v[134:137], v[166:169], v[198:201], v[134:137]
	v_mfma_f32_16x16x32_bf16 v[130:133], v[190:193], v[198:201], v[130:133]
	v_mfma_f32_16x16x32_bf16 v[118:121], v[166:169], v[206:209], v[118:121]
	v_mfma_f32_16x16x32_bf16 v[114:117], v[190:193], v[206:209], v[114:117]
	v_mfma_f32_16x16x32_bf16 v[102:105], v[166:169], v[214:217], v[102:105]
	v_mfma_f32_16x16x32_bf16 v[98:101], v[190:193], v[214:217], v[98:101]
	v_mfma_f32_16x16x32_bf16 v[86:89], v[166:169], v[222:225], v[86:89]
	v_mfma_f32_16x16x32_bf16 v[82:85], v[190:193], v[222:225], v[82:85]
	v_mfma_f32_16x16x32_bf16 v[134:137], v[170:173], v[202:205], v[134:137]
	v_mfma_f32_16x16x32_bf16 v[130:133], v[194:197], v[202:205], v[130:133]
	v_mfma_f32_16x16x32_bf16 v[118:121], v[170:173], v[210:213], v[118:121]
	v_mfma_f32_16x16x32_bf16 v[114:117], v[194:197], v[210:213], v[114:117]
	v_mfma_f32_16x16x32_bf16 v[102:105], v[170:173], v[218:221], v[102:105]
	v_mfma_f32_16x16x32_bf16 v[98:101], v[194:197], v[218:221], v[98:101]
	v_mfma_f32_16x16x32_bf16 v[86:89], v[170:173], v[226:229], v[86:89]
	v_mfma_f32_16x16x32_bf16 v[82:85], v[194:197], v[226:229], v[82:85]
	s_setprio 0
	s_barrier
	s_add_i32 s3, s61, s66
	s_nop 0
	s_mov_b32 m0, s3
	ds_read_b128 v[198:201], v186 offset:16384
	ds_read_b128 v[202:205], v186 offset:17408
	ds_read_b128 v[206:209], v186 offset:18432
	ds_read_b128 v[210:213], v186 offset:19456
	ds_read_b128 v[214:217], v186 offset:20480
	ds_read_b128 v[218:221], v186 offset:21504
	ds_read_b128 v[222:225], v186 offset:22528
	ds_read_b128 v[226:229], v186 offset:23552
	global_load_lds_dwordx4 v150, s[84:85]
	s_add_i32 m0, s3, 0x2000
	s_add_u32 s24, s84, 0x40000
	s_nop 0
	s_addc_u32 s25, s85, 0
	s_add_i32 s3, s62, s66
	global_load_lds_dwordx4 v154, s[84:85]
	s_nop 0
	s_mov_b32 m0, s3
	s_nop 0
	global_load_lds_dwordx4 v150, s[24:25]
	s_nop 0
	s_add_i32 m0, s3, 0x2000
	s_nop 0
	global_load_lds_dwordx4 v154, s[24:25]
	s_nop 0
	s_mov_b32 m0, s67
	s_nop 0
	global_load_lds_dwordx4 v148, s[86:87]
	s_mov_b32 m0, s88
	s_nop 0
	global_load_lds_dwordx4 v152, s[86:87]
	s_waitcnt vmcnt(8)
	s_waitcnt lgkmcnt(0)
	s_barrier
	s_setprio 1
	s_waitcnt lgkmcnt(0)
	v_mfma_f32_16x16x32_bf16 v[78:81], v[34:37], v[198:201], v[78:81]
	v_mfma_f32_16x16x32_bf16 v[74:77], v[42:45], v[198:201], v[74:77]
	v_mfma_f32_16x16x32_bf16 v[62:65], v[34:37], v[206:209], v[62:65]
	v_mfma_f32_16x16x32_bf16 v[58:61], v[42:45], v[206:209], v[58:61]
	v_mfma_f32_16x16x32_bf16 v[30:33], v[34:37], v[214:217], v[30:33]
	v_mfma_f32_16x16x32_bf16 v[26:29], v[42:45], v[214:217], v[26:29]
	v_mfma_f32_16x16x32_bf16 v[14:17], v[34:37], v[222:225], v[14:17]
	v_mfma_f32_16x16x32_bf16 v[10:13], v[42:45], v[222:225], v[10:13]
	v_mfma_f32_16x16x32_bf16 v[78:81], v[38:41], v[202:205], v[78:81]
	v_mfma_f32_16x16x32_bf16 v[74:77], v[46:49], v[202:205], v[74:77]
	v_mfma_f32_16x16x32_bf16 v[62:65], v[38:41], v[210:213], v[62:65]
	v_mfma_f32_16x16x32_bf16 v[58:61], v[46:49], v[210:213], v[58:61]
	v_mfma_f32_16x16x32_bf16 v[30:33], v[38:41], v[218:221], v[30:33]
	v_mfma_f32_16x16x32_bf16 v[26:29], v[46:49], v[218:221], v[26:29]
	v_mfma_f32_16x16x32_bf16 v[14:17], v[38:41], v[226:229], v[14:17]
	v_mfma_f32_16x16x32_bf16 v[10:13], v[46:49], v[226:229], v[10:13]
	s_setprio 0
	s_setprio 1
	v_mfma_f32_16x16x32_bf16 v[22:25], v[166:169], v[214:217], v[22:25]
	v_mfma_f32_16x16x32_bf16 v[18:21], v[190:193], v[214:217], v[18:21]
	v_mfma_f32_16x16x32_bf16 v[6:9], v[166:169], v[222:225], v[6:9]
	v_mfma_f32_16x16x32_bf16 v[2:5], v[190:193], v[222:225], v[2:5]
	v_mfma_f32_16x16x32_bf16 v[34:37], v[166:169], v[198:201], v[70:73]
	v_mfma_f32_16x16x32_bf16 v[38:41], v[190:193], v[198:201], v[66:69]
	v_mfma_f32_16x16x32_bf16 v[42:45], v[166:169], v[206:209], v[54:57]
	v_mfma_f32_16x16x32_bf16 v[46:49], v[190:193], v[206:209], v[50:53]
	v_mfma_f32_16x16x32_bf16 v[22:25], v[170:173], v[218:221], v[22:25]
	v_mfma_f32_16x16x32_bf16 v[18:21], v[194:197], v[218:221], v[18:21]
	v_mfma_f32_16x16x32_bf16 v[6:9], v[170:173], v[226:229], v[6:9]
	v_mfma_f32_16x16x32_bf16 v[2:5], v[194:197], v[226:229], v[2:5]
	v_mfma_f32_16x16x32_bf16 v[34:37], v[170:173], v[202:205], v[34:37]
	v_mfma_f32_16x16x32_bf16 v[38:41], v[194:197], v[202:205], v[38:41]
	v_mfma_f32_16x16x32_bf16 v[42:45], v[170:173], v[210:213], v[42:45]
	v_mfma_f32_16x16x32_bf16 v[46:49], v[194:197], v[210:213], v[46:49]
	s_setprio 0
	s_barrier
	s_add_i32 s3, 0, 0x18000
	s_add_i32 s13, 0, 0x1c000
	v_add_u32_e32 v70, s3, v175
	v_add_u32_e32 v194, s13, v175
	ds_read_b128 v[50:53], v70
	ds_read_b128 v[54:57], v70 offset:1024
	ds_read_b128 v[66:69], v70 offset:2048
	ds_read_b128 v[70:73], v70 offset:3072
	ds_read_b128 v[166:169], v194
	ds_read_b128 v[170:173], v194 offset:1024
	ds_read_b128 v[190:193], v194 offset:2048
	ds_read_b128 v[194:197], v194 offset:3072
	s_add_u32 s24, s86, 0x40000
	s_addc_u32 s25, s87, 0
	s_mov_b32 m0, s89
	s_nop 0
	ds_read_b128 v[198:201], v186 offset:32768
	ds_read_b128 v[202:205], v186 offset:33792
	ds_read_b128 v[206:209], v186 offset:34816
	ds_read_b128 v[210:213], v186 offset:35840
	ds_read_b128 v[214:217], v186 offset:36864
	ds_read_b128 v[218:221], v186 offset:37888
	ds_read_b128 v[222:225], v186 offset:38912
	ds_read_b128 v[226:229], v186 offset:39936
	global_load_lds_dwordx4 v148, s[24:25]
	s_nop 0
	s_mov_b32 m0, s90
	s_nop 0
	global_load_lds_dwordx4 v152, s[24:25]
	s_waitcnt vmcnt(8)
	s_waitcnt lgkmcnt(0)
	s_barrier
	s_setprio 1
	s_waitcnt lgkmcnt(0)
	v_mfma_f32_16x16x32_bf16 v[142:145], v[50:53], v[198:201], v[142:145]
	v_mfma_f32_16x16x32_bf16 v[138:141], v[66:69], v[198:201], v[138:141]
	v_mfma_f32_16x16x32_bf16 v[126:129], v[50:53], v[206:209], v[126:129]
	v_mfma_f32_16x16x32_bf16 v[122:125], v[66:69], v[206:209], v[122:125]
	v_mfma_f32_16x16x32_bf16 v[110:113], v[50:53], v[214:217], v[110:113]
	v_mfma_f32_16x16x32_bf16 v[106:109], v[66:69], v[214:217], v[106:109]
	v_mfma_f32_16x16x32_bf16 v[94:97], v[50:53], v[222:225], v[94:97]
	v_mfma_f32_16x16x32_bf16 v[90:93], v[66:69], v[222:225], v[90:93]
	v_mfma_f32_16x16x32_bf16 v[142:145], v[54:57], v[202:205], v[142:145]
	v_mfma_f32_16x16x32_bf16 v[138:141], v[70:73], v[202:205], v[138:141]
	v_mfma_f32_16x16x32_bf16 v[126:129], v[54:57], v[210:213], v[126:129]
	v_mfma_f32_16x16x32_bf16 v[122:125], v[70:73], v[210:213], v[122:125]
	v_mfma_f32_16x16x32_bf16 v[110:113], v[54:57], v[218:221], v[110:113]
	v_mfma_f32_16x16x32_bf16 v[106:109], v[70:73], v[218:221], v[106:109]
	v_mfma_f32_16x16x32_bf16 v[94:97], v[54:57], v[226:229], v[94:97]
	v_mfma_f32_16x16x32_bf16 v[90:93], v[70:73], v[226:229], v[90:93]
	s_setprio 0
	s_setprio 1
	v_mfma_f32_16x16x32_bf16 v[134:137], v[166:169], v[198:201], v[134:137]
	v_mfma_f32_16x16x32_bf16 v[130:133], v[190:193], v[198:201], v[130:133]
	v_mfma_f32_16x16x32_bf16 v[118:121], v[166:169], v[206:209], v[118:121]
	v_mfma_f32_16x16x32_bf16 v[114:117], v[190:193], v[206:209], v[114:117]
	v_mfma_f32_16x16x32_bf16 v[102:105], v[166:169], v[214:217], v[102:105]
	v_mfma_f32_16x16x32_bf16 v[98:101], v[190:193], v[214:217], v[98:101]
	v_mfma_f32_16x16x32_bf16 v[86:89], v[166:169], v[222:225], v[86:89]
	v_mfma_f32_16x16x32_bf16 v[82:85], v[190:193], v[222:225], v[82:85]
	v_mfma_f32_16x16x32_bf16 v[134:137], v[170:173], v[202:205], v[134:137]
	v_mfma_f32_16x16x32_bf16 v[130:133], v[194:197], v[202:205], v[130:133]
	v_mfma_f32_16x16x32_bf16 v[118:121], v[170:173], v[210:213], v[118:121]
	v_mfma_f32_16x16x32_bf16 v[114:117], v[194:197], v[210:213], v[114:117]
	v_mfma_f32_16x16x32_bf16 v[102:105], v[170:173], v[218:221], v[102:105]
	v_mfma_f32_16x16x32_bf16 v[98:101], v[194:197], v[218:221], v[98:101]
	v_mfma_f32_16x16x32_bf16 v[86:89], v[170:173], v[226:229], v[86:89]
	v_mfma_f32_16x16x32_bf16 v[82:85], v[194:197], v[226:229], v[82:85]
	s_setprio 0
	s_barrier
	s_add_i32 s3, s3, s66
	s_nop 0
	s_mov_b32 m0, s3
	ds_read_b128 v[198:201], v186 offset:49152
	ds_read_b128 v[202:205], v186 offset:50176
	ds_read_b128 v[206:209], v186 offset:51200
	ds_read_b128 v[210:213], v186 offset:52224
	ds_read_b128 v[214:217], v186 offset:53248
	ds_read_b128 v[218:221], v186 offset:54272
	ds_read_b128 v[222:225], v186 offset:55296
	ds_read_b128 v[226:229], v186 offset:56320
	global_load_lds_dwordx4 v251, s[84:85]
	s_add_i32 m0, s3, 0x2000
	s_add_u32 s24, s84, 0x40080
	s_nop 0
	s_addc_u32 s25, s85, 0
	s_add_i32 s3, s13, s66
	global_load_lds_dwordx4 v252, s[84:85]
	s_nop 0
	s_mov_b32 m0, s3
	s_nop 0
	global_load_lds_dwordx4 v150, s[24:25]
	s_nop 0
	s_add_i32 m0, s3, 0x2000
	s_nop 0
	global_load_lds_dwordx4 v154, s[24:25]
	s_nop 0
	s_mov_b32 m0, s93
	s_nop 0
	global_load_lds_dwordx4 v253, s[86:87]
	s_nop 0
	s_mov_b32 m0, s44
	s_nop 0
	global_load_lds_dwordx4 v254, s[86:87]
	s_waitcnt vmcnt(8)
	s_waitcnt lgkmcnt(0)
	s_barrier
	s_setprio 1
	s_waitcnt lgkmcnt(0)
	v_mfma_f32_16x16x32_bf16 v[78:81], v[50:53], v[198:201], v[78:81]
	v_mfma_f32_16x16x32_bf16 v[74:77], v[66:69], v[198:201], v[74:77]
	v_mfma_f32_16x16x32_bf16 v[62:65], v[50:53], v[206:209], v[62:65]
	v_mfma_f32_16x16x32_bf16 v[58:61], v[66:69], v[206:209], v[58:61]
	v_mfma_f32_16x16x32_bf16 v[30:33], v[50:53], v[214:217], v[30:33]
	v_mfma_f32_16x16x32_bf16 v[26:29], v[66:69], v[214:217], v[26:29]
	v_mfma_f32_16x16x32_bf16 v[14:17], v[50:53], v[222:225], v[14:17]
	v_mfma_f32_16x16x32_bf16 v[10:13], v[66:69], v[222:225], v[10:13]
	v_mfma_f32_16x16x32_bf16 v[78:81], v[54:57], v[202:205], v[78:81]
	v_mfma_f32_16x16x32_bf16 v[74:77], v[70:73], v[202:205], v[74:77]
	v_mfma_f32_16x16x32_bf16 v[62:65], v[54:57], v[210:213], v[62:65]
	v_mfma_f32_16x16x32_bf16 v[58:61], v[70:73], v[210:213], v[58:61]
	v_mfma_f32_16x16x32_bf16 v[30:33], v[54:57], v[218:221], v[30:33]
	v_mfma_f32_16x16x32_bf16 v[26:29], v[70:73], v[218:221], v[26:29]
	v_mfma_f32_16x16x32_bf16 v[14:17], v[54:57], v[226:229], v[14:17]
	v_mfma_f32_16x16x32_bf16 v[10:13], v[70:73], v[226:229], v[10:13]
	s_setprio 0
	s_setprio 1
	v_mfma_f32_16x16x32_bf16 v[34:37], v[166:169], v[198:201], v[34:37]
	v_mfma_f32_16x16x32_bf16 v[70:73], v[170:173], v[202:205], v[34:37]
	v_mfma_f32_16x16x32_bf16 v[34:37], v[190:193], v[198:201], v[38:41]
	v_mfma_f32_16x16x32_bf16 v[66:69], v[194:197], v[202:205], v[34:37]
	v_mfma_f32_16x16x32_bf16 v[34:37], v[166:169], v[206:209], v[42:45]
	v_mfma_f32_16x16x32_bf16 v[54:57], v[170:173], v[210:213], v[34:37]
	v_mfma_f32_16x16x32_bf16 v[34:37], v[190:193], v[206:209], v[46:49]
	v_mfma_f32_16x16x32_bf16 v[22:25], v[166:169], v[214:217], v[22:25]
	v_mfma_f32_16x16x32_bf16 v[18:21], v[190:193], v[214:217], v[18:21]
	v_mfma_f32_16x16x32_bf16 v[6:9], v[166:169], v[222:225], v[6:9]
	v_mfma_f32_16x16x32_bf16 v[2:5], v[190:193], v[222:225], v[2:5]
	v_mfma_f32_16x16x32_bf16 v[50:53], v[194:197], v[210:213], v[34:37]
	v_mfma_f32_16x16x32_bf16 v[22:25], v[170:173], v[218:221], v[22:25]
	v_mfma_f32_16x16x32_bf16 v[18:21], v[194:197], v[218:221], v[18:21]
	v_mfma_f32_16x16x32_bf16 v[6:9], v[170:173], v[226:229], v[6:9]
	v_mfma_f32_16x16x32_bf16 v[2:5], v[194:197], v[226:229], v[2:5]
	s_setprio 0
	s_barrier
	s_add_i32 s12, s12, 2
	s_add_u32 s0, s0, 0x100
	s_addc_u32 s1, s1, 0
	s_add_u32 s63, s63, 0x100
	s_addc_u32 s77, s77, 0
	s_cmp_gt_u32 s12, 13
	s_cbranch_scc0 .LBB0_991
	s_and_b64 vcc, exec, s[74:75]
	s_cbranch_vccz .LBB0_994
	s_barrier

.LBB0_1479:
	ds_read_b128 v[98:101], v176
	ds_read_b128 v[102:105], v176 offset:1024
	ds_read_b128 v[106:109], v176 offset:2048
	ds_read_b128 v[110:113], v176 offset:3072
	ds_read_b128 v[182:185], v177
	ds_read_b128 v[186:189], v177 offset:1024
	ds_read_b128 v[190:193], v177 offset:2048
	ds_read_b128 v[194:197], v177 offset:3072
	s_add_u32 s13, s0, 0xfffc0080
	s_addc_u32 s44, s1, -1
	s_cmp_eq_u32 s12, 12
	s_cselect_b32 s47, s31, s44
	s_cselect_b32 s46, s43, s13
	s_cselect_b32 s45, s29, s69
	s_cselect_b32 s44, s67, s68
	s_nop 0
	s_add_i32 m0, s52, 0xc000
	ds_read_b128 v[198:201], v178
	ds_read_b128 v[202:205], v178 offset:1024
	ds_read_b128 v[206:209], v178 offset:2048
	ds_read_b128 v[210:213], v178 offset:3072
	ds_read_b128 v[214:217], v178 offset:4096
	ds_read_b128 v[218:221], v178 offset:5120
	ds_read_b128 v[222:225], v178 offset:6144
	ds_read_b128 v[226:229], v178 offset:7168
	global_load_lds_dwordx4 v158, s[0:1]
	s_nop 0
	s_add_i32 m0, s52, 0xe000
	s_nop 0
	global_load_lds_dwordx4 v160, s[0:1]
	s_waitcnt vmcnt(8)
	s_waitcnt lgkmcnt(0)
	s_barrier
	s_setprio 1
	s_waitcnt lgkmcnt(0)
	v_mfma_f32_16x16x32_bf16 v[142:145], v[98:101], v[198:201], v[142:145]
	v_mfma_f32_16x16x32_bf16 v[138:141], v[106:109], v[198:201], v[138:141]
	v_mfma_f32_16x16x32_bf16 v[126:129], v[98:101], v[206:209], v[126:129]
	v_mfma_f32_16x16x32_bf16 v[122:125], v[106:109], v[206:209], v[122:125]
	v_mfma_f32_16x16x32_bf16 v[94:97], v[98:101], v[214:217], v[94:97]
	v_mfma_f32_16x16x32_bf16 v[90:93], v[106:109], v[214:217], v[90:93]
	v_mfma_f32_16x16x32_bf16 v[78:81], v[98:101], v[222:225], v[78:81]
	v_mfma_f32_16x16x32_bf16 v[74:77], v[106:109], v[222:225], v[74:77]
	v_mfma_f32_16x16x32_bf16 v[142:145], v[102:105], v[202:205], v[142:145]
	v_mfma_f32_16x16x32_bf16 v[138:141], v[110:113], v[202:205], v[138:141]
	v_mfma_f32_16x16x32_bf16 v[126:129], v[102:105], v[210:213], v[126:129]
	v_mfma_f32_16x16x32_bf16 v[122:125], v[110:113], v[210:213], v[122:125]
	v_mfma_f32_16x16x32_bf16 v[94:97], v[102:105], v[218:221], v[94:97]
	v_mfma_f32_16x16x32_bf16 v[90:93], v[110:113], v[218:221], v[90:93]
	v_mfma_f32_16x16x32_bf16 v[78:81], v[102:105], v[226:229], v[78:81]
	v_mfma_f32_16x16x32_bf16 v[74:77], v[110:113], v[226:229], v[74:77]
	s_setprio 0
	s_setprio 1
	v_mfma_f32_16x16x32_bf16 v[134:137], v[182:185], v[198:201], v[134:137]
	v_mfma_f32_16x16x32_bf16 v[130:133], v[190:193], v[198:201], v[130:133]
	v_mfma_f32_16x16x32_bf16 v[118:121], v[182:185], v[206:209], v[118:121]
	v_mfma_f32_16x16x32_bf16 v[114:117], v[190:193], v[206:209], v[114:117]
	v_mfma_f32_16x16x32_bf16 v[86:89], v[182:185], v[214:217], v[86:89]
	v_mfma_f32_16x16x32_bf16 v[82:85], v[190:193], v[214:217], v[82:85]
	v_mfma_f32_16x16x32_bf16 v[70:73], v[182:185], v[222:225], v[70:73]
	v_mfma_f32_16x16x32_bf16 v[66:69], v[190:193], v[222:225], v[66:69]
	v_mfma_f32_16x16x32_bf16 v[134:137], v[186:189], v[202:205], v[134:137]
	v_mfma_f32_16x16x32_bf16 v[130:133], v[194:197], v[202:205], v[130:133]
	v_mfma_f32_16x16x32_bf16 v[118:121], v[186:189], v[210:213], v[118:121]
	v_mfma_f32_16x16x32_bf16 v[114:117], v[194:197], v[210:213], v[114:117]
	v_mfma_f32_16x16x32_bf16 v[86:89], v[186:189], v[218:221], v[86:89]
	v_mfma_f32_16x16x32_bf16 v[82:85], v[194:197], v[218:221], v[82:85]
	v_mfma_f32_16x16x32_bf16 v[70:73], v[186:189], v[226:229], v[70:73]
	v_mfma_f32_16x16x32_bf16 v[66:69], v[194:197], v[226:229], v[66:69]
	s_setprio 0
	s_barrier
	s_add_i32 s13, s61, s49
	s_nop 0
	s_mov_b32 m0, s13
	ds_read_b128 v[198:201], v178 offset:16384
	ds_read_b128 v[202:205], v178 offset:17408
	ds_read_b128 v[206:209], v178 offset:18432
	ds_read_b128 v[210:213], v178 offset:19456
	ds_read_b128 v[214:217], v178 offset:20480
	ds_read_b128 v[218:221], v178 offset:21504
	ds_read_b128 v[222:225], v178 offset:22528
	ds_read_b128 v[226:229], v178 offset:23552
	global_load_lds_dwordx4 v152, s[44:45]
	s_add_i32 m0, s13, 0x2000
	s_add_u32 s70, s44, 0x40000
	v_lshl_add_u64 v[232:233], s[44:45], 0, v[148:149]
	s_addc_u32 s71, s45, 0
	s_add_i32 s13, s62, s49
	global_load_lds_dwordx4 v148, s[44:45]
	s_nop 0
	s_mov_b32 m0, s13
	v_lshl_add_u64 v[236:237], s[46:47], 0, v[150:151]
	global_load_lds_dwordx4 v152, s[70:71]
	s_nop 0
	s_add_i32 m0, s13, 0x2000
	s_nop 0
	global_load_lds_dwordx4 v148, s[70:71]
	v_lshl_add_u64 v[234:235], s[46:47], 0, v[154:155]
	s_mov_b32 m0, s52
	s_nop 0
	global_load_lds_dwordx4 v154, s[46:47]
	s_mov_b32 m0, s53
	s_nop 0
	global_load_lds_dwordx4 v150, s[46:47]
	s_waitcnt vmcnt(8)
	s_waitcnt lgkmcnt(0)
	s_barrier
	s_setprio 1
	s_waitcnt lgkmcnt(0)
	v_mfma_f32_16x16x32_bf16 v[62:65], v[98:101], v[198:201], v[62:65]
	v_mfma_f32_16x16x32_bf16 v[58:61], v[106:109], v[198:201], v[58:61]
	v_mfma_f32_16x16x32_bf16 v[46:49], v[98:101], v[206:209], v[46:49]
	v_mfma_f32_16x16x32_bf16 v[42:45], v[106:109], v[206:209], v[42:45]
	v_mfma_f32_16x16x32_bf16 v[30:33], v[98:101], v[214:217], v[30:33]
	v_mfma_f32_16x16x32_bf16 v[26:29], v[106:109], v[214:217], v[26:29]
	v_mfma_f32_16x16x32_bf16 v[14:17], v[98:101], v[222:225], v[14:17]
	v_mfma_f32_16x16x32_bf16 v[10:13], v[106:109], v[222:225], v[10:13]
	v_mfma_f32_16x16x32_bf16 v[62:65], v[102:105], v[202:205], v[62:65]
	v_mfma_f32_16x16x32_bf16 v[58:61], v[110:113], v[202:205], v[58:61]
	v_mfma_f32_16x16x32_bf16 v[46:49], v[102:105], v[210:213], v[46:49]
	v_mfma_f32_16x16x32_bf16 v[42:45], v[110:113], v[210:213], v[42:45]
	v_mfma_f32_16x16x32_bf16 v[30:33], v[102:105], v[218:221], v[30:33]
	v_mfma_f32_16x16x32_bf16 v[26:29], v[110:113], v[218:221], v[26:29]
	v_mfma_f32_16x16x32_bf16 v[14:17], v[102:105], v[226:229], v[14:17]
	v_mfma_f32_16x16x32_bf16 v[10:13], v[110:113], v[226:229], v[10:13]
	s_setprio 0
	s_setprio 1
	v_mfma_f32_16x16x32_bf16 v[54:57], v[182:185], v[198:201], v[54:57]
	v_mfma_f32_16x16x32_bf16 v[50:53], v[190:193], v[198:201], v[50:53]
	v_mfma_f32_16x16x32_bf16 v[38:41], v[182:185], v[206:209], v[38:41]
	v_mfma_f32_16x16x32_bf16 v[34:37], v[190:193], v[206:209], v[34:37]
	v_mfma_f32_16x16x32_bf16 v[22:25], v[182:185], v[214:217], v[22:25]
	v_mfma_f32_16x16x32_bf16 v[18:21], v[190:193], v[214:217], v[18:21]
	v_mfma_f32_16x16x32_bf16 v[6:9], v[182:185], v[222:225], v[6:9]
	v_mfma_f32_16x16x32_bf16 v[2:5], v[190:193], v[222:225], v[2:5]
	v_mfma_f32_16x16x32_bf16 v[54:57], v[186:189], v[202:205], v[54:57]
	v_mfma_f32_16x16x32_bf16 v[50:53], v[194:197], v[202:205], v[50:53]
	v_mfma_f32_16x16x32_bf16 v[38:41], v[186:189], v[210:213], v[38:41]
	v_mfma_f32_16x16x32_bf16 v[34:37], v[194:197], v[210:213], v[34:37]
	v_mfma_f32_16x16x32_bf16 v[22:25], v[186:189], v[218:221], v[22:25]
	v_mfma_f32_16x16x32_bf16 v[18:21], v[194:197], v[218:221], v[18:21]
	v_mfma_f32_16x16x32_bf16 v[6:9], v[186:189], v[226:229], v[6:9]
	v_mfma_f32_16x16x32_bf16 v[2:5], v[194:197], v[226:229], v[2:5]
	s_setprio 0
	s_barrier
	s_add_i32 s13, 0, 0x18000
	s_add_i32 s70, 0, 0x1c000
	v_add_u32_e32 v110, s13, v167
	v_add_u32_e32 v181, s70, v167
	ds_read_b128 v[98:101], v110
	ds_read_b128 v[102:105], v110 offset:1024
	ds_read_b128 v[106:109], v110 offset:2048
	ds_read_b128 v[110:113], v110 offset:3072
	ds_read_b128 v[182:185], v181
	ds_read_b128 v[186:189], v181 offset:1024
	ds_read_b128 v[190:193], v181 offset:2048
	ds_read_b128 v[194:197], v181 offset:3072
	s_add_u32 s46, s46, 0x40000
	s_addc_u32 s47, s47, 0
	s_mov_b32 m0, s54
	s_nop 0
	ds_read_b128 v[198:201], v178 offset:32768
	ds_read_b128 v[202:205], v178 offset:33792
	ds_read_b128 v[206:209], v178 offset:34816
	ds_read_b128 v[210:213], v178 offset:35840
	ds_read_b128 v[214:217], v178 offset:36864
	ds_read_b128 v[218:221], v178 offset:37888
	ds_read_b128 v[222:225], v178 offset:38912
	ds_read_b128 v[226:229], v178 offset:39936
	global_load_lds_dwordx4 v154, s[46:47]
	s_nop 0
	s_mov_b32 m0, s55
	s_nop 0
	global_load_lds_dwordx4 v150, s[46:47]
	s_waitcnt vmcnt(8)
	s_waitcnt lgkmcnt(0)
	s_barrier
	s_setprio 1
	s_waitcnt lgkmcnt(0)
	v_mfma_f32_16x16x32_bf16 v[142:145], v[98:101], v[198:201], v[142:145]
	v_mfma_f32_16x16x32_bf16 v[138:141], v[106:109], v[198:201], v[138:141]
	v_mfma_f32_16x16x32_bf16 v[126:129], v[98:101], v[206:209], v[126:129]
	v_mfma_f32_16x16x32_bf16 v[122:125], v[106:109], v[206:209], v[122:125]
	v_mfma_f32_16x16x32_bf16 v[94:97], v[98:101], v[214:217], v[94:97]
	v_mfma_f32_16x16x32_bf16 v[90:93], v[106:109], v[214:217], v[90:93]
	v_mfma_f32_16x16x32_bf16 v[78:81], v[98:101], v[222:225], v[78:81]
	v_mfma_f32_16x16x32_bf16 v[74:77], v[106:109], v[222:225], v[74:77]
	v_mfma_f32_16x16x32_bf16 v[142:145], v[102:105], v[202:205], v[142:145]
	v_mfma_f32_16x16x32_bf16 v[138:141], v[110:113], v[202:205], v[138:141]
	v_mfma_f32_16x16x32_bf16 v[126:129], v[102:105], v[210:213], v[126:129]
	v_mfma_f32_16x16x32_bf16 v[122:125], v[110:113], v[210:213], v[122:125]
	v_mfma_f32_16x16x32_bf16 v[94:97], v[102:105], v[218:221], v[94:97]
	v_mfma_f32_16x16x32_bf16 v[90:93], v[110:113], v[218:221], v[90:93]
	v_mfma_f32_16x16x32_bf16 v[78:81], v[102:105], v[226:229], v[78:81]
	v_mfma_f32_16x16x32_bf16 v[74:77], v[110:113], v[226:229], v[74:77]
	s_setprio 0
	s_setprio 1
	v_mfma_f32_16x16x32_bf16 v[134:137], v[182:185], v[198:201], v[134:137]
	v_mfma_f32_16x16x32_bf16 v[130:133], v[190:193], v[198:201], v[130:133]
	v_mfma_f32_16x16x32_bf16 v[118:121], v[182:185], v[206:209], v[118:121]
	v_mfma_f32_16x16x32_bf16 v[114:117], v[190:193], v[206:209], v[114:117]
	v_mfma_f32_16x16x32_bf16 v[86:89], v[182:185], v[214:217], v[86:89]
	v_mfma_f32_16x16x32_bf16 v[82:85], v[190:193], v[214:217], v[82:85]
	v_mfma_f32_16x16x32_bf16 v[70:73], v[182:185], v[222:225], v[70:73]
	v_mfma_f32_16x16x32_bf16 v[66:69], v[190:193], v[222:225], v[66:69]
	v_mfma_f32_16x16x32_bf16 v[134:137], v[186:189], v[202:205], v[134:137]
	v_mfma_f32_16x16x32_bf16 v[130:133], v[194:197], v[202:205], v[130:133]
	v_mfma_f32_16x16x32_bf16 v[118:121], v[186:189], v[210:213], v[118:121]
	v_mfma_f32_16x16x32_bf16 v[114:117], v[194:197], v[210:213], v[114:117]
	v_mfma_f32_16x16x32_bf16 v[86:89], v[186:189], v[218:221], v[86:89]
	v_mfma_f32_16x16x32_bf16 v[82:85], v[194:197], v[218:221], v[82:85]
	v_mfma_f32_16x16x32_bf16 v[70:73], v[186:189], v[226:229], v[70:73]
	v_mfma_f32_16x16x32_bf16 v[66:69], v[194:197], v[226:229], v[66:69]
	s_setprio 0
	s_barrier
	s_add_i32 s13, s13, s49
	s_nop 0
	s_mov_b32 m0, s13
	ds_read_b128 v[198:201], v178 offset:49152
	ds_read_b128 v[202:205], v178 offset:50176
	ds_read_b128 v[206:209], v178 offset:51200
	ds_read_b128 v[210:213], v178 offset:52224
	ds_read_b128 v[214:217], v178 offset:53248
	ds_read_b128 v[218:221], v178 offset:54272
	ds_read_b128 v[222:225], v178 offset:55296
	ds_read_b128 v[226:229], v178 offset:56320
	global_load_lds_dwordx4 v251, s[44:45]
	s_add_i32 m0, s13, 0x2000
	s_add_u32 s44, s44, 0x40080
	v_lshl_add_u64 v[230:231], v[232:233], 0, s[20:21]
	s_addc_u32 s45, s45, 0
	s_add_i32 s13, s70, s49
	global_load_lds_dwordx4 v[230:231], off
	s_nop 0
	s_mov_b32 m0, s13
	s_nop 0
	global_load_lds_dwordx4 v152, s[44:45]
	s_nop 0
	s_add_i32 m0, s13, 0x2000
	s_nop 0
	global_load_lds_dwordx4 v148, s[44:45]
	v_lshl_add_u64 v[230:231], v[234:235], 0, s[20:21]
	s_mov_b32 m0, s58
	s_nop 0
	global_load_lds_dwordx4 v[230:231], off
	v_lshl_add_u64 v[230:231], v[236:237], 0, s[20:21]
	s_mov_b32 m0, s59
	s_nop 0
	global_load_lds_dwordx4 v[230:231], off
	s_waitcnt vmcnt(8)
	s_waitcnt lgkmcnt(0)
	s_barrier
	s_setprio 1
	s_waitcnt lgkmcnt(0)
	v_mfma_f32_16x16x32_bf16 v[62:65], v[98:101], v[198:201], v[62:65]
	v_mfma_f32_16x16x32_bf16 v[58:61], v[106:109], v[198:201], v[58:61]
	v_mfma_f32_16x16x32_bf16 v[46:49], v[98:101], v[206:209], v[46:49]
	v_mfma_f32_16x16x32_bf16 v[42:45], v[106:109], v[206:209], v[42:45]
	v_mfma_f32_16x16x32_bf16 v[30:33], v[98:101], v[214:217], v[30:33]
	v_mfma_f32_16x16x32_bf16 v[26:29], v[106:109], v[214:217], v[26:29]
	v_mfma_f32_16x16x32_bf16 v[14:17], v[98:101], v[222:225], v[14:17]
	v_mfma_f32_16x16x32_bf16 v[10:13], v[106:109], v[222:225], v[10:13]
	v_mfma_f32_16x16x32_bf16 v[62:65], v[102:105], v[202:205], v[62:65]
	v_mfma_f32_16x16x32_bf16 v[58:61], v[110:113], v[202:205], v[58:61]
	v_mfma_f32_16x16x32_bf16 v[46:49], v[102:105], v[210:213], v[46:49]
	v_mfma_f32_16x16x32_bf16 v[42:45], v[110:113], v[210:213], v[42:45]
	v_mfma_f32_16x16x32_bf16 v[30:33], v[102:105], v[218:221], v[30:33]
	v_mfma_f32_16x16x32_bf16 v[26:29], v[110:113], v[218:221], v[26:29]
	v_mfma_f32_16x16x32_bf16 v[14:17], v[102:105], v[226:229], v[14:17]
	v_mfma_f32_16x16x32_bf16 v[10:13], v[110:113], v[226:229], v[10:13]
	s_setprio 0
	s_setprio 1
	v_mfma_f32_16x16x32_bf16 v[54:57], v[182:185], v[198:201], v[54:57]
	v_mfma_f32_16x16x32_bf16 v[50:53], v[190:193], v[198:201], v[50:53]
	v_mfma_f32_16x16x32_bf16 v[38:41], v[182:185], v[206:209], v[38:41]
	v_mfma_f32_16x16x32_bf16 v[34:37], v[190:193], v[206:209], v[34:37]
	v_mfma_f32_16x16x32_bf16 v[22:25], v[182:185], v[214:217], v[22:25]
	v_mfma_f32_16x16x32_bf16 v[18:21], v[190:193], v[214:217], v[18:21]
	v_mfma_f32_16x16x32_bf16 v[6:9], v[182:185], v[222:225], v[6:9]
	v_mfma_f32_16x16x32_bf16 v[2:5], v[190:193], v[222:225], v[2:5]
	v_mfma_f32_16x16x32_bf16 v[54:57], v[186:189], v[202:205], v[54:57]
	v_mfma_f32_16x16x32_bf16 v[50:53], v[194:197], v[202:205], v[50:53]
	v_mfma_f32_16x16x32_bf16 v[38:41], v[186:189], v[210:213], v[38:41]
	v_mfma_f32_16x16x32_bf16 v[34:37], v[194:197], v[210:213], v[34:37]
	v_mfma_f32_16x16x32_bf16 v[22:25], v[186:189], v[218:221], v[22:25]
	v_mfma_f32_16x16x32_bf16 v[18:21], v[194:197], v[218:221], v[18:21]
	v_mfma_f32_16x16x32_bf16 v[6:9], v[186:189], v[226:229], v[6:9]
	v_mfma_f32_16x16x32_bf16 v[2:5], v[194:197], v[226:229], v[2:5]
	s_setprio 0
	s_barrier
	s_add_i32 s12, s12, 2
	s_add_u32 s0, s0, 0x100
	s_addc_u32 s1, s1, 0
	s_add_u32 s68, s68, 0x100
	s_addc_u32 s69, s69, 0
	s_cmp_gt_u32 s12, 13
	s_cbranch_scc0 .LBB0_1479
	s_and_b64 vcc, exec, s[24:25]
	s_cbranch_vccz .LBB0_1482
	s_barrier

.LBB0_1561:
	ds_read_b128 v[130:133], v228
	ds_read_b128 v[134:137], v228 offset:1024
	ds_read_b128 v[154:157], v228 offset:2048
	ds_read_b128 v[158:161], v228 offset:3072
	ds_read_b128 v[162:165], v229
	ds_read_b128 v[166:169], v229 offset:1024
	ds_read_b128 v[170:173], v229 offset:2048
	ds_read_b128 v[174:177], v229 offset:3072
	s_add_u32 s30, s28, 0x100
	s_addc_u32 s31, s29, 0
	s_cmp_eq_u32 s12, 40
	s_cselect_b32 s39, s1, s31
	s_cselect_b32 s38, s0, s30
	s_cselect_b32 s37, s9, s67
	s_cselect_b32 s36, s8, s27
	v_lshl_add_u64 v[210:211], s[28:29], 0, v[146:147]
	s_add_i32 m0, s41, 0xc000
	ds_read_b128 v[178:181], v230
	ds_read_b128 v[182:185], v230 offset:1024
	ds_read_b128 v[186:189], v230 offset:2048
	ds_read_b128 v[190:193], v230 offset:3072
	ds_read_b128 v[194:197], v230 offset:4096
	ds_read_b128 v[198:201], v230 offset:5120
	ds_read_b128 v[202:205], v230 offset:6144
	ds_read_b128 v[206:209], v230 offset:7168
	global_load_lds_dwordx4 v[210:211], off
	v_lshl_add_u64 v[210:211], s[28:29], 0, v[148:149]
	s_add_i32 m0, s41, 0xe000
	s_nop 0
	global_load_lds_dwordx4 v[210:211], off
	s_waitcnt vmcnt(8)
	s_waitcnt lgkmcnt(0)
	s_barrier
	s_setprio 1
	s_waitcnt lgkmcnt(0)
	v_mfma_f32_16x16x32_bf16 v[126:129], v[130:133], v[178:181], v[126:129]
	v_mfma_f32_16x16x32_bf16 v[122:125], v[154:157], v[178:181], v[122:125]
	v_mfma_f32_16x16x32_bf16 v[118:121], v[130:133], v[186:189], v[118:121]
	v_mfma_f32_16x16x32_bf16 v[114:117], v[154:157], v[186:189], v[114:117]
	v_mfma_f32_16x16x32_bf16 v[110:113], v[130:133], v[194:197], v[110:113]
	v_mfma_f32_16x16x32_bf16 v[106:109], v[154:157], v[194:197], v[106:109]
	v_mfma_f32_16x16x32_bf16 v[102:105], v[130:133], v[202:205], v[102:105]
	v_mfma_f32_16x16x32_bf16 v[98:101], v[154:157], v[202:205], v[98:101]
	v_mfma_f32_16x16x32_bf16 v[126:129], v[134:137], v[182:185], v[126:129]
	v_mfma_f32_16x16x32_bf16 v[122:125], v[158:161], v[182:185], v[122:125]
	v_mfma_f32_16x16x32_bf16 v[118:121], v[134:137], v[190:193], v[118:121]
	v_mfma_f32_16x16x32_bf16 v[114:117], v[158:161], v[190:193], v[114:117]
	v_mfma_f32_16x16x32_bf16 v[110:113], v[134:137], v[198:201], v[110:113]
	v_mfma_f32_16x16x32_bf16 v[106:109], v[158:161], v[198:201], v[106:109]
	v_mfma_f32_16x16x32_bf16 v[102:105], v[134:137], v[206:209], v[102:105]
	v_mfma_f32_16x16x32_bf16 v[98:101], v[158:161], v[206:209], v[98:101]
	s_setprio 0
	s_setprio 1
	v_mfma_f32_16x16x32_bf16 v[62:65], v[162:165], v[178:181], v[62:65]
	v_mfma_f32_16x16x32_bf16 v[58:61], v[170:173], v[178:181], v[58:61]
	v_mfma_f32_16x16x32_bf16 v[54:57], v[162:165], v[186:189], v[54:57]
	v_mfma_f32_16x16x32_bf16 v[50:53], v[170:173], v[186:189], v[50:53]
	v_mfma_f32_16x16x32_bf16 v[46:49], v[162:165], v[194:197], v[46:49]
	v_mfma_f32_16x16x32_bf16 v[42:45], v[170:173], v[194:197], v[42:45]
	v_mfma_f32_16x16x32_bf16 v[38:41], v[162:165], v[202:205], v[38:41]
	v_mfma_f32_16x16x32_bf16 v[34:37], v[170:173], v[202:205], v[34:37]
	v_mfma_f32_16x16x32_bf16 v[62:65], v[166:169], v[182:185], v[62:65]
	v_mfma_f32_16x16x32_bf16 v[58:61], v[174:177], v[182:185], v[58:61]
	v_mfma_f32_16x16x32_bf16 v[54:57], v[166:169], v[190:193], v[54:57]
	v_mfma_f32_16x16x32_bf16 v[50:53], v[174:177], v[190:193], v[50:53]
	v_mfma_f32_16x16x32_bf16 v[46:49], v[166:169], v[198:201], v[46:49]
	v_mfma_f32_16x16x32_bf16 v[42:45], v[174:177], v[198:201], v[42:45]
	v_mfma_f32_16x16x32_bf16 v[38:41], v[166:169], v[206:209], v[38:41]
	v_mfma_f32_16x16x32_bf16 v[34:37], v[174:177], v[206:209], v[34:37]
	s_setprio 0
	s_barrier
	s_add_i32 s13, s60, s40
	s_nop 0
	s_mov_b32 m0, s13
	ds_read_b128 v[178:181], v230 offset:16384
	ds_read_b128 v[182:185], v230 offset:17408
	ds_read_b128 v[186:189], v230 offset:18432
	ds_read_b128 v[190:193], v230 offset:19456
	ds_read_b128 v[194:197], v230 offset:20480
	ds_read_b128 v[198:201], v230 offset:21504
	ds_read_b128 v[202:205], v230 offset:22528
	ds_read_b128 v[206:209], v230 offset:23552
	global_load_lds_dwordx4 v140, s[36:37]
	s_add_i32 m0, s13, 0x2000
	s_add_u32 s28, s36, 0xb0000
	s_nop 0
	s_addc_u32 s29, s37, 0
	s_add_i32 s13, s61, s40
	global_load_lds_dwordx4 v144, s[36:37]
	s_nop 0
	s_mov_b32 m0, s13
	s_nop 0
	global_load_lds_dwordx4 v140, s[28:29]
	s_nop 0
	s_add_i32 m0, s13, 0x2000
	s_nop 0
	global_load_lds_dwordx4 v144, s[28:29]
	s_nop 0
	s_mov_b32 m0, s41
	s_nop 0
	global_load_lds_dwordx4 v138, s[38:39]
	s_mov_b32 m0, s42
	s_nop 0
	global_load_lds_dwordx4 v142, s[38:39]
	s_waitcnt vmcnt(8)
	s_waitcnt lgkmcnt(0)
	s_barrier
	s_setprio 1
	s_waitcnt lgkmcnt(0)
	v_mfma_f32_16x16x32_bf16 v[94:97], v[130:133], v[178:181], v[94:97]
	v_mfma_f32_16x16x32_bf16 v[90:93], v[154:157], v[178:181], v[90:93]
	v_mfma_f32_16x16x32_bf16 v[86:89], v[130:133], v[186:189], v[86:89]
	v_mfma_f32_16x16x32_bf16 v[82:85], v[154:157], v[186:189], v[82:85]
	v_mfma_f32_16x16x32_bf16 v[78:81], v[130:133], v[194:197], v[78:81]
	v_mfma_f32_16x16x32_bf16 v[74:77], v[154:157], v[194:197], v[74:77]
	v_mfma_f32_16x16x32_bf16 v[70:73], v[130:133], v[202:205], v[70:73]
	v_mfma_f32_16x16x32_bf16 v[66:69], v[154:157], v[202:205], v[66:69]
	v_mfma_f32_16x16x32_bf16 v[94:97], v[134:137], v[182:185], v[94:97]
	v_mfma_f32_16x16x32_bf16 v[90:93], v[158:161], v[182:185], v[90:93]
	v_mfma_f32_16x16x32_bf16 v[86:89], v[134:137], v[190:193], v[86:89]
	v_mfma_f32_16x16x32_bf16 v[82:85], v[158:161], v[190:193], v[82:85]
	v_mfma_f32_16x16x32_bf16 v[78:81], v[134:137], v[198:201], v[78:81]
	v_mfma_f32_16x16x32_bf16 v[74:77], v[158:161], v[198:201], v[74:77]
	v_mfma_f32_16x16x32_bf16 v[70:73], v[134:137], v[206:209], v[70:73]
	v_mfma_f32_16x16x32_bf16 v[66:69], v[158:161], v[206:209], v[66:69]
	s_setprio 0
	s_setprio 1
	v_mfma_f32_16x16x32_bf16 v[30:33], v[162:165], v[178:181], v[30:33]
	v_mfma_f32_16x16x32_bf16 v[26:29], v[170:173], v[178:181], v[26:29]
	v_mfma_f32_16x16x32_bf16 v[22:25], v[162:165], v[186:189], v[22:25]
	v_mfma_f32_16x16x32_bf16 v[18:21], v[170:173], v[186:189], v[18:21]
	v_mfma_f32_16x16x32_bf16 v[14:17], v[162:165], v[194:197], v[14:17]
	v_mfma_f32_16x16x32_bf16 v[10:13], v[170:173], v[194:197], v[10:13]
	v_mfma_f32_16x16x32_bf16 v[6:9], v[162:165], v[202:205], v[6:9]
	v_mfma_f32_16x16x32_bf16 v[2:5], v[170:173], v[202:205], v[2:5]
	v_mfma_f32_16x16x32_bf16 v[30:33], v[166:169], v[182:185], v[30:33]
	v_mfma_f32_16x16x32_bf16 v[26:29], v[174:177], v[182:185], v[26:29]
	v_mfma_f32_16x16x32_bf16 v[22:25], v[166:169], v[190:193], v[22:25]
	v_mfma_f32_16x16x32_bf16 v[18:21], v[174:177], v[190:193], v[18:21]
	v_mfma_f32_16x16x32_bf16 v[14:17], v[166:169], v[198:201], v[14:17]
	v_mfma_f32_16x16x32_bf16 v[10:13], v[174:177], v[198:201], v[10:13]
	v_mfma_f32_16x16x32_bf16 v[6:9], v[166:169], v[206:209], v[6:9]
	v_mfma_f32_16x16x32_bf16 v[2:5], v[174:177], v[206:209], v[2:5]
	s_setprio 0
	s_barrier
	s_add_i32 s13, 0, 0x18000
	s_add_i32 s68, 0, 0x1c000
	v_add_u32_e32 v158, s13, v226
	v_add_u32_e32 v174, s68, v226
	ds_read_b128 v[130:133], v158
	ds_read_b128 v[134:137], v158 offset:1024
	ds_read_b128 v[154:157], v158 offset:2048
	ds_read_b128 v[158:161], v158 offset:3072
	ds_read_b128 v[162:165], v174
	ds_read_b128 v[166:169], v174 offset:1024
	ds_read_b128 v[170:173], v174 offset:2048
	ds_read_b128 v[174:177], v174 offset:3072
	s_add_u32 s28, s38, 0xb0000
	s_addc_u32 s29, s39, 0
	s_mov_b32 m0, s43
	s_nop 0
	ds_read_b128 v[178:181], v230 offset:32768
	ds_read_b128 v[182:185], v230 offset:33792
	ds_read_b128 v[186:189], v230 offset:34816
	ds_read_b128 v[190:193], v230 offset:35840
	ds_read_b128 v[194:197], v230 offset:36864
	ds_read_b128 v[198:201], v230 offset:37888
	ds_read_b128 v[202:205], v230 offset:38912
	ds_read_b128 v[206:209], v230 offset:39936
	global_load_lds_dwordx4 v138, s[28:29]
	s_nop 0
	s_mov_b32 m0, s44
	s_nop 0
	global_load_lds_dwordx4 v142, s[28:29]
	s_waitcnt vmcnt(8)
	s_waitcnt lgkmcnt(0)
	s_barrier
	s_setprio 1
	s_waitcnt lgkmcnt(0)
	v_mfma_f32_16x16x32_bf16 v[126:129], v[130:133], v[178:181], v[126:129]
	v_mfma_f32_16x16x32_bf16 v[122:125], v[154:157], v[178:181], v[122:125]
	v_mfma_f32_16x16x32_bf16 v[118:121], v[130:133], v[186:189], v[118:121]
	v_mfma_f32_16x16x32_bf16 v[114:117], v[154:157], v[186:189], v[114:117]
	v_mfma_f32_16x16x32_bf16 v[110:113], v[130:133], v[194:197], v[110:113]
	v_mfma_f32_16x16x32_bf16 v[106:109], v[154:157], v[194:197], v[106:109]
	v_mfma_f32_16x16x32_bf16 v[102:105], v[130:133], v[202:205], v[102:105]
	v_mfma_f32_16x16x32_bf16 v[98:101], v[154:157], v[202:205], v[98:101]
	v_mfma_f32_16x16x32_bf16 v[126:129], v[134:137], v[182:185], v[126:129]
	v_mfma_f32_16x16x32_bf16 v[122:125], v[158:161], v[182:185], v[122:125]
	v_mfma_f32_16x16x32_bf16 v[118:121], v[134:137], v[190:193], v[118:121]
	v_mfma_f32_16x16x32_bf16 v[114:117], v[158:161], v[190:193], v[114:117]
	v_mfma_f32_16x16x32_bf16 v[110:113], v[134:137], v[198:201], v[110:113]
	v_mfma_f32_16x16x32_bf16 v[106:109], v[158:161], v[198:201], v[106:109]
	v_mfma_f32_16x16x32_bf16 v[102:105], v[134:137], v[206:209], v[102:105]
	v_mfma_f32_16x16x32_bf16 v[98:101], v[158:161], v[206:209], v[98:101]
	s_setprio 0
	s_setprio 1
	v_mfma_f32_16x16x32_bf16 v[62:65], v[162:165], v[178:181], v[62:65]
	v_mfma_f32_16x16x32_bf16 v[58:61], v[170:173], v[178:181], v[58:61]
	v_mfma_f32_16x16x32_bf16 v[54:57], v[162:165], v[186:189], v[54:57]
	v_mfma_f32_16x16x32_bf16 v[50:53], v[170:173], v[186:189], v[50:53]
	v_mfma_f32_16x16x32_bf16 v[46:49], v[162:165], v[194:197], v[46:49]
	v_mfma_f32_16x16x32_bf16 v[42:45], v[170:173], v[194:197], v[42:45]
	v_mfma_f32_16x16x32_bf16 v[38:41], v[162:165], v[202:205], v[38:41]
	v_mfma_f32_16x16x32_bf16 v[34:37], v[170:173], v[202:205], v[34:37]
	v_mfma_f32_16x16x32_bf16 v[62:65], v[166:169], v[182:185], v[62:65]
	v_mfma_f32_16x16x32_bf16 v[58:61], v[174:177], v[182:185], v[58:61]
	v_mfma_f32_16x16x32_bf16 v[54:57], v[166:169], v[190:193], v[54:57]
	v_mfma_f32_16x16x32_bf16 v[50:53], v[174:177], v[190:193], v[50:53]
	v_mfma_f32_16x16x32_bf16 v[46:49], v[166:169], v[198:201], v[46:49]
	v_mfma_f32_16x16x32_bf16 v[42:45], v[174:177], v[198:201], v[42:45]
	v_mfma_f32_16x16x32_bf16 v[38:41], v[166:169], v[206:209], v[38:41]
	v_mfma_f32_16x16x32_bf16 v[34:37], v[174:177], v[206:209], v[34:37]
	s_setprio 0
	s_barrier
	s_add_i32 s13, s13, s40
	s_nop 0
	s_mov_b32 m0, s13
	ds_read_b128 v[178:181], v230 offset:49152
	ds_read_b128 v[182:185], v230 offset:50176
	ds_read_b128 v[186:189], v230 offset:51200
	ds_read_b128 v[190:193], v230 offset:52224
	ds_read_b128 v[194:197], v230 offset:53248
	ds_read_b128 v[198:201], v230 offset:54272
	ds_read_b128 v[202:205], v230 offset:55296
	ds_read_b128 v[206:209], v230 offset:56320
	global_load_lds_dwordx4 v251, s[36:37]
	s_add_i32 m0, s13, 0x2000
	s_add_u32 s28, s36, 0xb0080
	s_nop 0
	s_addc_u32 s29, s37, 0
	s_add_i32 s13, s68, s40
	global_load_lds_dwordx4 v252, s[36:37]
	s_nop 0
	s_mov_b32 m0, s13
	s_nop 0
	global_load_lds_dwordx4 v140, s[28:29]
	s_nop 0
	s_add_i32 m0, s13, 0x2000
	s_nop 0
	global_load_lds_dwordx4 v144, s[28:29]
	s_nop 0
	s_mov_b32 m0, s57
	s_nop 0
	global_load_lds_dwordx4 v253, s[38:39]
	s_nop 0
	s_mov_b32 m0, s58
	s_nop 0
	global_load_lds_dwordx4 v254, s[38:39]
	s_waitcnt vmcnt(8)
	s_waitcnt lgkmcnt(0)
	s_barrier
	s_setprio 1
	s_waitcnt lgkmcnt(0)
	v_mfma_f32_16x16x32_bf16 v[94:97], v[130:133], v[178:181], v[94:97]
	v_mfma_f32_16x16x32_bf16 v[90:93], v[154:157], v[178:181], v[90:93]
	v_mfma_f32_16x16x32_bf16 v[86:89], v[130:133], v[186:189], v[86:89]
	v_mfma_f32_16x16x32_bf16 v[82:85], v[154:157], v[186:189], v[82:85]
	v_mfma_f32_16x16x32_bf16 v[78:81], v[130:133], v[194:197], v[78:81]
	v_mfma_f32_16x16x32_bf16 v[74:77], v[154:157], v[194:197], v[74:77]
	v_mfma_f32_16x16x32_bf16 v[70:73], v[130:133], v[202:205], v[70:73]
	v_mfma_f32_16x16x32_bf16 v[66:69], v[154:157], v[202:205], v[66:69]
	v_mfma_f32_16x16x32_bf16 v[94:97], v[134:137], v[182:185], v[94:97]
	v_mfma_f32_16x16x32_bf16 v[90:93], v[158:161], v[182:185], v[90:93]
	v_mfma_f32_16x16x32_bf16 v[86:89], v[134:137], v[190:193], v[86:89]
	v_mfma_f32_16x16x32_bf16 v[82:85], v[158:161], v[190:193], v[82:85]
	v_mfma_f32_16x16x32_bf16 v[78:81], v[134:137], v[198:201], v[78:81]
	v_mfma_f32_16x16x32_bf16 v[74:77], v[158:161], v[198:201], v[74:77]
	v_mfma_f32_16x16x32_bf16 v[70:73], v[134:137], v[206:209], v[70:73]
	v_mfma_f32_16x16x32_bf16 v[66:69], v[158:161], v[206:209], v[66:69]
	s_setprio 0
	s_setprio 1
	v_mfma_f32_16x16x32_bf16 v[30:33], v[162:165], v[178:181], v[30:33]
	v_mfma_f32_16x16x32_bf16 v[26:29], v[170:173], v[178:181], v[26:29]
	v_mfma_f32_16x16x32_bf16 v[22:25], v[162:165], v[186:189], v[22:25]
	v_mfma_f32_16x16x32_bf16 v[18:21], v[170:173], v[186:189], v[18:21]
	v_mfma_f32_16x16x32_bf16 v[14:17], v[162:165], v[194:197], v[14:17]
	v_mfma_f32_16x16x32_bf16 v[10:13], v[170:173], v[194:197], v[10:13]
	v_mfma_f32_16x16x32_bf16 v[6:9], v[162:165], v[202:205], v[6:9]
	v_mfma_f32_16x16x32_bf16 v[2:5], v[170:173], v[202:205], v[2:5]
	v_mfma_f32_16x16x32_bf16 v[30:33], v[166:169], v[182:185], v[30:33]
	v_mfma_f32_16x16x32_bf16 v[26:29], v[174:177], v[182:185], v[26:29]
	v_mfma_f32_16x16x32_bf16 v[22:25], v[166:169], v[190:193], v[22:25]
	v_mfma_f32_16x16x32_bf16 v[18:21], v[174:177], v[190:193], v[18:21]
	v_mfma_f32_16x16x32_bf16 v[14:17], v[166:169], v[198:201], v[14:17]
	v_mfma_f32_16x16x32_bf16 v[10:13], v[174:177], v[198:201], v[10:13]
	v_mfma_f32_16x16x32_bf16 v[6:9], v[166:169], v[206:209], v[6:9]
	v_mfma_f32_16x16x32_bf16 v[2:5], v[174:177], v[206:209], v[2:5]
	s_setprio 0
	s_barrier
	s_add_i32 s12, s12, 2
	s_add_u32 s27, s27, 0x100
	s_addc_u32 s67, s67, 0
	s_cmp_gt_u32 s12, 41
	s_mov_b64 s[28:29], s[30:31]
	s_cbranch_scc0 .LBB0_1561
	s_ashr_i32 s12, s26, 3
	s_ashr_i32 s27, s26, 31
	s_mul_i32 s37, s12, 0x6000
	s_mul_hi_i32 s36, s12, 0x6000
	s_add_u32 s12, s54, s37
	v_mov_b32_e32 v130, v1
	s_addc_u32 s13, s55, s36
	s_lshl_b64 s[28:29], s[26:27], 19
	v_lshl_or_b32 v166, s66, 8, v227
	s_add_u32 s30, s46, s28
	v_add_u32_e32 v160, s56, v130
	v_ashrrev_i32_e32 v167, 31, v166
	s_addc_u32 s31, s47, s29
	v_lshlrev_b64 v[156:157], 1, v[166:167]
	v_ashrrev_i32_e32 v161, 31, v160
	v_lshlrev_b64 v[130:131], 2, v[166:167]
	v_lshl_add_u64 v[162:163], s[30:31], 0, v[156:157]
	v_lshlrev_b64 v[154:155], 11, v[160:161]
	v_add_u32_e32 v170, 16, v160
	v_lshl_add_u64 v[172:173], s[12:13], 0, v[130:131]
	v_lshl_add_u64 v[174:175], v[162:163], 0, v[154:155]
	v_ashrrev_i32_e32 v171, 31, v170
	s_add_u32 s12, s48, s28
	v_lshl_add_u64 v[132:133], s[16:17], 0, v[130:131]
	global_load_dwordx4 v[180:183], v[172:173], off offset:16
	global_load_dwordx4 v[184:187], v[172:173], off
	global_load_dwordx4 v[188:191], v[132:133], off offset:16
	global_load_dwordx4 v[192:195], v[132:133], off
	global_load_dwordx4 v[196:199], v[174:175], off nt
	v_lshlrev_b64 v[204:205], 11, v[170:171]
	s_addc_u32 s13, s49, s29
	v_lshl_add_u64 v[178:179], v[162:163], 0, v[204:205]
	s_add_u32 s28, s50, s37
	global_load_dwordx4 v[200:203], v[178:179], off nt
	s_addc_u32 s29, s51, s36
	v_lshl_add_u64 v[176:177], s[28:29], 0, v[130:131]
	global_load_dwordx4 v[134:137], v[176:177], off
	global_load_dwordx4 v[130:133], v[176:177], off offset:16
	v_lshl_add_u64 v[158:159], s[12:13], 0, v[156:157]
	s_lshl_b32 s12, s26, 8
	v_lshl_add_u64 v[164:165], v[158:159], 0, v[154:155]
	v_add_u32_e32 v154, s12, v160
	v_ashrrev_i32_e32 v155, 31, v154
	v_lshlrev_b64 v[168:169], 11, v[154:155]
	v_lshl_add_u64 v[168:169], s[10:11], 0, v[168:169]
	v_add_u32_e32 v170, s12, v170
	v_lshl_add_u64 v[168:169], v[168:169], 0, v[156:157]
	v_ashrrev_i32_e32 v171, 31, v170
	v_lshlrev_b64 v[170:171], 11, v[170:171]
	v_lshl_add_u64 v[170:171], s[10:11], 0, v[170:171]
	s_waitcnt vmcnt(0)
	v_pk_add_f32 v[182:183], v[182:183], 1.0 op_sel_hi:[1,0]
	v_pk_add_f32 v[186:187], v[186:187], 1.0 op_sel_hi:[1,0]
	v_pk_add_f32 v[184:185], v[184:185], 1.0 op_sel_hi:[1,0]
	v_pk_add_f32 v[180:181], v[180:181], 1.0 op_sel_hi:[1,0]
	v_pk_mul_f32 v[216:217], v[194:195], v[186:187]
	v_pk_mul_f32 v[218:219], v[192:193], v[184:185]
	v_pk_mul_f32 v[220:221], v[190:191], v[182:183]
	v_pk_mul_f32 v[222:223], v[188:189], v[180:181]
	v_cvt_f32_f16_e32 v180, v198
	v_cvt_f32_f16_sdwa v181, v198 dst_sel:DWORD dst_unused:UNUSED_PAD src0_sel:WORD_1
	v_cvt_f32_f16_e32 v182, v199
	v_cvt_f32_f16_sdwa v183, v199 dst_sel:DWORD dst_unused:UNUSED_PAD src0_sel:WORD_1
	v_cvt_f32_f16_e32 v184, v196
	v_cvt_f32_f16_sdwa v185, v196 dst_sel:DWORD dst_unused:UNUSED_PAD src0_sel:WORD_1
	v_cvt_f32_f16_e32 v186, v197
	v_cvt_f32_f16_sdwa v187, v197 dst_sel:DWORD dst_unused:UNUSED_PAD src0_sel:WORD_1
	v_cvt_f32_f16_e32 v188, v202
	v_cvt_f32_f16_sdwa v189, v202 dst_sel:DWORD dst_unused:UNUSED_PAD src0_sel:WORD_1
	v_cvt_f32_f16_e32 v190, v203
	v_cvt_f32_f16_sdwa v191, v203 dst_sel:DWORD dst_unused:UNUSED_PAD src0_sel:WORD_1
	v_cvt_f32_f16_e32 v192, v200
	v_cvt_f32_f16_sdwa v193, v200 dst_sel:DWORD dst_unused:UNUSED_PAD src0_sel:WORD_1
	v_cvt_f32_f16_e32 v194, v201
	v_cvt_f32_f16_sdwa v195, v201 dst_sel:DWORD dst_unused:UNUSED_PAD src0_sel:WORD_1
	v_pk_fma_f32 v[128:129], v[128:129], v[136:137], v[186:187]
	v_pk_fma_f32 v[126:127], v[126:127], v[134:135], v[184:185]
	v_pk_fma_f32 v[124:125], v[124:125], v[132:133], v[182:183]
	v_pk_fma_f32 v[122:123], v[122:123], v[130:131], v[180:181]
	v_cvt_pk_f16_f32 v183, v124, v125
	v_cvt_pk_f16_f32 v181, v128, v129
	v_cvt_pk_f16_f32 v182, v122, v123
	v_cvt_pk_f16_f32 v180, v126, v127
	v_pk_fma_f32 v[120:121], v[120:121], v[136:137], v[194:195]
	v_pk_fma_f32 v[118:119], v[118:119], v[134:135], v[192:193]
	v_pk_fma_f32 v[116:117], v[116:117], v[132:133], v[190:191]
	v_pk_fma_f32 v[114:115], v[114:115], v[130:131], v[188:189]
	v_pk_mul_f32 v[188:189], v[216:217], v[128:129]
	v_pk_mul_f32 v[190:191], v[218:219], v[126:127]
	global_store_dwordx4 v[164:165], v[180:183], off
	v_pk_mul_f32 v[192:193], v[220:221], v[124:125]
	v_pk_mul_f32 v[194:195], v[222:223], v[122:123]
	v_cvt_pk_bf16_f32 v180, v190, v191
	v_cvt_pk_bf16_f32 v181, v188, v189
	v_cvt_pk_f16_f32 v187, v116, v117
	v_cvt_pk_f16_f32 v185, v120, v121
	v_cvt_pk_f16_f32 v186, v114, v115
	v_cvt_pk_bf16_f32 v182, v194, v195
	v_cvt_pk_bf16_f32 v183, v192, v193
	global_store_dwordx4 v[168:169], v[180:183], off
	v_cvt_pk_f16_f32 v184, v118, v119
	v_pk_mul_f32 v[188:189], v[222:223], v[114:115]
	v_lshl_add_u64 v[180:181], v[158:159], 0, v[204:205]
	global_store_dwordx4 v[180:181], v[184:187], off
	v_pk_mul_f32 v[182:183], v[218:219], v[118:119]
	v_add_u32_e32 v192, 48, v160
	v_pk_mul_f32 v[184:185], v[216:217], v[120:121]
	v_pk_mul_f32 v[186:187], v[220:221], v[116:117]
	v_cvt_pk_bf16_f32 v182, v182, v183
	v_cvt_pk_bf16_f32 v183, v184, v185
	v_cvt_pk_bf16_f32 v184, v188, v189
	v_ashrrev_i32_e32 v193, 31, v192
	v_cvt_pk_bf16_f32 v185, v186, v187
	v_lshl_add_u64 v[186:187], v[170:171], 0, v[156:157]
	global_store_dwordx4 v[186:187], v[182:185], off
	v_mul_f32_e32 v127, v127, v127
	v_mul_f32_e32 v129, v129, v129
	v_add_u32_e32 v182, 32, v160
	v_ashrrev_i32_e32 v183, 31, v182
	v_lshlrev_b64 v[170:171], 11, v[182:183]
	v_lshl_add_u64 v[188:189], v[162:163], 0, v[170:171]
	global_load_dwordx4 v[194:197], v[188:189], off nt
	v_lshlrev_b64 v[184:185], 11, v[192:193]
	v_lshl_add_u64 v[190:191], v[162:163], 0, v[184:185]
	global_load_dwordx4 v[198:201], v[190:191], off nt
	v_add_u32_e32 v182, s12, v182
	v_add_u32_e32 v192, s12, v192
	v_ashrrev_i32_e32 v183, 31, v182
	v_ashrrev_i32_e32 v193, 31, v192
	v_lshlrev_b64 v[182:183], 11, v[182:183]
	v_lshlrev_b64 v[192:193], 11, v[192:193]
	v_lshl_add_u64 v[182:183], s[10:11], 0, v[182:183]
	v_lshl_add_u64 v[202:203], s[10:11], 0, v[192:193]
	v_lshl_add_u64 v[192:193], v[182:183], 0, v[156:157]
	v_lshl_add_u64 v[170:171], v[158:159], 0, v[170:171]
	v_lshl_add_u64 v[184:185], v[158:159], 0, v[184:185]
	v_mul_f32_e32 v123, v123, v123
	v_mul_f32_e32 v125, v125, v125
	v_fmac_f32_e32 v127, v126, v126
	v_fmac_f32_e32 v129, v128, v128
	v_fmac_f32_e32 v123, v122, v122
	v_fmac_f32_e32 v125, v124, v124
	v_add_f32_e32 v122, v127, v129
	v_add_f32_e32 v123, v123, v125
	v_add_f32_e32 v122, v122, v123
	s_waitcnt vmcnt(1)
	v_cvt_f32_f16_e32 v182, v196
	v_cvt_f32_f16_sdwa v183, v196 dst_sel:DWORD dst_unused:UNUSED_PAD src0_sel:WORD_1
	v_cvt_f32_f16_e32 v196, v197
	v_cvt_f32_f16_sdwa v197, v197 dst_sel:DWORD dst_unused:UNUSED_PAD src0_sel:WORD_1
	v_cvt_f32_f16_e32 v204, v194
	v_cvt_f32_f16_sdwa v205, v194 dst_sel:DWORD dst_unused:UNUSED_PAD src0_sel:WORD_1
	v_cvt_f32_f16_e32 v194, v195
	v_cvt_f32_f16_sdwa v195, v195 dst_sel:DWORD dst_unused:UNUSED_PAD src0_sel:WORD_1
	s_waitcnt vmcnt(0)
	v_cvt_f32_f16_e32 v206, v200
	v_cvt_f32_f16_sdwa v207, v200 dst_sel:DWORD dst_unused:UNUSED_PAD src0_sel:WORD_1
	v_cvt_f32_f16_e32 v208, v198
	v_cvt_f32_f16_sdwa v209, v198 dst_sel:DWORD dst_unused:UNUSED_PAD src0_sel:WORD_1
	v_cvt_f32_f16_e32 v198, v199
	v_cvt_f32_f16_sdwa v199, v199 dst_sel:DWORD dst_unused:UNUSED_PAD src0_sel:WORD_1
	v_cvt_f32_f16_e32 v200, v201
	v_cvt_f32_f16_sdwa v201, v201 dst_sel:DWORD dst_unused:UNUSED_PAD src0_sel:WORD_1
	v_pk_fma_f32 v[112:113], v[112:113], v[136:137], v[194:195]
	v_pk_fma_f32 v[110:111], v[110:111], v[134:135], v[204:205]
	v_pk_fma_f32 v[108:109], v[108:109], v[132:133], v[196:197]
	v_pk_fma_f32 v[106:107], v[106:107], v[130:131], v[182:183]
	v_cvt_pk_f16_f32 v197, v108, v109
	v_cvt_pk_f16_f32 v195, v112, v113
	v_cvt_pk_f16_f32 v196, v106, v107
	v_cvt_pk_f16_f32 v194, v110, v111
	v_pk_mul_f32 v[182:183], v[216:217], v[112:113]
	v_pk_fma_f32 v[104:105], v[104:105], v[136:137], v[198:199]
	v_pk_fma_f32 v[102:103], v[102:103], v[134:135], v[208:209]
	v_pk_fma_f32 v[98:99], v[98:99], v[130:131], v[206:207]
	v_pk_mul_f32 v[204:205], v[218:219], v[110:111]
	v_pk_mul_f32 v[206:207], v[220:221], v[108:109]
	global_store_dwordx4 v[170:171], v[194:197], off
	v_pk_fma_f32 v[100:101], v[100:101], v[132:133], v[200:201]
	v_pk_mul_f32 v[208:209], v[222:223], v[106:107]
	v_cvt_pk_bf16_f32 v194, v204, v205
	v_cvt_pk_bf16_f32 v195, v182, v183
	v_add_u32_e32 v182, 0x80, v160
	v_cvt_pk_f16_f32 v199, v104, v105
	v_cvt_pk_f16_f32 v198, v102, v103
	v_cvt_pk_bf16_f32 v196, v208, v209
	v_cvt_pk_bf16_f32 v197, v206, v207
	v_ashrrev_i32_e32 v183, 31, v182
	v_add_u32_e32 v206, 0x90, v160
	v_cvt_pk_f16_f32 v201, v100, v101
	v_cvt_pk_f16_f32 v200, v98, v99
	v_pk_mul_f32 v[210:211], v[216:217], v[104:105]
	v_pk_mul_f32 v[212:213], v[218:219], v[102:103]
	global_store_dwordx4 v[192:193], v[194:197], off
	global_store_dwordx4 v[184:185], v[198:201], off
	v_ashrrev_i32_e32 v207, 31, v206
	v_lshl_add_u64 v[196:197], v[202:203], 0, v[156:157]
	v_cvt_pk_bf16_f32 v198, v212, v213
	v_cvt_pk_bf16_f32 v199, v210, v211
	v_lshlrev_b64 v[194:195], 11, v[182:183]
	v_pk_mul_f32 v[214:215], v[220:221], v[100:101]
	v_pk_mul_f32 v[224:225], v[222:223], v[98:99]
	v_lshlrev_b64 v[208:209], 11, v[206:207]
	v_cvt_pk_bf16_f32 v200, v224, v225
	v_cvt_pk_bf16_f32 v201, v214, v215
	global_store_dwordx4 v[196:197], v[198:201], off
	v_lshl_add_u64 v[204:205], v[162:163], 0, v[208:209]
	global_load_dwordx4 v[236:239], v[204:205], off nt
	v_lshl_add_u64 v[198:199], v[162:163], 0, v[194:195]
	global_load_dwordx4 v[232:235], v[198:199], off nt
	v_lshl_add_u64 v[212:213], v[158:159], 0, v[194:195]
	v_add_u32_e32 v182, s12, v182
	v_add_u32_e32 v194, s12, v206
	v_ashrrev_i32_e32 v183, 31, v182
	v_ashrrev_i32_e32 v195, 31, v194
	v_lshlrev_b64 v[182:183], 11, v[182:183]
	v_lshlrev_b64 v[194:195], 11, v[194:195]
	v_lshl_add_u64 v[182:183], s[10:11], 0, v[182:183]
	v_lshl_add_u64 v[194:195], s[10:11], 0, v[194:195]
	v_lshl_add_u64 v[210:211], v[158:159], 0, v[208:209]
	v_lshl_add_u64 v[214:215], v[182:183], 0, v[156:157]
	v_lshl_add_u64 v[208:209], v[194:195], 0, v[156:157]
	v_add_u32_e32 v200, 0xa0, v160
	v_ashrrev_i32_e32 v201, 31, v200
	v_lshlrev_b64 v[240:241], 11, v[200:201]
	v_lshl_add_u64 v[202:203], v[162:163], 0, v[240:241]
	s_waitcnt vmcnt(0)
	v_cvt_f32_f16_e32 v182, v234
	v_cvt_f32_f16_sdwa v183, v234 dst_sel:DWORD dst_unused:UNUSED_PAD src0_sel:WORD_1
	v_cvt_f32_f16_e32 v194, v235
	v_cvt_f32_f16_sdwa v195, v235 dst_sel:DWORD dst_unused:UNUSED_PAD src0_sel:WORD_1
	v_cvt_f32_f16_e32 v206, v232
	v_cvt_f32_f16_sdwa v207, v232 dst_sel:DWORD dst_unused:UNUSED_PAD src0_sel:WORD_1
	v_cvt_f32_f16_e32 v224, v233
	v_cvt_f32_f16_sdwa v225, v233 dst_sel:DWORD dst_unused:UNUSED_PAD src0_sel:WORD_1
	v_cvt_f32_f16_e32 v232, v238
	v_cvt_f32_f16_sdwa v233, v238 dst_sel:DWORD dst_unused:UNUSED_PAD src0_sel:WORD_1
	v_cvt_f32_f16_e32 v234, v239
	v_cvt_f32_f16_sdwa v235, v239 dst_sel:DWORD dst_unused:UNUSED_PAD src0_sel:WORD_1
	v_cvt_f32_f16_e32 v238, v236
	v_cvt_f32_f16_sdwa v239, v236 dst_sel:DWORD dst_unused:UNUSED_PAD src0_sel:WORD_1
	v_cvt_f32_f16_e32 v236, v237
	v_cvt_f32_f16_sdwa v237, v237 dst_sel:DWORD dst_unused:UNUSED_PAD src0_sel:WORD_1
	v_pk_fma_f32 v[96:97], v[96:97], v[136:137], v[224:225]
	v_pk_fma_f32 v[94:95], v[94:95], v[134:135], v[206:207]
	v_pk_fma_f32 v[92:93], v[92:93], v[132:133], v[194:195]
	v_pk_fma_f32 v[90:91], v[90:91], v[130:131], v[182:183]
	v_pk_fma_f32 v[84:85], v[84:85], v[132:133], v[234:235]
	v_pk_fma_f32 v[82:83], v[82:83], v[130:131], v[232:233]
	v_cvt_pk_f16_f32 v235, v92, v93
	v_cvt_pk_f16_f32 v233, v96, v97
	v_cvt_pk_f16_f32 v234, v90, v91
	v_cvt_pk_f16_f32 v232, v94, v95
	v_pk_mul_f32 v[206:207], v[220:221], v[92:93]
	v_pk_mul_f32 v[182:183], v[216:217], v[96:97]
	v_pk_mul_f32 v[194:195], v[218:219], v[94:95]
	v_pk_mul_f32 v[224:225], v[222:223], v[90:91]
	global_store_dwordx4 v[212:213], v[232:235], off
	v_pk_fma_f32 v[88:89], v[88:89], v[136:137], v[236:237]
	v_pk_fma_f32 v[86:87], v[86:87], v[134:135], v[238:239]
	v_cvt_pk_bf16_f32 v232, v194, v195
	v_cvt_pk_bf16_f32 v233, v182, v183
	v_cvt_pk_bf16_f32 v234, v224, v225
	v_cvt_pk_bf16_f32 v235, v206, v207
	v_add_u32_e32 v206, 0xb0, v160
	v_ashrrev_i32_e32 v207, 31, v206
	v_cvt_pk_f16_f32 v239, v84, v85
	v_cvt_pk_f16_f32 v237, v88, v89
	v_cvt_pk_f16_f32 v238, v82, v83
	v_cvt_pk_f16_f32 v236, v86, v87
	v_pk_mul_f32 v[242:243], v[216:217], v[88:89]
	v_pk_mul_f32 v[244:245], v[218:219], v[86:87]
	v_pk_mul_f32 v[246:247], v[220:221], v[84:85]
	v_pk_mul_f32 v[248:249], v[222:223], v[82:83]
	global_store_dwordx4 v[214:215], v[232:235], off
	global_store_dwordx4 v[210:211], v[236:239], off
	v_lshlrev_b64 v[194:195], 11, v[206:207]
	v_cvt_pk_bf16_f32 v232, v244, v245
	v_cvt_pk_bf16_f32 v233, v242, v243
	v_cvt_pk_bf16_f32 v234, v248, v249
	v_cvt_pk_bf16_f32 v235, v246, v247
	global_store_dwordx4 v[208:209], v[232:235], off
	global_load_dwordx4 v[232:235], v[202:203], off nt
	v_lshl_add_u64 v[224:225], v[162:163], 0, v[194:195]
	global_load_dwordx4 v[160:163], v[224:225], off nt
	v_lshl_add_u64 v[182:183], v[158:159], 0, v[240:241]
	v_lshl_add_u64 v[194:195], v[158:159], 0, v[194:195]
	v_add_u32_e32 v158, s12, v200
	v_add_u32_e32 v200, s12, v206
	v_ashrrev_i32_e32 v159, 31, v158
	v_ashrrev_i32_e32 v201, 31, v200
	v_lshlrev_b64 v[158:159], 11, v[158:159]
	v_lshlrev_b64 v[200:201], 11, v[200:201]
	v_lshl_add_u64 v[158:159], s[10:11], 0, v[158:159]
	v_lshl_add_u64 v[200:201], s[10:11], 0, v[200:201]
	v_lshl_add_u64 v[206:207], v[158:159], 0, v[156:157]
	v_lshl_add_u64 v[200:201], v[200:201], 0, v[156:157]
	s_waitcnt vmcnt(1)
	v_cvt_f32_f16_e32 v158, v234
	v_cvt_f32_f16_sdwa v159, v234 dst_sel:DWORD dst_unused:UNUSED_PAD src0_sel:WORD_1
	v_cvt_f32_f16_e32 v156, v235
	v_cvt_f32_f16_sdwa v157, v235 dst_sel:DWORD dst_unused:UNUSED_PAD src0_sel:WORD_1
	v_cvt_f32_f16_e32 v234, v232
	v_cvt_f32_f16_sdwa v235, v232 dst_sel:DWORD dst_unused:UNUSED_PAD src0_sel:WORD_1
	v_cvt_f32_f16_e32 v232, v233
	v_cvt_f32_f16_sdwa v233, v233 dst_sel:DWORD dst_unused:UNUSED_PAD src0_sel:WORD_1
	s_waitcnt vmcnt(0)
	v_cvt_f32_f16_e32 v236, v162
	v_cvt_f32_f16_sdwa v237, v162 dst_sel:DWORD dst_unused:UNUSED_PAD src0_sel:WORD_1
	v_cvt_f32_f16_e32 v238, v163
	v_cvt_f32_f16_sdwa v239, v163 dst_sel:DWORD dst_unused:UNUSED_PAD src0_sel:WORD_1
	v_cvt_f32_f16_e32 v240, v160
	v_cvt_f32_f16_sdwa v241, v160 dst_sel:DWORD dst_unused:UNUSED_PAD src0_sel:WORD_1
	v_cvt_f32_f16_e32 v242, v161
	v_cvt_f32_f16_sdwa v243, v161 dst_sel:DWORD dst_unused:UNUSED_PAD src0_sel:WORD_1
	v_pk_fma_f32 v[160:161], v[80:81], v[136:137], v[232:233]
	v_pk_fma_f32 v[162:163], v[78:79], v[134:135], v[234:235]
	v_pk_fma_f32 v[156:157], v[76:77], v[132:133], v[156:157]
	v_pk_fma_f32 v[158:159], v[74:75], v[130:131], v[158:159]
	v_pk_fma_f32 v[74:75], v[68:69], v[132:133], v[238:239]
	v_pk_fma_f32 v[76:77], v[66:67], v[130:131], v[236:237]
	v_cvt_pk_f16_f32 v69, v156, v157
	v_cvt_pk_f16_f32 v67, v160, v161
	v_cvt_pk_f16_f32 v68, v158, v159
	v_cvt_pk_f16_f32 v66, v162, v163
	v_pk_fma_f32 v[78:79], v[72:73], v[136:137], v[242:243]
	v_pk_fma_f32 v[80:81], v[70:71], v[134:135], v[240:241]
	v_pk_mul_f32 v[130:131], v[216:217], v[160:161]
	v_pk_mul_f32 v[132:133], v[218:219], v[162:163]
	v_pk_mul_f32 v[134:135], v[220:221], v[156:157]
	v_pk_mul_f32 v[136:137], v[222:223], v[158:159]
	global_store_dwordx4 v[182:183], v[66:69], off
	v_cvt_pk_f16_f32 v73, v74, v75
	v_cvt_pk_f16_f32 v71, v78, v79
	v_cvt_pk_bf16_f32 v66, v132, v133
	v_cvt_pk_bf16_f32 v67, v130, v131
	v_cvt_pk_bf16_f32 v68, v136, v137
	v_cvt_pk_bf16_f32 v69, v134, v135
	v_cvt_pk_f16_f32 v72, v76, v77
	v_cvt_pk_f16_f32 v70, v80, v81
	v_pk_mul_f32 v[216:217], v[216:217], v[78:79]
	v_pk_mul_f32 v[218:219], v[218:219], v[80:81]
	v_pk_mul_f32 v[220:221], v[220:221], v[74:75]
	v_pk_mul_f32 v[222:223], v[222:223], v[76:77]
	global_store_dwordx4 v[206:207], v[66:69], off
	global_store_dwordx4 v[194:195], v[70:73], off
	s_nop 0
	v_cvt_pk_bf16_f32 v66, v218, v219
	v_cvt_pk_bf16_f32 v67, v216, v217
	v_cvt_pk_bf16_f32 v68, v222, v223
	v_cvt_pk_bf16_f32 v69, v220, v221
	global_store_dwordx4 v[200:201], v[66:69], off
	global_load_dwordx4 v[130:133], v[172:173], off offset:512
	global_load_dwordx4 v[134:137], v[172:173], off offset:528
	s_nop 0
	global_load_dwordx4 v[172:175], v[174:175], off offset:256 nt
	s_nop 0
	global_load_dwordx4 v[216:219], v[178:179], off offset:256 nt
	v_or_b32_e32 v66, 0x80, v166
	v_ashrrev_i32_e32 v67, 31, v66
	v_lshl_add_u64 v[66:67], v[66:67], 2, s[16:17]
	global_load_dwordx4 v[220:223], v[66:67], off
	global_load_dwordx4 v[232:235], v[66:67], off offset:16
	global_load_dwordx4 v[70:73], v[176:177], off offset:512
	s_nop 0
	global_load_dwordx4 v[66:69], v[176:177], off offset:528
	s_waitcnt vmcnt(7)
	v_pk_add_f32 v[132:133], v[132:133], 1.0 op_sel_hi:[1,0]
	v_pk_add_f32 v[166:167], v[130:131], 1.0 op_sel_hi:[1,0]
	s_waitcnt vmcnt(5)
	v_cvt_f32_f16_e32 v178, v174
	v_cvt_f32_f16_sdwa v179, v174 dst_sel:DWORD dst_unused:UNUSED_PAD src0_sel:WORD_1
	v_cvt_f32_f16_e32 v174, v175
	v_cvt_f32_f16_sdwa v175, v175 dst_sel:DWORD dst_unused:UNUSED_PAD src0_sel:WORD_1
	v_cvt_f32_f16_e32 v236, v172
	v_cvt_f32_f16_sdwa v237, v172 dst_sel:DWORD dst_unused:UNUSED_PAD src0_sel:WORD_1
	v_cvt_f32_f16_e32 v172, v173
	v_cvt_f32_f16_sdwa v173, v173 dst_sel:DWORD dst_unused:UNUSED_PAD src0_sel:WORD_1
	s_waitcnt vmcnt(4)
	v_cvt_f32_f16_e32 v238, v218
	v_cvt_f32_f16_sdwa v239, v218 dst_sel:DWORD dst_unused:UNUSED_PAD src0_sel:WORD_1
	v_cvt_f32_f16_e32 v218, v219
	v_cvt_f32_f16_sdwa v219, v219 dst_sel:DWORD dst_unused:UNUSED_PAD src0_sel:WORD_1
	v_cvt_f32_f16_e32 v240, v216
	v_cvt_f32_f16_sdwa v241, v216 dst_sel:DWORD dst_unused:UNUSED_PAD src0_sel:WORD_1
	v_cvt_f32_f16_e32 v216, v217
	v_cvt_f32_f16_sdwa v217, v217 dst_sel:DWORD dst_unused:UNUSED_PAD src0_sel:WORD_1
	v_pk_add_f32 v[136:137], v[136:137], 1.0 op_sel_hi:[1,0]
	v_pk_add_f32 v[176:177], v[134:135], 1.0 op_sel_hi:[1,0]
	s_waitcnt vmcnt(3)
	v_pk_mul_f32 v[130:131], v[222:223], v[132:133]
	s_waitcnt vmcnt(1)
	v_pk_fma_f32 v[64:65], v[64:65], v[72:73], v[172:173]
	v_pk_fma_f32 v[62:63], v[62:63], v[70:71], v[236:237]
	s_waitcnt vmcnt(0)
	v_pk_fma_f32 v[60:61], v[60:61], v[68:69], v[174:175]
	v_pk_fma_f32 v[58:59], v[58:59], v[66:67], v[178:179]
	v_pk_mul_f32 v[132:133], v[220:221], v[166:167]
	v_pk_mul_f32 v[134:135], v[234:235], v[136:137]
	v_pk_mul_f32 v[136:137], v[232:233], v[176:177]
	v_cvt_pk_f16_f32 v175, v60, v61
	v_cvt_pk_f16_f32 v173, v64, v65
	v_cvt_pk_f16_f32 v174, v58, v59
	v_cvt_pk_f16_f32 v172, v62, v63
	v_pk_mul_f32 v[166:167], v[130:131], v[64:65]
	v_pk_fma_f32 v[56:57], v[56:57], v[72:73], v[216:217]
	v_pk_fma_f32 v[54:55], v[54:55], v[70:71], v[240:241]
	v_pk_fma_f32 v[52:53], v[52:53], v[68:69], v[218:219]
	v_pk_fma_f32 v[50:51], v[50:51], v[66:67], v[238:239]
	v_pk_mul_f32 v[216:217], v[132:133], v[62:63]
	v_pk_mul_f32 v[218:219], v[134:135], v[60:61]
	v_pk_mul_f32 v[220:221], v[136:137], v[58:59]
	global_store_dwordx4 v[164:165], v[172:175], off offset:256
	v_cvt_pk_bf16_f32 v164, v216, v217
	v_cvt_pk_bf16_f32 v165, v166, v167
	v_cvt_pk_bf16_f32 v166, v220, v221
	v_cvt_pk_bf16_f32 v167, v218, v219
	v_cvt_pk_f16_f32 v179, v52, v53
	v_cvt_pk_f16_f32 v177, v56, v57
	v_cvt_pk_f16_f32 v178, v50, v51
	v_cvt_pk_f16_f32 v176, v54, v55
	v_pk_mul_f32 v[222:223], v[130:131], v[56:57]
	v_pk_mul_f32 v[232:233], v[132:133], v[54:55]
	v_pk_mul_f32 v[234:235], v[134:135], v[52:53]
	v_pk_mul_f32 v[236:237], v[136:137], v[50:51]
	global_store_dwordx4 v[168:169], v[164:167], off offset:256
	global_store_dwordx4 v[180:181], v[176:179], off offset:256
	v_mul_f32_e32 v63, v63, v63
	v_cvt_pk_bf16_f32 v164, v232, v233
	v_cvt_pk_bf16_f32 v165, v222, v223
	v_cvt_pk_bf16_f32 v166, v236, v237
	v_cvt_pk_bf16_f32 v167, v234, v235
	global_store_dwordx4 v[186:187], v[164:167], off offset:256
	global_load_dwordx4 v[164:167], v[188:189], off offset:256 nt
	s_nop 0
	global_load_dwordx4 v[172:175], v[190:191], off offset:256 nt
	v_mul_f32_e32 v65, v65, v65
	v_mul_f32_e32 v59, v59, v59
	v_mul_f32_e32 v61, v61, v61
	v_fmac_f32_e32 v63, v62, v62
	v_fmac_f32_e32 v65, v64, v64
	v_fmac_f32_e32 v59, v58, v58
	v_fmac_f32_e32 v61, v60, v60
	v_add_f32_e32 v58, v63, v65
	v_add_f32_e32 v59, v59, v61
	v_add_f32_e32 v58, v58, v59
	v_add_f32_e32 v59, v122, v58
	v_xor_b32_e32 v58, 32, v231
	s_waitcnt vmcnt(1)
	v_cvt_f32_f16_e32 v168, v166
	v_cvt_f32_f16_sdwa v169, v166 dst_sel:DWORD dst_unused:UNUSED_PAD src0_sel:WORD_1
	v_cvt_f32_f16_e32 v166, v167
	v_cvt_f32_f16_sdwa v167, v167 dst_sel:DWORD dst_unused:UNUSED_PAD src0_sel:WORD_1
	v_cvt_f32_f16_e32 v176, v164
	v_cvt_f32_f16_sdwa v177, v164 dst_sel:DWORD dst_unused:UNUSED_PAD src0_sel:WORD_1
	v_cvt_f32_f16_e32 v164, v165
	v_cvt_f32_f16_sdwa v165, v165 dst_sel:DWORD dst_unused:UNUSED_PAD src0_sel:WORD_1
	s_waitcnt vmcnt(0)
	v_cvt_f32_f16_e32 v178, v174
	v_cvt_f32_f16_sdwa v179, v174 dst_sel:DWORD dst_unused:UNUSED_PAD src0_sel:WORD_1
	v_cvt_f32_f16_e32 v174, v175
	v_cvt_f32_f16_sdwa v175, v175 dst_sel:DWORD dst_unused:UNUSED_PAD src0_sel:WORD_1
	v_cvt_f32_f16_e32 v180, v172
	v_cvt_f32_f16_sdwa v181, v172 dst_sel:DWORD dst_unused:UNUSED_PAD src0_sel:WORD_1
	v_cvt_f32_f16_e32 v172, v173
	v_cvt_f32_f16_sdwa v173, v173 dst_sel:DWORD dst_unused:UNUSED_PAD src0_sel:WORD_1
	v_pk_fma_f32 v[48:49], v[48:49], v[72:73], v[164:165]
	v_pk_fma_f32 v[46:47], v[46:47], v[70:71], v[176:177]
	v_pk_fma_f32 v[44:45], v[44:45], v[68:69], v[166:167]
	v_pk_fma_f32 v[42:43], v[42:43], v[66:67], v[168:169]
	v_cvt_pk_f16_f32 v167, v44, v45
	v_cvt_pk_f16_f32 v165, v48, v49
	v_cvt_pk_f16_f32 v166, v42, v43
	v_cvt_pk_f16_f32 v164, v46, v47
	v_pk_fma_f32 v[40:41], v[40:41], v[72:73], v[172:173]
	v_pk_fma_f32 v[38:39], v[38:39], v[70:71], v[180:181]
	v_pk_fma_f32 v[36:37], v[36:37], v[68:69], v[174:175]
	v_pk_fma_f32 v[34:35], v[34:35], v[66:67], v[178:179]
	v_pk_mul_f32 v[168:169], v[130:131], v[48:49]
	v_pk_mul_f32 v[176:177], v[132:133], v[46:47]
	v_pk_mul_f32 v[178:179], v[134:135], v[44:45]
	v_pk_mul_f32 v[180:181], v[136:137], v[42:43]
	global_store_dwordx4 v[170:171], v[164:167], off offset:256
	v_cvt_pk_f16_f32 v175, v36, v37
	v_cvt_pk_f16_f32 v173, v40, v41
	v_cvt_pk_bf16_f32 v164, v176, v177
	v_cvt_pk_bf16_f32 v165, v168, v169
	v_cvt_pk_bf16_f32 v166, v180, v181
	v_cvt_pk_bf16_f32 v167, v178, v179
	v_cvt_pk_f16_f32 v174, v34, v35
	v_cvt_pk_f16_f32 v172, v38, v39
	v_pk_mul_f32 v[186:187], v[130:131], v[40:41]
	v_pk_mul_f32 v[188:189], v[132:133], v[38:39]
	v_pk_mul_f32 v[190:191], v[134:135], v[36:37]
	v_pk_mul_f32 v[216:217], v[136:137], v[34:35]
	global_store_dwordx4 v[192:193], v[164:167], off offset:256
	global_store_dwordx4 v[184:185], v[172:175], off offset:256
	s_nop 0
	v_cvt_pk_bf16_f32 v164, v188, v189
	v_cvt_pk_bf16_f32 v165, v186, v187
	v_cvt_pk_bf16_f32 v166, v216, v217
	v_cvt_pk_bf16_f32 v167, v190, v191
	global_store_dwordx4 v[196:197], v[164:167], off offset:256
	global_load_dwordx4 v[164:167], v[198:199], off offset:256 nt
	s_nop 0
	global_load_dwordx4 v[168:171], v[204:205], off offset:256 nt
	s_waitcnt vmcnt(1)
	v_cvt_f32_f16_e32 v172, v166
	v_cvt_f32_f16_sdwa v173, v166 dst_sel:DWORD dst_unused:UNUSED_PAD src0_sel:WORD_1
	v_cvt_f32_f16_e32 v166, v167
	v_cvt_f32_f16_sdwa v167, v167 dst_sel:DWORD dst_unused:UNUSED_PAD src0_sel:WORD_1
	v_cvt_f32_f16_e32 v174, v164
	v_cvt_f32_f16_sdwa v175, v164 dst_sel:DWORD dst_unused:UNUSED_PAD src0_sel:WORD_1
	v_cvt_f32_f16_e32 v164, v165
	v_cvt_f32_f16_sdwa v165, v165 dst_sel:DWORD dst_unused:UNUSED_PAD src0_sel:WORD_1
	s_waitcnt vmcnt(0)
	v_cvt_f32_f16_e32 v176, v170
	v_cvt_f32_f16_sdwa v177, v170 dst_sel:DWORD dst_unused:UNUSED_PAD src0_sel:WORD_1
	v_cvt_f32_f16_e32 v170, v171
	v_cvt_f32_f16_sdwa v171, v171 dst_sel:DWORD dst_unused:UNUSED_PAD src0_sel:WORD_1
	v_cvt_f32_f16_e32 v178, v168
	v_cvt_f32_f16_sdwa v179, v168 dst_sel:DWORD dst_unused:UNUSED_PAD src0_sel:WORD_1
	v_cvt_f32_f16_e32 v168, v169
	v_cvt_f32_f16_sdwa v169, v169 dst_sel:DWORD dst_unused:UNUSED_PAD src0_sel:WORD_1
	v_pk_fma_f32 v[32:33], v[32:33], v[72:73], v[164:165]
	v_pk_fma_f32 v[30:31], v[30:31], v[70:71], v[174:175]
	v_pk_fma_f32 v[28:29], v[28:29], v[68:69], v[166:167]
	v_pk_fma_f32 v[26:27], v[26:27], v[66:67], v[172:173]
	v_cvt_pk_f16_f32 v167, v28, v29
	v_cvt_pk_f16_f32 v165, v32, v33
	v_cvt_pk_f16_f32 v166, v26, v27
	v_cvt_pk_f16_f32 v164, v30, v31
	v_pk_fma_f32 v[24:25], v[24:25], v[72:73], v[168:169]
	v_pk_fma_f32 v[22:23], v[22:23], v[70:71], v[178:179]
	v_pk_fma_f32 v[20:21], v[20:21], v[68:69], v[170:171]
	v_pk_fma_f32 v[18:19], v[18:19], v[66:67], v[176:177]
	v_pk_mul_f32 v[172:173], v[130:131], v[32:33]
	v_pk_mul_f32 v[174:175], v[132:133], v[30:31]
	v_pk_mul_f32 v[176:177], v[134:135], v[28:29]
	v_pk_mul_f32 v[178:179], v[136:137], v[26:27]
	global_store_dwordx4 v[212:213], v[164:167], off offset:256
	v_cvt_pk_f16_f32 v171, v20, v21
	v_cvt_pk_f16_f32 v169, v24, v25
	v_cvt_pk_bf16_f32 v164, v174, v175
	v_cvt_pk_bf16_f32 v165, v172, v173
	v_cvt_pk_bf16_f32 v166, v178, v179
	v_cvt_pk_bf16_f32 v167, v176, v177
	v_cvt_pk_f16_f32 v170, v18, v19
	v_cvt_pk_f16_f32 v168, v22, v23
	v_pk_mul_f32 v[180:181], v[130:131], v[24:25]
	v_pk_mul_f32 v[184:185], v[132:133], v[22:23]
	v_pk_mul_f32 v[186:187], v[134:135], v[20:21]
	v_pk_mul_f32 v[188:189], v[136:137], v[18:19]
	global_store_dwordx4 v[214:215], v[164:167], off offset:256
	global_store_dwordx4 v[210:211], v[168:171], off offset:256
	s_nop 0
	v_cvt_pk_bf16_f32 v164, v184, v185
	v_cvt_pk_bf16_f32 v165, v180, v181
	v_cvt_pk_bf16_f32 v166, v188, v189
	v_cvt_pk_bf16_f32 v167, v186, v187
	global_store_dwordx4 v[208:209], v[164:167], off offset:256
	global_load_dwordx4 v[166:169], v[202:203], off offset:256 nt
	s_nop 0
	global_load_dwordx4 v[170:173], v[224:225], off offset:256 nt
	v_and_b32_e32 v165, 64, v231
	v_xor_b32_e32 v164, 16, v231
	v_add_u32_e32 v165, 64, v165
	v_cmp_lt_i32_e32 vcc, v164, v165
	s_waitcnt vmcnt(1)
	v_cvt_f32_f16_e32 v62, v168
	v_cndmask_b32_e32 v164, v231, v164, vcc
	v_lshlrev_b32_e32 v164, 2, v164
	ds_bpermute_b32 v60, v164, v59
	v_cmp_lt_i32_e32 vcc, v58, v165
	v_cvt_f32_f16_sdwa v63, v168 dst_sel:DWORD dst_unused:UNUSED_PAD src0_sel:WORD_1
	v_cvt_f32_f16_e32 v64, v169
	v_cndmask_b32_e32 v58, v231, v58, vcc
	v_cvt_f32_f16_sdwa v65, v169 dst_sel:DWORD dst_unused:UNUSED_PAD src0_sel:WORD_1
	v_cvt_f32_f16_e32 v122, v166
	v_cvt_f32_f16_sdwa v123, v166 dst_sel:DWORD dst_unused:UNUSED_PAD src0_sel:WORD_1
	v_cvt_f32_f16_e32 v124, v167
	v_cvt_f32_f16_sdwa v125, v167 dst_sel:DWORD dst_unused:UNUSED_PAD src0_sel:WORD_1
	v_lshlrev_b32_e32 v58, 2, v58
	s_waitcnt lgkmcnt(0)
	v_add_f32_e32 v59, v59, v60
	ds_bpermute_b32 v60, v58, v59
	s_waitcnt vmcnt(0)
	v_cvt_f32_f16_e32 v126, v172
	v_cvt_f32_f16_sdwa v127, v172 dst_sel:DWORD dst_unused:UNUSED_PAD src0_sel:WORD_1
	v_cvt_f32_f16_e32 v128, v173
	v_cvt_f32_f16_sdwa v129, v173 dst_sel:DWORD dst_unused:UNUSED_PAD src0_sel:WORD_1
	v_cvt_f32_f16_e32 v166, v170
	v_cvt_f32_f16_sdwa v167, v170 dst_sel:DWORD dst_unused:UNUSED_PAD src0_sel:WORD_1
	v_cvt_f32_f16_e32 v168, v171
	v_cvt_f32_f16_sdwa v169, v171 dst_sel:DWORD dst_unused:UNUSED_PAD src0_sel:WORD_1
	v_pk_fma_f32 v[16:17], v[16:17], v[72:73], v[124:125]
	v_pk_fma_f32 v[14:15], v[14:15], v[70:71], v[122:123]
	v_pk_fma_f32 v[12:13], v[12:13], v[68:69], v[64:65]
	v_pk_fma_f32 v[10:11], v[10:11], v[66:67], v[62:63]
	v_cvt_pk_f16_f32 v65, v12, v13
	v_cvt_pk_f16_f32 v63, v16, v17
	v_cvt_pk_f16_f32 v64, v10, v11
	v_cvt_pk_f16_f32 v62, v14, v15
	v_pk_fma_f32 v[8:9], v[8:9], v[72:73], v[168:169]
	v_pk_fma_f32 v[6:7], v[6:7], v[70:71], v[166:167]
	v_pk_fma_f32 v[4:5], v[4:5], v[68:69], v[128:129]
	v_pk_fma_f32 v[2:3], v[2:3], v[66:67], v[126:127]
	v_pk_mul_f32 v[70:71], v[130:131], v[16:17]
	v_pk_mul_f32 v[72:73], v[132:133], v[14:15]
	v_pk_mul_f32 v[122:123], v[134:135], v[12:13]
	v_pk_mul_f32 v[124:125], v[136:137], v[10:11]
	global_store_dwordx4 v[182:183], v[62:65], off offset:256
	v_cvt_pk_f16_f32 v69, v4, v5
	v_cvt_pk_f16_f32 v67, v8, v9
	v_cvt_pk_bf16_f32 v62, v72, v73
	v_cvt_pk_bf16_f32 v63, v70, v71
	v_cvt_pk_bf16_f32 v64, v124, v125
	v_cvt_pk_bf16_f32 v65, v122, v123
	v_cvt_pk_f16_f32 v68, v2, v3
	v_cvt_pk_f16_f32 v66, v6, v7
	v_pk_mul_f32 v[126:127], v[130:131], v[8:9]
	v_pk_mul_f32 v[128:129], v[132:133], v[6:7]
	v_pk_mul_f32 v[130:131], v[134:135], v[4:5]
	v_pk_mul_f32 v[132:133], v[136:137], v[2:3]
	global_store_dwordx4 v[206:207], v[62:65], off offset:256
	global_store_dwordx4 v[194:195], v[66:69], off offset:256
	s_nop 0
	v_cvt_pk_bf16_f32 v62, v128, v129
	v_cvt_pk_bf16_f32 v63, v126, v127
	v_cvt_pk_bf16_f32 v64, v132, v133
	v_cvt_pk_bf16_f32 v65, v130, v131
	global_store_dwordx4 v[200:201], v[62:65], off offset:256
	s_and_saveexec_b64 s[26:27], s[4:5]
	s_cbranch_execz .LBB0_1564
	v_lshl_add_u64 v[62:63], v[154:155], 2, s[22:23]
	s_waitcnt lgkmcnt(0)
	v_add_f32_e32 v59, v59, v60
	global_atomic_add_f32 v[62:63], v59, off

.LBB0_1606:
	ds_read_b128 v[106:109], v201
	ds_read_b128 v[110:113], v201 offset:1024
	ds_read_b128 v[138:141], v201 offset:2048
	ds_read_b128 v[158:161], v201 offset:3072
	ds_read_b128 v[162:165], v202
	ds_read_b128 v[166:169], v202 offset:1024
	ds_read_b128 v[170:173], v202 offset:2048
	ds_read_b128 v[174:177], v202 offset:3072
	s_add_u32 s0, s10, 0x100
	s_addc_u32 s1, s11, 0
	s_cmp_eq_u32 s12, 40
	s_cselect_b32 s51, s45, s1
	s_cselect_b32 s50, s44, s0
	s_cselect_b32 s49, s47, s77
	s_cselect_b32 s48, s46, s9
	v_lshl_add_u64 v[220:221], s[10:11], 0, v[150:151]
	s_add_i32 m0, s54, 0xc000
	ds_read_b128 v[178:181], v203
	ds_read_b128 v[182:185], v203 offset:1024
	ds_read_b128 v[186:189], v203 offset:2048
	ds_read_b128 v[190:193], v203 offset:3072
	ds_read_b128 v[194:197], v203 offset:4096
	ds_read_b128 v[208:211], v203 offset:5120
	ds_read_b128 v[212:215], v203 offset:6144
	ds_read_b128 v[216:219], v203 offset:7168
	global_load_lds_dwordx4 v[220:221], off
	v_lshl_add_u64 v[220:221], s[10:11], 0, v[152:153]
	s_add_i32 m0, s54, 0xe000
	s_nop 0
	global_load_lds_dwordx4 v[220:221], off
	s_waitcnt vmcnt(8)
	s_waitcnt lgkmcnt(0)
	s_barrier
	s_setprio 1
	s_waitcnt lgkmcnt(0)
	v_mfma_f32_16x16x32_bf16 v[74:77], v[106:109], v[178:181], v[74:77]
	v_mfma_f32_16x16x32_bf16 v[70:73], v[138:141], v[178:181], v[70:73]
	v_mfma_f32_16x16x32_bf16 v[134:137], v[106:109], v[186:189], v[134:137]
	v_mfma_f32_16x16x32_bf16 v[130:133], v[138:141], v[186:189], v[130:133]
	v_mfma_f32_16x16x32_bf16 v[54:57], v[106:109], v[194:197], v[54:57]
	v_mfma_f32_16x16x32_bf16 v[50:53], v[138:141], v[194:197], v[50:53]
	v_mfma_f32_16x16x32_bf16 v[126:129], v[106:109], v[212:215], v[126:129]
	v_mfma_f32_16x16x32_bf16 v[122:125], v[138:141], v[212:215], v[122:125]
	v_mfma_f32_16x16x32_bf16 v[74:77], v[110:113], v[182:185], v[74:77]
	v_mfma_f32_16x16x32_bf16 v[70:73], v[158:161], v[182:185], v[70:73]
	v_mfma_f32_16x16x32_bf16 v[134:137], v[110:113], v[190:193], v[134:137]
	v_mfma_f32_16x16x32_bf16 v[130:133], v[158:161], v[190:193], v[130:133]
	v_mfma_f32_16x16x32_bf16 v[54:57], v[110:113], v[208:211], v[54:57]
	v_mfma_f32_16x16x32_bf16 v[50:53], v[158:161], v[208:211], v[50:53]
	v_mfma_f32_16x16x32_bf16 v[126:129], v[110:113], v[216:219], v[126:129]
	v_mfma_f32_16x16x32_bf16 v[122:125], v[158:161], v[216:219], v[122:125]
	s_setprio 0
	s_setprio 1
	v_mfma_f32_16x16x32_bf16 v[62:65], v[162:165], v[178:181], v[62:65]
	v_mfma_f32_16x16x32_bf16 v[58:61], v[170:173], v[178:181], v[58:61]
	v_mfma_f32_16x16x32_bf16 v[94:97], v[162:165], v[186:189], v[94:97]
	v_mfma_f32_16x16x32_bf16 v[90:93], v[170:173], v[186:189], v[90:93]
	v_mfma_f32_16x16x32_bf16 v[38:41], v[162:165], v[194:197], v[38:41]
	v_mfma_f32_16x16x32_bf16 v[34:37], v[170:173], v[194:197], v[34:37]
	v_mfma_f32_16x16x32_bf16 v[86:89], v[162:165], v[212:215], v[86:89]
	v_mfma_f32_16x16x32_bf16 v[82:85], v[170:173], v[212:215], v[82:85]
	v_mfma_f32_16x16x32_bf16 v[62:65], v[166:169], v[182:185], v[62:65]
	v_mfma_f32_16x16x32_bf16 v[58:61], v[174:177], v[182:185], v[58:61]
	v_mfma_f32_16x16x32_bf16 v[94:97], v[166:169], v[190:193], v[94:97]
	v_mfma_f32_16x16x32_bf16 v[90:93], v[174:177], v[190:193], v[90:93]
	v_mfma_f32_16x16x32_bf16 v[38:41], v[166:169], v[208:211], v[38:41]
	v_mfma_f32_16x16x32_bf16 v[34:37], v[174:177], v[208:211], v[34:37]
	v_mfma_f32_16x16x32_bf16 v[86:89], v[166:169], v[216:219], v[86:89]
	v_mfma_f32_16x16x32_bf16 v[82:85], v[174:177], v[216:219], v[82:85]
	s_setprio 0
	s_barrier
	s_add_i32 s10, s70, s33
	s_nop 0
	s_mov_b32 m0, s10
	ds_read_b128 v[178:181], v203 offset:16384
	ds_read_b128 v[182:185], v203 offset:17408
	ds_read_b128 v[186:189], v203 offset:18432
	ds_read_b128 v[190:193], v203 offset:19456
	ds_read_b128 v[194:197], v203 offset:20480
	ds_read_b128 v[208:211], v203 offset:21504
	ds_read_b128 v[212:215], v203 offset:22528
	ds_read_b128 v[216:219], v203 offset:23552
	global_load_lds_dwordx4 v144, s[48:49]
	s_add_i32 m0, s10, 0x2000
	s_add_u32 s10, s48, 0xb0000
	s_nop 0
	s_addc_u32 s11, s49, 0
	s_add_i32 s13, s71, s33
	global_load_lds_dwordx4 v148, s[48:49]
	s_nop 0
	s_mov_b32 m0, s13
	s_nop 0
	global_load_lds_dwordx4 v144, s[10:11]
	s_nop 0
	s_add_i32 m0, s13, 0x2000
	s_nop 0
	global_load_lds_dwordx4 v148, s[10:11]
	s_nop 0
	s_mov_b32 m0, s54
	s_nop 0
	global_load_lds_dwordx4 v142, s[50:51]
	s_mov_b32 m0, s55
	s_nop 0
	global_load_lds_dwordx4 v146, s[50:51]
	s_waitcnt vmcnt(8)
	s_waitcnt lgkmcnt(0)
	s_barrier
	s_setprio 1
	s_waitcnt lgkmcnt(0)
	v_mfma_f32_16x16x32_bf16 v[30:33], v[106:109], v[178:181], v[30:33]
	v_mfma_f32_16x16x32_bf16 v[26:29], v[138:141], v[178:181], v[26:29]
	v_mfma_f32_16x16x32_bf16 v[118:121], v[106:109], v[186:189], v[118:121]
	v_mfma_f32_16x16x32_bf16 v[114:117], v[138:141], v[186:189], v[114:117]
	v_mfma_f32_16x16x32_bf16 v[14:17], v[106:109], v[194:197], v[14:17]
	v_mfma_f32_16x16x32_bf16 v[10:13], v[138:141], v[194:197], v[10:13]
	v_mfma_f32_16x16x32_bf16 v[102:105], v[106:109], v[212:215], v[102:105]
	v_mfma_f32_16x16x32_bf16 v[98:101], v[138:141], v[212:215], v[98:101]
	v_mfma_f32_16x16x32_bf16 v[30:33], v[110:113], v[182:185], v[30:33]
	v_mfma_f32_16x16x32_bf16 v[26:29], v[158:161], v[182:185], v[26:29]
	v_mfma_f32_16x16x32_bf16 v[118:121], v[110:113], v[190:193], v[118:121]
	v_mfma_f32_16x16x32_bf16 v[114:117], v[158:161], v[190:193], v[114:117]
	v_mfma_f32_16x16x32_bf16 v[14:17], v[110:113], v[208:211], v[14:17]
	v_mfma_f32_16x16x32_bf16 v[10:13], v[158:161], v[208:211], v[10:13]
	v_mfma_f32_16x16x32_bf16 v[102:105], v[110:113], v[216:219], v[102:105]
	v_mfma_f32_16x16x32_bf16 v[98:101], v[158:161], v[216:219], v[98:101]
	s_setprio 0
	s_setprio 1
	v_mfma_f32_16x16x32_bf16 v[22:25], v[162:165], v[178:181], v[22:25]
	v_mfma_f32_16x16x32_bf16 v[18:21], v[170:173], v[178:181], v[18:21]
	v_mfma_f32_16x16x32_bf16 v[78:81], v[162:165], v[186:189], v[78:81]
	v_mfma_f32_16x16x32_bf16 v[66:69], v[170:173], v[186:189], v[66:69]
	v_mfma_f32_16x16x32_bf16 v[6:9], v[162:165], v[194:197], v[6:9]
	v_mfma_f32_16x16x32_bf16 v[2:5], v[170:173], v[194:197], v[2:5]
	v_mfma_f32_16x16x32_bf16 v[46:49], v[162:165], v[212:215], v[46:49]
	v_mfma_f32_16x16x32_bf16 v[42:45], v[170:173], v[212:215], v[42:45]
	v_mfma_f32_16x16x32_bf16 v[22:25], v[166:169], v[182:185], v[22:25]
	v_mfma_f32_16x16x32_bf16 v[18:21], v[174:177], v[182:185], v[18:21]
	v_mfma_f32_16x16x32_bf16 v[78:81], v[166:169], v[190:193], v[78:81]
	v_mfma_f32_16x16x32_bf16 v[66:69], v[174:177], v[190:193], v[66:69]
	v_mfma_f32_16x16x32_bf16 v[6:9], v[166:169], v[208:211], v[6:9]
	v_mfma_f32_16x16x32_bf16 v[2:5], v[174:177], v[208:211], v[2:5]
	v_mfma_f32_16x16x32_bf16 v[46:49], v[166:169], v[216:219], v[46:49]
	v_mfma_f32_16x16x32_bf16 v[42:45], v[174:177], v[216:219], v[42:45]
	s_setprio 0
	s_barrier
	s_add_i32 s13, 0, 0x18000
	s_add_i32 s78, 0, 0x1c000
	v_add_u32_e32 v158, s13, v199
	v_add_u32_e32 v174, s78, v199
	ds_read_b128 v[106:109], v158
	ds_read_b128 v[110:113], v158 offset:1024
	ds_read_b128 v[138:141], v158 offset:2048
	ds_read_b128 v[158:161], v158 offset:3072
	ds_read_b128 v[162:165], v174
	ds_read_b128 v[166:169], v174 offset:1024
	ds_read_b128 v[170:173], v174 offset:2048
	ds_read_b128 v[174:177], v174 offset:3072
	s_add_u32 s10, s50, 0xb0000
	s_addc_u32 s11, s51, 0
	s_mov_b32 m0, s56
	s_nop 0
	ds_read_b128 v[178:181], v203 offset:32768
	ds_read_b128 v[182:185], v203 offset:33792
	ds_read_b128 v[186:189], v203 offset:34816
	ds_read_b128 v[190:193], v203 offset:35840
	ds_read_b128 v[194:197], v203 offset:36864
	ds_read_b128 v[208:211], v203 offset:37888
	ds_read_b128 v[212:215], v203 offset:38912
	ds_read_b128 v[216:219], v203 offset:39936
	global_load_lds_dwordx4 v142, s[10:11]
	s_nop 0
	s_mov_b32 m0, s57
	s_nop 0
	global_load_lds_dwordx4 v146, s[10:11]
	s_waitcnt vmcnt(8)
	s_waitcnt lgkmcnt(0)
	s_barrier
	s_setprio 1
	s_waitcnt lgkmcnt(0)
	v_mfma_f32_16x16x32_bf16 v[74:77], v[106:109], v[178:181], v[74:77]
	v_mfma_f32_16x16x32_bf16 v[70:73], v[138:141], v[178:181], v[70:73]
	v_mfma_f32_16x16x32_bf16 v[134:137], v[106:109], v[186:189], v[134:137]
	v_mfma_f32_16x16x32_bf16 v[130:133], v[138:141], v[186:189], v[130:133]
	v_mfma_f32_16x16x32_bf16 v[54:57], v[106:109], v[194:197], v[54:57]
	v_mfma_f32_16x16x32_bf16 v[50:53], v[138:141], v[194:197], v[50:53]
	v_mfma_f32_16x16x32_bf16 v[126:129], v[106:109], v[212:215], v[126:129]
	v_mfma_f32_16x16x32_bf16 v[122:125], v[138:141], v[212:215], v[122:125]
	v_mfma_f32_16x16x32_bf16 v[74:77], v[110:113], v[182:185], v[74:77]
	v_mfma_f32_16x16x32_bf16 v[70:73], v[158:161], v[182:185], v[70:73]
	v_mfma_f32_16x16x32_bf16 v[134:137], v[110:113], v[190:193], v[134:137]
	v_mfma_f32_16x16x32_bf16 v[130:133], v[158:161], v[190:193], v[130:133]
	v_mfma_f32_16x16x32_bf16 v[54:57], v[110:113], v[208:211], v[54:57]
	v_mfma_f32_16x16x32_bf16 v[50:53], v[158:161], v[208:211], v[50:53]
	v_mfma_f32_16x16x32_bf16 v[126:129], v[110:113], v[216:219], v[126:129]
	v_mfma_f32_16x16x32_bf16 v[122:125], v[158:161], v[216:219], v[122:125]
	s_setprio 0
	s_setprio 1
	v_mfma_f32_16x16x32_bf16 v[62:65], v[162:165], v[178:181], v[62:65]
	v_mfma_f32_16x16x32_bf16 v[58:61], v[170:173], v[178:181], v[58:61]
	v_mfma_f32_16x16x32_bf16 v[94:97], v[162:165], v[186:189], v[94:97]
	v_mfma_f32_16x16x32_bf16 v[90:93], v[170:173], v[186:189], v[90:93]
	v_mfma_f32_16x16x32_bf16 v[38:41], v[162:165], v[194:197], v[38:41]
	v_mfma_f32_16x16x32_bf16 v[34:37], v[170:173], v[194:197], v[34:37]
	v_mfma_f32_16x16x32_bf16 v[86:89], v[162:165], v[212:215], v[86:89]
	v_mfma_f32_16x16x32_bf16 v[82:85], v[170:173], v[212:215], v[82:85]
	v_mfma_f32_16x16x32_bf16 v[62:65], v[166:169], v[182:185], v[62:65]
	v_mfma_f32_16x16x32_bf16 v[58:61], v[174:177], v[182:185], v[58:61]
	v_mfma_f32_16x16x32_bf16 v[94:97], v[166:169], v[190:193], v[94:97]
	v_mfma_f32_16x16x32_bf16 v[90:93], v[174:177], v[190:193], v[90:93]
	v_mfma_f32_16x16x32_bf16 v[38:41], v[166:169], v[208:211], v[38:41]
	v_mfma_f32_16x16x32_bf16 v[34:37], v[174:177], v[208:211], v[34:37]
	v_mfma_f32_16x16x32_bf16 v[86:89], v[166:169], v[216:219], v[86:89]
	v_mfma_f32_16x16x32_bf16 v[82:85], v[174:177], v[216:219], v[82:85]
	s_setprio 0
	s_barrier
	s_add_i32 s10, s13, s33
	s_nop 0
	s_mov_b32 m0, s10
	ds_read_b128 v[178:181], v203 offset:49152
	ds_read_b128 v[182:185], v203 offset:50176
	ds_read_b128 v[186:189], v203 offset:51200
	ds_read_b128 v[190:193], v203 offset:52224
	ds_read_b128 v[194:197], v203 offset:53248
	ds_read_b128 v[208:211], v203 offset:54272
	ds_read_b128 v[212:215], v203 offset:55296
	ds_read_b128 v[216:219], v203 offset:56320
	global_load_lds_dwordx4 v251, s[48:49]
	s_add_i32 m0, s10, 0x2000
	s_add_u32 s10, s48, 0xb0080
	s_nop 0
	s_addc_u32 s11, s49, 0
	s_add_i32 s13, s78, s33
	global_load_lds_dwordx4 v252, s[48:49]
	s_nop 0
	s_mov_b32 m0, s13
	s_nop 0
	global_load_lds_dwordx4 v144, s[10:11]
	s_nop 0
	s_add_i32 m0, s13, 0x2000
	s_nop 0
	global_load_lds_dwordx4 v148, s[10:11]
	s_nop 0
	s_mov_b32 m0, s67
	s_nop 0
	global_load_lds_dwordx4 v253, s[50:51]
	s_nop 0
	s_mov_b32 m0, s68
	s_nop 0
	global_load_lds_dwordx4 v254, s[50:51]
	s_waitcnt vmcnt(8)
	s_waitcnt lgkmcnt(0)
	s_barrier
	s_setprio 1
	s_waitcnt lgkmcnt(0)
	v_mfma_f32_16x16x32_bf16 v[30:33], v[106:109], v[178:181], v[30:33]
	v_mfma_f32_16x16x32_bf16 v[26:29], v[138:141], v[178:181], v[26:29]
	v_mfma_f32_16x16x32_bf16 v[118:121], v[106:109], v[186:189], v[118:121]
	v_mfma_f32_16x16x32_bf16 v[114:117], v[138:141], v[186:189], v[114:117]
	v_mfma_f32_16x16x32_bf16 v[14:17], v[106:109], v[194:197], v[14:17]
	v_mfma_f32_16x16x32_bf16 v[10:13], v[138:141], v[194:197], v[10:13]
	v_mfma_f32_16x16x32_bf16 v[102:105], v[106:109], v[212:215], v[102:105]
	v_mfma_f32_16x16x32_bf16 v[98:101], v[138:141], v[212:215], v[98:101]
	v_mfma_f32_16x16x32_bf16 v[30:33], v[110:113], v[182:185], v[30:33]
	v_mfma_f32_16x16x32_bf16 v[26:29], v[158:161], v[182:185], v[26:29]
	v_mfma_f32_16x16x32_bf16 v[118:121], v[110:113], v[190:193], v[118:121]
	v_mfma_f32_16x16x32_bf16 v[114:117], v[158:161], v[190:193], v[114:117]
	v_mfma_f32_16x16x32_bf16 v[14:17], v[110:113], v[208:211], v[14:17]
	v_mfma_f32_16x16x32_bf16 v[10:13], v[158:161], v[208:211], v[10:13]
	v_mfma_f32_16x16x32_bf16 v[102:105], v[110:113], v[216:219], v[102:105]
	v_mfma_f32_16x16x32_bf16 v[98:101], v[158:161], v[216:219], v[98:101]
	s_setprio 0
	s_setprio 1
	v_mfma_f32_16x16x32_bf16 v[22:25], v[162:165], v[178:181], v[22:25]
	v_mfma_f32_16x16x32_bf16 v[18:21], v[170:173], v[178:181], v[18:21]
	v_mfma_f32_16x16x32_bf16 v[78:81], v[162:165], v[186:189], v[78:81]
	v_mfma_f32_16x16x32_bf16 v[66:69], v[170:173], v[186:189], v[66:69]
	v_mfma_f32_16x16x32_bf16 v[6:9], v[162:165], v[194:197], v[6:9]
	v_mfma_f32_16x16x32_bf16 v[2:5], v[170:173], v[194:197], v[2:5]
	v_mfma_f32_16x16x32_bf16 v[46:49], v[162:165], v[212:215], v[46:49]
	v_mfma_f32_16x16x32_bf16 v[42:45], v[170:173], v[212:215], v[42:45]
	v_mfma_f32_16x16x32_bf16 v[22:25], v[166:169], v[182:185], v[22:25]
	v_mfma_f32_16x16x32_bf16 v[18:21], v[174:177], v[182:185], v[18:21]
	v_mfma_f32_16x16x32_bf16 v[78:81], v[166:169], v[190:193], v[78:81]
	v_mfma_f32_16x16x32_bf16 v[66:69], v[174:177], v[190:193], v[66:69]
	v_mfma_f32_16x16x32_bf16 v[6:9], v[166:169], v[208:211], v[6:9]
	v_mfma_f32_16x16x32_bf16 v[2:5], v[174:177], v[208:211], v[2:5]
	v_mfma_f32_16x16x32_bf16 v[46:49], v[166:169], v[216:219], v[46:49]
	v_mfma_f32_16x16x32_bf16 v[42:45], v[174:177], v[216:219], v[42:45]
	s_setprio 0
	s_barrier
	s_add_i32 s12, s12, 2
	s_add_u32 s9, s9, 0x100
	s_addc_u32 s77, s77, 0
	s_cmp_gt_u32 s12, 41
	s_mov_b64 s[10:11], s[0:1]
	s_cbranch_scc0 .LBB0_1606
	s_and_b64 vcc, exec, s[28:29]
	s_cbranch_vccz .LBB0_1609
	s_barrier
